# static priority raise: waves 4-7 s_setprio 1 once at entry, the per-phase s_setprio flips in the GEMM K loops removed
# baseline (speedup 1.0000x reference)
; #define LAS __attribute__((address_space(3)))
; DI unsigned xb_add(unsigned* p, unsigned v) { return __hip_atomic_fetch_add(p, v, __ATOMIC_RELAXED, __HIP_MEMORY_SCOPE_AGENT); }
; DI unsigned xb_xcc_id() { return (unsigned)__builtin_amdgcn_s_getreg((3 << 11) | 20) & 0xFu; }
; DI XcdBarrier xcd_barrier_post(unsigned* bar, volatile LAS unsigned* st) {
;     XcdBarrier b; b.bar = bar; b.x = xb_xcc_id(); b.st = st;
;     if (threadIdx.x == 0) (void)xb_add(&bar[XB_XCNT(b.x)], 1u);
;     return b;
; }
; __global__ void __launch_bounds__(NTHR, 2) fwd_kernel(Args a) {
;     ...
;     const int tid = threadIdx.x, lane = tid & 63, wave = __builtin_amdgcn_readfirstlane(tid >> 6);
;     const int G = gridDim.x, gw = blockIdx.x * NWAVES + wave, NGW = G * NWAVES;
;     volatile LAS unsigned* lctl = (volatile LAS unsigned*)(lds + 131072);
;     if (tid < 4) lctl[tid] = 0u;
;     __syncthreads();
;     XcdBarrier xbar = xcd_barrier_post((unsigned*)(a.ws + WS_CTL), lctl);
_Z10fwd_kernel4Args:
	s_load_dword s3, s[0:1], 0x98
	s_add_u32 s4, s0, 0x98
	s_addc_u32 s5, s1, 0
	v_readfirstlane_b32 s78, v0
	s_cmpk_lt_u32 s78, 0x100
	s_cbranch_scc1 .Lprio_done
	s_setprio 1
.Lprio_done:
	v_writelane_b32 v253, s4, 0
	v_cmp_gt_u32_e32 vcc, 4, v0
	s_nop 0
	v_writelane_b32 v253, s5, 1
	s_and_saveexec_b64 s[4:5], vcc
	v_lshl_add_u32 v1, v0, 2, 0
	v_add_u32_e32 v1, 0x20000, v1
	v_mov_b32_e32 v2, 0
	ds_write_b32 v1, v2
	s_or_b64 exec, exec, s[4:5]
	s_load_dwordx2 s[24:25], s[0:1], 0x90
	s_waitcnt lgkmcnt(0)
	s_barrier
	s_getreg_b32 s4, hwreg(HW_REG_XCC_ID, 0, 4)
	s_add_u32 s6, s24, 0x1f700000
	s_addc_u32 s7, s25, 0
	v_writelane_b32 v253, s6, 2
	s_and_b32 s4, s4, 15
	v_cmp_eq_u32_e64 s[96:97], 0, v0
	v_writelane_b32 v253, s7, 3
	v_writelane_b32 v253, s4, 4
	s_and_saveexec_b64 s[4:5], s[96:97]
	s_cbranch_execz .LBB0_5
	s_mov_b64 s[6:7], exec
	v_mbcnt_lo_u32_b32 v1, s6, 0
	v_mbcnt_hi_u32_b32 v1, s7, v1
	v_cmp_eq_u32_e32 vcc, 0, v1
	s_and_b64 s[8:9], exec, vcc
	s_mov_b64 exec, s[8:9]
	s_cbranch_execz .LBB0_5
	v_readlane_b32 s8, v253, 4
	s_bcnt1_i32_b64 s6, s[6:7]
	s_lshl_b32 s8, s8, 8
	v_mov_b32_e32 v2, s6
	v_readlane_b32 s6, v253, 2
	v_mov_b32_e32 v1, s8
	v_readlane_b32 s7, v253, 3
	s_nop 4
	global_atomic_add v1, v2, s[6:7] offset:1024

.LBB0_233:
	ds_read_b128 v[172:175], v168
	ds_read_b128 v[176:179], v168 offset:1024
	ds_read_b128 v[180:183], v168 offset:2048
	ds_read_b128 v[184:187], v168 offset:3072
	ds_read_b128 v[188:191], v169
	ds_read_b128 v[192:195], v169 offset:1024
	ds_read_b128 v[196:199], v169 offset:2048
	ds_read_b128 v[200:203], v169 offset:3072
	s_add_u32 s52, s50, 0xfffc0080
	s_addc_u32 s53, s51, -1
	s_cmp_eq_u32 s70, 12
	s_cselect_b32 s55, s31, s53
	s_cselect_b32 s54, s37, s52
	s_cselect_b32 s53, s35, s69
	s_cselect_b32 s52, s67, s68
	v_lshl_add_u64 v[162:163], s[50:51], 0, v[152:153]
	s_add_i32 m0, s57, 0xc000
	ds_read_b128 v[204:207], v170
	ds_read_b128 v[208:211], v170 offset:1024
	ds_read_b128 v[216:219], v170 offset:2048
	ds_read_b128 v[220:223], v170 offset:3072
	ds_read_b128 v[224:227], v170 offset:4096
	ds_read_b128 v[228:231], v170 offset:5120
	ds_read_b128 v[232:235], v170 offset:6144
	ds_read_b128 v[236:239], v170 offset:7168
	global_load_lds_dwordx4 v[162:163], off
	v_lshl_add_u64 v[162:163], s[50:51], 0, v[154:155]
	s_add_i32 m0, s57, 0xe000
	s_nop 0
	global_load_lds_dwordx4 v[162:163], off
	s_waitcnt vmcnt(8)
	s_waitcnt lgkmcnt(0)
	s_barrier
	s_waitcnt lgkmcnt(0)
	v_mfma_f32_16x16x32_bf16 v[126:129], v[172:175], v[204:207], v[126:129]
	v_mfma_f32_16x16x32_bf16 v[122:125], v[180:183], v[204:207], v[122:125]
	v_mfma_f32_16x16x32_bf16 v[110:113], v[172:175], v[216:219], v[110:113]
	v_mfma_f32_16x16x32_bf16 v[106:109], v[180:183], v[216:219], v[106:109]
	v_mfma_f32_16x16x32_bf16 v[94:97], v[172:175], v[224:227], v[94:97]
	v_mfma_f32_16x16x32_bf16 v[90:93], v[180:183], v[224:227], v[90:93]
	v_mfma_f32_16x16x32_bf16 v[78:81], v[172:175], v[232:235], v[78:81]
	v_mfma_f32_16x16x32_bf16 v[74:77], v[180:183], v[232:235], v[74:77]
	v_mfma_f32_16x16x32_bf16 v[126:129], v[176:179], v[208:211], v[126:129]
	v_mfma_f32_16x16x32_bf16 v[122:125], v[184:187], v[208:211], v[122:125]
	v_mfma_f32_16x16x32_bf16 v[110:113], v[176:179], v[220:223], v[110:113]
	v_mfma_f32_16x16x32_bf16 v[106:109], v[184:187], v[220:223], v[106:109]
	v_mfma_f32_16x16x32_bf16 v[94:97], v[176:179], v[228:231], v[94:97]
	v_mfma_f32_16x16x32_bf16 v[90:93], v[184:187], v[228:231], v[90:93]
	v_mfma_f32_16x16x32_bf16 v[78:81], v[176:179], v[236:239], v[78:81]
	v_mfma_f32_16x16x32_bf16 v[74:77], v[184:187], v[236:239], v[74:77]
	v_mfma_f32_16x16x32_bf16 v[118:121], v[188:191], v[204:207], v[118:121]
	v_mfma_f32_16x16x32_bf16 v[114:117], v[196:199], v[204:207], v[114:117]
	v_mfma_f32_16x16x32_bf16 v[102:105], v[188:191], v[216:219], v[102:105]
	v_mfma_f32_16x16x32_bf16 v[98:101], v[196:199], v[216:219], v[98:101]
	v_mfma_f32_16x16x32_bf16 v[86:89], v[188:191], v[224:227], v[86:89]
	v_mfma_f32_16x16x32_bf16 v[82:85], v[196:199], v[224:227], v[82:85]
	v_mfma_f32_16x16x32_bf16 v[70:73], v[188:191], v[232:235], v[70:73]
	v_mfma_f32_16x16x32_bf16 v[66:69], v[196:199], v[232:235], v[66:69]
	v_mfma_f32_16x16x32_bf16 v[118:121], v[192:195], v[208:211], v[118:121]
	v_mfma_f32_16x16x32_bf16 v[114:117], v[200:203], v[208:211], v[114:117]
	v_mfma_f32_16x16x32_bf16 v[102:105], v[192:195], v[220:223], v[102:105]
	v_mfma_f32_16x16x32_bf16 v[98:101], v[200:203], v[220:223], v[98:101]
	v_mfma_f32_16x16x32_bf16 v[86:89], v[192:195], v[228:231], v[86:89]
	v_mfma_f32_16x16x32_bf16 v[82:85], v[200:203], v[228:231], v[82:85]
	v_mfma_f32_16x16x32_bf16 v[70:73], v[192:195], v[236:239], v[70:73]
	v_mfma_f32_16x16x32_bf16 v[66:69], v[200:203], v[236:239], v[66:69]
	s_barrier
	s_add_i32 s71, s63, s21
	v_lshl_add_u64 v[162:163], s[52:53], 0, v[142:143]
	s_mov_b32 m0, s71
	ds_read_b128 v[204:207], v170 offset:16384
	ds_read_b128 v[208:211], v170 offset:17408
	ds_read_b128 v[216:219], v170 offset:18432
	ds_read_b128 v[220:223], v170 offset:19456
	ds_read_b128 v[224:227], v170 offset:20480
	ds_read_b128 v[228:231], v170 offset:21504
	ds_read_b128 v[232:235], v170 offset:22528
	ds_read_b128 v[236:239], v170 offset:23552
	global_load_lds_dwordx4 v[162:163], off
	s_add_i32 m0, s71, 0x2000
	s_add_u32 s72, s52, 0x40000
	v_lshl_add_u64 v[212:213], s[52:53], 0, v[136:137]
	s_addc_u32 s73, s53, 0
	s_add_i32 s71, s64, s21
	global_load_lds_dwordx4 v[212:213], off
	v_lshl_add_u64 v[240:241], s[72:73], 0, v[142:143]
	s_mov_b32 m0, s71
	v_lshl_add_u64 v[242:243], s[54:55], 0, v[138:139]
	global_load_lds_dwordx4 v[240:241], off
	v_lshl_add_u64 v[240:241], s[72:73], 0, v[136:137]
	s_add_i32 m0, s71, 0x2000
	s_nop 0
	global_load_lds_dwordx4 v[240:241], off
	v_lshl_add_u64 v[240:241], s[54:55], 0, v[144:145]
	s_mov_b32 m0, s57
	s_nop 0
	global_load_lds_dwordx4 v[240:241], off
	s_mov_b32 m0, s58
	s_nop 0
	global_load_lds_dwordx4 v[242:243], off
	s_waitcnt vmcnt(8)
	s_waitcnt lgkmcnt(0)
	s_barrier
	s_waitcnt lgkmcnt(0)
	v_mfma_f32_16x16x32_bf16 v[62:65], v[172:175], v[204:207], v[62:65]
	v_mfma_f32_16x16x32_bf16 v[58:61], v[180:183], v[204:207], v[58:61]
	v_mfma_f32_16x16x32_bf16 v[46:49], v[172:175], v[216:219], v[46:49]
	v_mfma_f32_16x16x32_bf16 v[42:45], v[180:183], v[216:219], v[42:45]
	v_mfma_f32_16x16x32_bf16 v[30:33], v[172:175], v[224:227], v[30:33]
	v_mfma_f32_16x16x32_bf16 v[26:29], v[180:183], v[224:227], v[26:29]
	v_mfma_f32_16x16x32_bf16 v[14:17], v[172:175], v[232:235], v[14:17]
	v_mfma_f32_16x16x32_bf16 v[10:13], v[180:183], v[232:235], v[10:13]
	v_mfma_f32_16x16x32_bf16 v[62:65], v[176:179], v[208:211], v[62:65]
	v_mfma_f32_16x16x32_bf16 v[58:61], v[184:187], v[208:211], v[58:61]
	v_mfma_f32_16x16x32_bf16 v[46:49], v[176:179], v[220:223], v[46:49]
	v_mfma_f32_16x16x32_bf16 v[42:45], v[184:187], v[220:223], v[42:45]
	v_mfma_f32_16x16x32_bf16 v[30:33], v[176:179], v[228:231], v[30:33]
	v_mfma_f32_16x16x32_bf16 v[26:29], v[184:187], v[228:231], v[26:29]
	v_mfma_f32_16x16x32_bf16 v[14:17], v[176:179], v[236:239], v[14:17]
	v_mfma_f32_16x16x32_bf16 v[10:13], v[184:187], v[236:239], v[10:13]
	v_mfma_f32_16x16x32_bf16 v[54:57], v[188:191], v[204:207], v[54:57]
	v_mfma_f32_16x16x32_bf16 v[50:53], v[196:199], v[204:207], v[50:53]
	v_mfma_f32_16x16x32_bf16 v[38:41], v[188:191], v[216:219], v[38:41]
	v_mfma_f32_16x16x32_bf16 v[34:37], v[196:199], v[216:219], v[34:37]
	v_mfma_f32_16x16x32_bf16 v[22:25], v[188:191], v[224:227], v[22:25]
	v_mfma_f32_16x16x32_bf16 v[18:21], v[196:199], v[224:227], v[18:21]
	v_mfma_f32_16x16x32_bf16 v[6:9], v[188:191], v[232:235], v[6:9]
	v_mfma_f32_16x16x32_bf16 v[2:5], v[196:199], v[232:235], v[2:5]
	v_mfma_f32_16x16x32_bf16 v[54:57], v[192:195], v[208:211], v[54:57]
	v_mfma_f32_16x16x32_bf16 v[50:53], v[200:203], v[208:211], v[50:53]
	v_mfma_f32_16x16x32_bf16 v[38:41], v[192:195], v[220:223], v[38:41]
	v_mfma_f32_16x16x32_bf16 v[34:37], v[200:203], v[220:223], v[34:37]
	v_mfma_f32_16x16x32_bf16 v[22:25], v[192:195], v[228:231], v[22:25]
	v_mfma_f32_16x16x32_bf16 v[18:21], v[200:203], v[228:231], v[18:21]
	v_mfma_f32_16x16x32_bf16 v[6:9], v[192:195], v[236:239], v[6:9]
	v_mfma_f32_16x16x32_bf16 v[2:5], v[200:203], v[236:239], v[2:5]
	s_barrier
	s_add_i32 s71, 0, 0x18000
	v_add_u32_e32 v161, s71, v131
	s_add_i32 s72, 0, 0x1c000
	ds_read_b128 v[172:175], v161
	ds_read_b128 v[176:179], v161 offset:1024
	ds_read_b128 v[180:183], v161 offset:2048
	ds_read_b128 v[184:187], v161 offset:3072
	v_add_u32_e32 v161, s72, v131
	ds_read_b128 v[188:191], v161
	ds_read_b128 v[192:195], v161 offset:1024
	ds_read_b128 v[196:199], v161 offset:2048
	ds_read_b128 v[200:203], v161 offset:3072
	s_add_u32 s54, s54, 0x40000
	s_addc_u32 s55, s55, 0
	s_mov_b32 m0, s59
	v_lshl_add_u64 v[244:245], s[54:55], 0, v[144:145]
	ds_read_b128 v[204:207], v170 offset:32768
	ds_read_b128 v[208:211], v170 offset:33792
	ds_read_b128 v[216:219], v170 offset:34816
	ds_read_b128 v[220:223], v170 offset:35840
	ds_read_b128 v[224:227], v170 offset:36864
	ds_read_b128 v[228:231], v170 offset:37888
	ds_read_b128 v[232:235], v170 offset:38912
	ds_read_b128 v[236:239], v170 offset:39936
	global_load_lds_dwordx4 v[244:245], off
	v_lshl_add_u64 v[244:245], s[54:55], 0, v[138:139]
	s_mov_b32 m0, s60
	s_nop 0
	global_load_lds_dwordx4 v[244:245], off
	s_waitcnt vmcnt(8)
	s_waitcnt lgkmcnt(0)
	s_barrier
	s_waitcnt lgkmcnt(0)
	v_mfma_f32_16x16x32_bf16 v[126:129], v[172:175], v[204:207], v[126:129]
	v_mfma_f32_16x16x32_bf16 v[122:125], v[180:183], v[204:207], v[122:125]
	v_mfma_f32_16x16x32_bf16 v[110:113], v[172:175], v[216:219], v[110:113]
	v_mfma_f32_16x16x32_bf16 v[106:109], v[180:183], v[216:219], v[106:109]
	v_mfma_f32_16x16x32_bf16 v[94:97], v[172:175], v[224:227], v[94:97]
	v_mfma_f32_16x16x32_bf16 v[90:93], v[180:183], v[224:227], v[90:93]
	v_mfma_f32_16x16x32_bf16 v[78:81], v[172:175], v[232:235], v[78:81]
	v_mfma_f32_16x16x32_bf16 v[74:77], v[180:183], v[232:235], v[74:77]
	v_mfma_f32_16x16x32_bf16 v[126:129], v[176:179], v[208:211], v[126:129]
	v_mfma_f32_16x16x32_bf16 v[122:125], v[184:187], v[208:211], v[122:125]
	v_mfma_f32_16x16x32_bf16 v[110:113], v[176:179], v[220:223], v[110:113]
	v_mfma_f32_16x16x32_bf16 v[106:109], v[184:187], v[220:223], v[106:109]
	v_mfma_f32_16x16x32_bf16 v[94:97], v[176:179], v[228:231], v[94:97]
	v_mfma_f32_16x16x32_bf16 v[90:93], v[184:187], v[228:231], v[90:93]
	v_mfma_f32_16x16x32_bf16 v[78:81], v[176:179], v[236:239], v[78:81]
	v_mfma_f32_16x16x32_bf16 v[74:77], v[184:187], v[236:239], v[74:77]
	v_mfma_f32_16x16x32_bf16 v[118:121], v[188:191], v[204:207], v[118:121]
	v_mfma_f32_16x16x32_bf16 v[114:117], v[196:199], v[204:207], v[114:117]
	v_mfma_f32_16x16x32_bf16 v[102:105], v[188:191], v[216:219], v[102:105]
	v_mfma_f32_16x16x32_bf16 v[98:101], v[196:199], v[216:219], v[98:101]
	v_mfma_f32_16x16x32_bf16 v[86:89], v[188:191], v[224:227], v[86:89]
	v_mfma_f32_16x16x32_bf16 v[82:85], v[196:199], v[224:227], v[82:85]
	v_mfma_f32_16x16x32_bf16 v[70:73], v[188:191], v[232:235], v[70:73]
	v_mfma_f32_16x16x32_bf16 v[66:69], v[196:199], v[232:235], v[66:69]
	v_mfma_f32_16x16x32_bf16 v[118:121], v[192:195], v[208:211], v[118:121]
	v_mfma_f32_16x16x32_bf16 v[114:117], v[200:203], v[208:211], v[114:117]
	v_mfma_f32_16x16x32_bf16 v[102:105], v[192:195], v[220:223], v[102:105]
	v_mfma_f32_16x16x32_bf16 v[98:101], v[200:203], v[220:223], v[98:101]
	v_mfma_f32_16x16x32_bf16 v[86:89], v[192:195], v[228:231], v[86:89]
	v_mfma_f32_16x16x32_bf16 v[82:85], v[200:203], v[228:231], v[82:85]
	v_mfma_f32_16x16x32_bf16 v[70:73], v[192:195], v[236:239], v[70:73]
	v_mfma_f32_16x16x32_bf16 v[66:69], v[200:203], v[236:239], v[66:69]
	s_barrier
	s_add_i32 s54, s71, s21
	v_lshl_add_u64 v[162:163], v[162:163], 0, s[10:11]
	s_mov_b32 m0, s54
	ds_read_b128 v[204:207], v170 offset:49152
	ds_read_b128 v[208:211], v170 offset:50176
	ds_read_b128 v[216:219], v170 offset:51200
	ds_read_b128 v[220:223], v170 offset:52224
	ds_read_b128 v[224:227], v170 offset:53248
	ds_read_b128 v[228:231], v170 offset:54272
	ds_read_b128 v[232:235], v170 offset:55296
	ds_read_b128 v[236:239], v170 offset:56320
	global_load_lds_dwordx4 v[162:163], off
	s_add_i32 m0, s54, 0x2000
	s_add_u32 s52, s52, 0x40080
	v_lshl_add_u64 v[162:163], v[212:213], 0, s[10:11]
	s_addc_u32 s53, s53, 0
	s_add_i32 s54, s72, s21
	global_load_lds_dwordx4 v[162:163], off
	v_lshl_add_u64 v[162:163], s[52:53], 0, v[142:143]
	s_mov_b32 m0, s54
	s_nop 0
	global_load_lds_dwordx4 v[162:163], off
	v_lshl_add_u64 v[162:163], s[52:53], 0, v[136:137]
	s_add_i32 m0, s54, 0x2000
	s_nop 0
	global_load_lds_dwordx4 v[162:163], off
	v_lshl_add_u64 v[162:163], v[240:241], 0, s[10:11]
	s_mov_b32 m0, s61
	s_nop 0
	global_load_lds_dwordx4 v[162:163], off
	v_lshl_add_u64 v[162:163], v[242:243], 0, s[10:11]
	s_mov_b32 m0, s62
	s_nop 0
	global_load_lds_dwordx4 v[162:163], off
	s_waitcnt vmcnt(8)
	s_waitcnt lgkmcnt(0)
	s_barrier
	s_waitcnt lgkmcnt(0)
	v_mfma_f32_16x16x32_bf16 v[62:65], v[172:175], v[204:207], v[62:65]
	v_mfma_f32_16x16x32_bf16 v[58:61], v[180:183], v[204:207], v[58:61]
	v_mfma_f32_16x16x32_bf16 v[46:49], v[172:175], v[216:219], v[46:49]
	v_mfma_f32_16x16x32_bf16 v[42:45], v[180:183], v[216:219], v[42:45]
	v_mfma_f32_16x16x32_bf16 v[30:33], v[172:175], v[224:227], v[30:33]
	v_mfma_f32_16x16x32_bf16 v[26:29], v[180:183], v[224:227], v[26:29]
	v_mfma_f32_16x16x32_bf16 v[14:17], v[172:175], v[232:235], v[14:17]
	v_mfma_f32_16x16x32_bf16 v[10:13], v[180:183], v[232:235], v[10:13]
	v_mfma_f32_16x16x32_bf16 v[62:65], v[176:179], v[208:211], v[62:65]
	v_mfma_f32_16x16x32_bf16 v[58:61], v[184:187], v[208:211], v[58:61]
	v_mfma_f32_16x16x32_bf16 v[46:49], v[176:179], v[220:223], v[46:49]
	v_mfma_f32_16x16x32_bf16 v[42:45], v[184:187], v[220:223], v[42:45]
	v_mfma_f32_16x16x32_bf16 v[30:33], v[176:179], v[228:231], v[30:33]
	v_mfma_f32_16x16x32_bf16 v[26:29], v[184:187], v[228:231], v[26:29]
	v_mfma_f32_16x16x32_bf16 v[14:17], v[176:179], v[236:239], v[14:17]
	v_mfma_f32_16x16x32_bf16 v[10:13], v[184:187], v[236:239], v[10:13]
	v_mfma_f32_16x16x32_bf16 v[54:57], v[188:191], v[204:207], v[54:57]
	v_mfma_f32_16x16x32_bf16 v[50:53], v[196:199], v[204:207], v[50:53]
	v_mfma_f32_16x16x32_bf16 v[38:41], v[188:191], v[216:219], v[38:41]
	v_mfma_f32_16x16x32_bf16 v[34:37], v[196:199], v[216:219], v[34:37]
	v_mfma_f32_16x16x32_bf16 v[22:25], v[188:191], v[224:227], v[22:25]
	v_mfma_f32_16x16x32_bf16 v[18:21], v[196:199], v[224:227], v[18:21]
	v_mfma_f32_16x16x32_bf16 v[6:9], v[188:191], v[232:235], v[6:9]
	v_mfma_f32_16x16x32_bf16 v[2:5], v[196:199], v[232:235], v[2:5]
	v_mfma_f32_16x16x32_bf16 v[54:57], v[192:195], v[208:211], v[54:57]
	v_mfma_f32_16x16x32_bf16 v[50:53], v[200:203], v[208:211], v[50:53]
	v_mfma_f32_16x16x32_bf16 v[38:41], v[192:195], v[220:223], v[38:41]
	v_mfma_f32_16x16x32_bf16 v[34:37], v[200:203], v[220:223], v[34:37]
	v_mfma_f32_16x16x32_bf16 v[22:25], v[192:195], v[228:231], v[22:25]
	v_mfma_f32_16x16x32_bf16 v[18:21], v[200:203], v[228:231], v[18:21]
	v_mfma_f32_16x16x32_bf16 v[6:9], v[192:195], v[236:239], v[6:9]
	v_mfma_f32_16x16x32_bf16 v[2:5], v[200:203], v[236:239], v[2:5]
	s_barrier
	s_add_i32 s70, s70, 2
	s_add_u32 s50, s50, 0x100
	s_addc_u32 s51, s51, 0
	s_add_u32 s68, s68, 0x100
	s_addc_u32 s69, s69, 0
	s_cmp_gt_u32 s70, 13
	s_cbranch_scc0 .LBB0_233
	s_and_b64 vcc, exec, s[12:13]
	s_cbranch_vccz .LBB0_236
	s_barrier

.LBB0_870:
	ds_read_b128 v[158:161], v168
	ds_read_b128 v[162:165], v168 offset:1024
	ds_read_b128 v[172:175], v168 offset:2048
	ds_read_b128 v[176:179], v168 offset:3072
	ds_read_b128 v[180:183], v169
	ds_read_b128 v[184:187], v169 offset:1024
	ds_read_b128 v[188:191], v169 offset:2048
	ds_read_b128 v[192:195], v169 offset:3072
	v_lshl_add_u64 v[196:197], v[132:133], 0, s[54:55]
	s_mov_b32 m0, s71
	v_lshl_add_u64 v[232:233], v[196:197], 0, s[16:17]
	v_lshl_add_u64 v[236:237], v[130:131], 0, s[54:55]
	ds_read_b128 v[200:203], v170
	ds_read_b128 v[204:207], v170 offset:1024
	ds_read_b128 v[208:211], v170 offset:2048
	ds_read_b128 v[212:215], v170 offset:3072
	ds_read_b128 v[216:219], v170 offset:4096
	ds_read_b128 v[220:223], v170 offset:5120
	ds_read_b128 v[224:227], v170 offset:6144
	ds_read_b128 v[228:231], v170 offset:7168
	global_load_lds_dwordx4 v[232:233], off
	v_lshl_add_u64 v[232:233], v[236:237], 0, s[16:17]
	s_mov_b32 m0, s72
	s_nop 0
	global_load_lds_dwordx4 v[232:233], off
	s_waitcnt vmcnt(8)
	s_waitcnt lgkmcnt(0)
	s_barrier
	s_waitcnt lgkmcnt(0)
	v_mfma_f32_16x16x32_bf16 v[34:37], v[158:161], v[200:203], v[34:37]
	v_mfma_f32_16x16x32_bf16 v[30:33], v[172:175], v[200:203], v[30:33]
	v_mfma_f32_16x16x32_bf16 v[58:61], v[158:161], v[208:211], v[58:61]
	v_mfma_f32_16x16x32_bf16 v[54:57], v[172:175], v[208:211], v[54:57]
	v_mfma_f32_16x16x32_bf16 v[74:77], v[158:161], v[216:219], v[74:77]
	v_mfma_f32_16x16x32_bf16 v[70:73], v[172:175], v[216:219], v[70:73]
	v_mfma_f32_16x16x32_bf16 v[110:113], v[158:161], v[224:227], v[110:113]
	v_mfma_f32_16x16x32_bf16 v[106:109], v[172:175], v[224:227], v[106:109]
	v_mfma_f32_16x16x32_bf16 v[34:37], v[162:165], v[204:207], v[34:37]
	v_mfma_f32_16x16x32_bf16 v[30:33], v[176:179], v[204:207], v[30:33]
	v_mfma_f32_16x16x32_bf16 v[58:61], v[162:165], v[212:215], v[58:61]
	v_mfma_f32_16x16x32_bf16 v[54:57], v[176:179], v[212:215], v[54:57]
	v_mfma_f32_16x16x32_bf16 v[74:77], v[162:165], v[220:223], v[74:77]
	v_mfma_f32_16x16x32_bf16 v[70:73], v[176:179], v[220:223], v[70:73]
	v_mfma_f32_16x16x32_bf16 v[110:113], v[162:165], v[228:231], v[110:113]
	v_mfma_f32_16x16x32_bf16 v[106:109], v[176:179], v[228:231], v[106:109]
	v_mfma_f32_16x16x32_bf16 v[50:53], v[180:183], v[200:203], v[50:53]
	v_mfma_f32_16x16x32_bf16 v[62:65], v[188:191], v[200:203], v[62:65]
	v_mfma_f32_16x16x32_bf16 v[66:69], v[180:183], v[208:211], v[66:69]
	v_mfma_f32_16x16x32_bf16 v[78:81], v[188:191], v[208:211], v[78:81]
	v_mfma_f32_16x16x32_bf16 v[82:85], v[180:183], v[216:219], v[82:85]
	v_mfma_f32_16x16x32_bf16 v[102:105], v[188:191], v[216:219], v[102:105]
	v_mfma_f32_16x16x32_bf16 v[114:117], v[180:183], v[224:227], v[114:117]
	v_mfma_f32_16x16x32_bf16 v[126:129], v[188:191], v[224:227], v[126:129]
	v_mfma_f32_16x16x32_bf16 v[50:53], v[184:187], v[204:207], v[50:53]
	v_mfma_f32_16x16x32_bf16 v[62:65], v[192:195], v[204:207], v[62:65]
	v_mfma_f32_16x16x32_bf16 v[66:69], v[184:187], v[212:215], v[66:69]
	v_mfma_f32_16x16x32_bf16 v[78:81], v[192:195], v[212:215], v[78:81]
	v_mfma_f32_16x16x32_bf16 v[82:85], v[184:187], v[220:223], v[82:85]
	v_mfma_f32_16x16x32_bf16 v[102:105], v[192:195], v[220:223], v[102:105]
	v_mfma_f32_16x16x32_bf16 v[114:117], v[184:187], v[228:231], v[114:117]
	v_mfma_f32_16x16x32_bf16 v[126:129], v[192:195], v[228:231], v[126:129]
	s_barrier
	v_lshl_add_u64 v[238:239], v[136:137], 0, s[54:55]
	s_mov_b32 m0, s73
	v_lshl_add_u64 v[232:233], v[238:239], 0, s[28:29]
	v_lshl_add_u64 v[240:241], v[134:135], 0, s[54:55]
	ds_read_b128 v[200:203], v170 offset:16384
	ds_read_b128 v[204:207], v170 offset:17408
	ds_read_b128 v[208:211], v170 offset:18432
	ds_read_b128 v[212:215], v170 offset:19456
	ds_read_b128 v[216:219], v170 offset:20480
	ds_read_b128 v[220:223], v170 offset:21504
	ds_read_b128 v[224:227], v170 offset:22528
	ds_read_b128 v[228:231], v170 offset:23552
	global_load_lds_dwordx4 v[232:233], off
	v_lshl_add_u64 v[232:233], v[240:241], 0, s[28:29]
	s_mov_b32 m0, s74
	s_add_i32 s76, s70, s20
	global_load_lds_dwordx4 v[232:233], off
	v_lshl_add_u64 v[232:233], v[238:239], 0, s[38:39]
	s_mov_b32 m0, s76
	s_add_i32 s77, s76, 0x2000
	global_load_lds_dwordx4 v[232:233], off
	v_lshl_add_u64 v[232:233], v[240:241], 0, s[38:39]
	s_mov_b32 m0, s77
	s_nop 0
	global_load_lds_dwordx4 v[232:233], off
	v_lshl_add_u64 v[232:233], v[196:197], 0, s[28:29]
	s_mov_b32 m0, s21
	s_nop 0
	global_load_lds_dwordx4 v[232:233], off
	v_lshl_add_u64 v[232:233], v[236:237], 0, s[28:29]
	s_mov_b32 m0, s64
	s_nop 0
	global_load_lds_dwordx4 v[232:233], off
	s_waitcnt vmcnt(8)
	s_waitcnt lgkmcnt(0)
	s_barrier
	s_waitcnt lgkmcnt(0)
	v_mfma_f32_16x16x32_bf16 v[122:125], v[158:161], v[200:203], v[122:125]
	v_mfma_f32_16x16x32_bf16 v[118:121], v[172:175], v[200:203], v[118:121]
	v_mfma_f32_16x16x32_bf16 v[90:93], v[158:161], v[208:211], v[90:93]
	v_mfma_f32_16x16x32_bf16 v[86:89], v[172:175], v[208:211], v[86:89]
	v_mfma_f32_16x16x32_bf16 v[38:41], v[158:161], v[216:219], v[38:41]
	v_mfma_f32_16x16x32_bf16 v[26:29], v[172:175], v[216:219], v[26:29]
	v_mfma_f32_16x16x32_bf16 v[14:17], v[158:161], v[224:227], v[14:17]
	v_mfma_f32_16x16x32_bf16 v[10:13], v[172:175], v[224:227], v[10:13]
	v_mfma_f32_16x16x32_bf16 v[122:125], v[162:165], v[204:207], v[122:125]
	v_mfma_f32_16x16x32_bf16 v[118:121], v[176:179], v[204:207], v[118:121]
	v_mfma_f32_16x16x32_bf16 v[90:93], v[162:165], v[212:215], v[90:93]
	v_mfma_f32_16x16x32_bf16 v[86:89], v[176:179], v[212:215], v[86:89]
	v_mfma_f32_16x16x32_bf16 v[38:41], v[162:165], v[220:223], v[38:41]
	v_mfma_f32_16x16x32_bf16 v[26:29], v[176:179], v[220:223], v[26:29]
	v_mfma_f32_16x16x32_bf16 v[14:17], v[162:165], v[228:231], v[14:17]
	v_mfma_f32_16x16x32_bf16 v[10:13], v[176:179], v[228:231], v[10:13]
	v_mfma_f32_16x16x32_bf16 v[98:101], v[180:183], v[200:203], v[98:101]
	v_mfma_f32_16x16x32_bf16 v[94:97], v[188:191], v[200:203], v[94:97]
	v_mfma_f32_16x16x32_bf16 v[46:49], v[180:183], v[208:211], v[46:49]
	v_mfma_f32_16x16x32_bf16 v[42:45], v[188:191], v[208:211], v[42:45]
	v_mfma_f32_16x16x32_bf16 v[22:25], v[180:183], v[216:219], v[22:25]
	v_mfma_f32_16x16x32_bf16 v[18:21], v[188:191], v[216:219], v[18:21]
	v_mfma_f32_16x16x32_bf16 v[6:9], v[180:183], v[224:227], v[6:9]
	v_mfma_f32_16x16x32_bf16 v[2:5], v[188:191], v[224:227], v[2:5]
	v_mfma_f32_16x16x32_bf16 v[98:101], v[184:187], v[204:207], v[98:101]
	v_mfma_f32_16x16x32_bf16 v[94:97], v[192:195], v[204:207], v[94:97]
	v_mfma_f32_16x16x32_bf16 v[46:49], v[184:187], v[212:215], v[46:49]
	v_mfma_f32_16x16x32_bf16 v[42:45], v[192:195], v[212:215], v[42:45]
	v_mfma_f32_16x16x32_bf16 v[22:25], v[184:187], v[220:223], v[22:25]
	v_mfma_f32_16x16x32_bf16 v[18:21], v[192:195], v[220:223], v[18:21]
	v_mfma_f32_16x16x32_bf16 v[6:9], v[184:187], v[228:231], v[6:9]
	v_mfma_f32_16x16x32_bf16 v[2:5], v[192:195], v[228:231], v[2:5]
	s_barrier
	s_add_i32 s78, 0, 0x18000
	s_add_i32 s80, 0, 0x1c000
	v_add_u32_e32 v161, s78, v166
	v_add_u32_e32 v171, s80, v166
	ds_read_b128 v[162:165], v161
	ds_read_b128 v[172:175], v161 offset:1024
	ds_read_b128 v[176:179], v161 offset:2048
	ds_read_b128 v[180:183], v161 offset:3072
	ds_read_b128 v[184:187], v171
	ds_read_b128 v[188:191], v171 offset:1024
	ds_read_b128 v[192:195], v171 offset:2048
	ds_read_b128 v[200:203], v171 offset:3072
	s_mov_b32 m0, s65
	v_lshl_add_u64 v[158:159], v[196:197], 0, s[38:39]
	ds_read_b128 v[204:207], v170 offset:32768
	ds_read_b128 v[208:211], v170 offset:33792
	ds_read_b128 v[212:215], v170 offset:34816
	ds_read_b128 v[216:219], v170 offset:35840
	ds_read_b128 v[220:223], v170 offset:36864
	ds_read_b128 v[224:227], v170 offset:37888
	ds_read_b128 v[228:231], v170 offset:38912
	ds_read_b128 v[232:235], v170 offset:39936
	global_load_lds_dwordx4 v[158:159], off
	v_lshl_add_u64 v[158:159], v[236:237], 0, s[38:39]
	s_mov_b32 m0, s66
	s_nop 0
	global_load_lds_dwordx4 v[158:159], off
	s_waitcnt vmcnt(8)
	s_waitcnt lgkmcnt(0)
	s_barrier
	s_waitcnt lgkmcnt(0)
	v_mfma_f32_16x16x32_bf16 v[34:37], v[162:165], v[204:207], v[34:37]
	v_mfma_f32_16x16x32_bf16 v[30:33], v[176:179], v[204:207], v[30:33]
	v_mfma_f32_16x16x32_bf16 v[58:61], v[162:165], v[212:215], v[58:61]
	v_mfma_f32_16x16x32_bf16 v[54:57], v[176:179], v[212:215], v[54:57]
	v_mfma_f32_16x16x32_bf16 v[74:77], v[162:165], v[220:223], v[74:77]
	v_mfma_f32_16x16x32_bf16 v[70:73], v[176:179], v[220:223], v[70:73]
	v_mfma_f32_16x16x32_bf16 v[110:113], v[162:165], v[228:231], v[110:113]
	v_mfma_f32_16x16x32_bf16 v[106:109], v[176:179], v[228:231], v[106:109]
	v_mfma_f32_16x16x32_bf16 v[34:37], v[172:175], v[208:211], v[34:37]
	v_mfma_f32_16x16x32_bf16 v[30:33], v[180:183], v[208:211], v[30:33]
	v_mfma_f32_16x16x32_bf16 v[58:61], v[172:175], v[216:219], v[58:61]
	v_mfma_f32_16x16x32_bf16 v[54:57], v[180:183], v[216:219], v[54:57]
	v_mfma_f32_16x16x32_bf16 v[74:77], v[172:175], v[224:227], v[74:77]
	v_mfma_f32_16x16x32_bf16 v[70:73], v[180:183], v[224:227], v[70:73]
	v_mfma_f32_16x16x32_bf16 v[110:113], v[172:175], v[232:235], v[110:113]
	v_mfma_f32_16x16x32_bf16 v[106:109], v[180:183], v[232:235], v[106:109]
	v_mfma_f32_16x16x32_bf16 v[50:53], v[184:187], v[204:207], v[50:53]
	v_mfma_f32_16x16x32_bf16 v[62:65], v[192:195], v[204:207], v[62:65]
	v_mfma_f32_16x16x32_bf16 v[66:69], v[184:187], v[212:215], v[66:69]
	v_mfma_f32_16x16x32_bf16 v[78:81], v[192:195], v[212:215], v[78:81]
	v_mfma_f32_16x16x32_bf16 v[82:85], v[184:187], v[220:223], v[82:85]
	v_mfma_f32_16x16x32_bf16 v[102:105], v[192:195], v[220:223], v[102:105]
	v_mfma_f32_16x16x32_bf16 v[114:117], v[184:187], v[228:231], v[114:117]
	v_mfma_f32_16x16x32_bf16 v[126:129], v[192:195], v[228:231], v[126:129]
	v_mfma_f32_16x16x32_bf16 v[50:53], v[188:191], v[208:211], v[50:53]
	v_mfma_f32_16x16x32_bf16 v[62:65], v[200:203], v[208:211], v[62:65]
	v_mfma_f32_16x16x32_bf16 v[66:69], v[188:191], v[216:219], v[66:69]
	v_mfma_f32_16x16x32_bf16 v[78:81], v[200:203], v[216:219], v[78:81]
	v_mfma_f32_16x16x32_bf16 v[82:85], v[188:191], v[224:227], v[82:85]
	v_mfma_f32_16x16x32_bf16 v[102:105], v[200:203], v[224:227], v[102:105]
	v_mfma_f32_16x16x32_bf16 v[114:117], v[188:191], v[232:235], v[114:117]
	v_mfma_f32_16x16x32_bf16 v[126:129], v[200:203], v[232:235], v[126:129]
	s_barrier
; template <class Epi, bool HOOK = false>
; DI void gemm_phase(LAS unsigned char* lds, const Gemm g, const StaticOrder& S, const Epi& E) {
;     ...
;         if constexpr (HOOK) {
;             for (int t = 0; t < (nt >> 1); t += 2) PG8_KBODY();
;             E.hook(acc, cur, wr, wc, fr, fq);
;     DI void hook(Acc& acc, const Unit& u, int wr, int wc, int fr, int fq) const {
;         const int row0 = u.pm * 256 + wr * 64 + fr;
; #pragma unroll
;         for (int ai = 0; ai < 2; ++ai)
; #pragma unroll
;             for (int m = 0; m < 4; ++m) {
;                 const int r = row0 + ai * 128 + m * 16;
; #pragma unroll
;                 for (int bj = 0; bj < 2; ++bj) {
;                     const int c0 = u.pn * 256 + bj * 128 + wc * 32 + 8 * fq;
;                     const u32x4 ga = *(const u32x4*)(Z + (size_t)r * NZ + ZC_GM + c0), gb = *(const u32x4*)(Z + (size_t)r * NZ + ZC_GM + DM + c0);
	s_add_i32 s78, s78, s20
	v_lshl_add_u64 v[158:159], v[238:239], 0, s[42:43]
	s_mov_b32 m0, s78
	s_add_i32 s79, s78, 0x2000
	ds_read_b128 v[204:207], v170 offset:49152
	ds_read_b128 v[208:211], v170 offset:50176
	ds_read_b128 v[212:215], v170 offset:51200
	ds_read_b128 v[216:219], v170 offset:52224
	ds_read_b128 v[220:223], v170 offset:53248
	ds_read_b128 v[224:227], v170 offset:54272
	ds_read_b128 v[228:231], v170 offset:55296
	ds_read_b128 v[232:235], v170 offset:56320
	global_load_lds_dwordx4 v[158:159], off
	v_lshl_add_u64 v[158:159], v[240:241], 0, s[42:43]
	s_mov_b32 m0, s79
	s_add_i32 s80, s80, s20
	global_load_lds_dwordx4 v[158:159], off
	v_lshl_add_u64 v[158:159], v[238:239], 0, s[44:45]
	s_mov_b32 m0, s80
	s_add_i32 s81, s80, 0x2000
	global_load_lds_dwordx4 v[158:159], off
	v_lshl_add_u64 v[158:159], v[240:241], 0, s[44:45]
	s_mov_b32 m0, s81
	s_nop 0
	global_load_lds_dwordx4 v[158:159], off
	v_lshl_add_u64 v[158:159], v[196:197], 0, s[42:43]
	s_mov_b32 m0, s68
	s_nop 0
	global_load_lds_dwordx4 v[158:159], off
	v_lshl_add_u64 v[158:159], v[236:237], 0, s[42:43]
	s_mov_b32 m0, s69
	s_nop 0
	global_load_lds_dwordx4 v[158:159], off
	s_waitcnt vmcnt(8)
	s_waitcnt lgkmcnt(0)
	s_barrier
	s_waitcnt lgkmcnt(0)
	v_mfma_f32_16x16x32_bf16 v[122:125], v[162:165], v[204:207], v[122:125]
	v_mfma_f32_16x16x32_bf16 v[118:121], v[176:179], v[204:207], v[118:121]
	v_mfma_f32_16x16x32_bf16 v[90:93], v[162:165], v[212:215], v[90:93]
	v_mfma_f32_16x16x32_bf16 v[86:89], v[176:179], v[212:215], v[86:89]
	v_mfma_f32_16x16x32_bf16 v[38:41], v[162:165], v[220:223], v[38:41]
	v_mfma_f32_16x16x32_bf16 v[26:29], v[176:179], v[220:223], v[26:29]
	v_mfma_f32_16x16x32_bf16 v[14:17], v[162:165], v[228:231], v[14:17]
	v_mfma_f32_16x16x32_bf16 v[10:13], v[176:179], v[228:231], v[10:13]
	v_mfma_f32_16x16x32_bf16 v[122:125], v[172:175], v[208:211], v[122:125]
	v_mfma_f32_16x16x32_bf16 v[118:121], v[180:183], v[208:211], v[118:121]
	v_mfma_f32_16x16x32_bf16 v[90:93], v[172:175], v[216:219], v[90:93]
	v_mfma_f32_16x16x32_bf16 v[86:89], v[180:183], v[216:219], v[86:89]
	v_mfma_f32_16x16x32_bf16 v[38:41], v[172:175], v[224:227], v[38:41]
	v_mfma_f32_16x16x32_bf16 v[26:29], v[180:183], v[224:227], v[26:29]
	v_mfma_f32_16x16x32_bf16 v[14:17], v[172:175], v[232:235], v[14:17]
	v_mfma_f32_16x16x32_bf16 v[10:13], v[180:183], v[232:235], v[10:13]
	v_mfma_f32_16x16x32_bf16 v[98:101], v[184:187], v[204:207], v[98:101]
	v_mfma_f32_16x16x32_bf16 v[94:97], v[192:195], v[204:207], v[94:97]
	v_mfma_f32_16x16x32_bf16 v[46:49], v[184:187], v[212:215], v[46:49]
	v_mfma_f32_16x16x32_bf16 v[42:45], v[192:195], v[212:215], v[42:45]
	v_mfma_f32_16x16x32_bf16 v[22:25], v[184:187], v[220:223], v[22:25]
	v_mfma_f32_16x16x32_bf16 v[18:21], v[192:195], v[220:223], v[18:21]
	v_mfma_f32_16x16x32_bf16 v[6:9], v[184:187], v[228:231], v[6:9]
	v_mfma_f32_16x16x32_bf16 v[2:5], v[192:195], v[228:231], v[2:5]
	v_mfma_f32_16x16x32_bf16 v[98:101], v[188:191], v[208:211], v[98:101]
	v_mfma_f32_16x16x32_bf16 v[94:97], v[200:203], v[208:211], v[94:97]
	v_mfma_f32_16x16x32_bf16 v[46:49], v[188:191], v[216:219], v[46:49]
	v_mfma_f32_16x16x32_bf16 v[42:45], v[200:203], v[216:219], v[42:45]
	v_mfma_f32_16x16x32_bf16 v[22:25], v[188:191], v[224:227], v[22:25]
	v_mfma_f32_16x16x32_bf16 v[18:21], v[200:203], v[224:227], v[18:21]
	v_mfma_f32_16x16x32_bf16 v[6:9], v[188:191], v[232:235], v[6:9]
	v_mfma_f32_16x16x32_bf16 v[2:5], v[200:203], v[232:235], v[2:5]
	s_barrier
	s_add_i32 s51, s51, 2
	s_add_u32 s54, s54, 0x100
	s_addc_u32 s55, s55, 0
	s_cmp_gt_u32 s51, 5
	s_cbranch_scc0 .LBB0_870
	v_lshl_add_u32 v160, s62, 8, v1
	v_lshl_or_b32 v130, s53, 8, v167
	s_ashr_i32 s53, s52, 31
	s_ashr_i32 s51, s50, 31
	s_lshl_b64 s[54:55], s[52:53], 19
	s_lshl_b64 s[56:57], s[50:51], 19
	s_add_u32 s54, s14, s54
	s_addc_u32 s55, s15, s55
	s_add_u32 s56, s40, s56
	s_addc_u32 s57, s41, s57
	s_and_b64 s[62:63], s[4:5], exec
	s_cselect_b32 s51, s55, s61
	s_cselect_b32 s53, s54, s60
	s_cselect_b32 s82, s57, s59
	s_cselect_b32 s83, s56, s58
	s_add_u32 s60, s60, 0x40480
	s_addc_u32 s61, s61, 0
	s_add_u32 s84, s58, 0x500
	s_addc_u32 s85, s59, 0
	s_mov_b32 s86, 6
	v_ashrrev_i32_e32 v131, 31, v130
	v_lshlrev_b64 v[158:159], 1, v[130:131]
	v_or_b32_e32 v132, 0x80, v130
	v_ashrrev_i32_e32 v133, 31, v132
	v_lshlrev_b64 v[162:163], 1, v[132:133]
	v_mad_u32_u24 v164, v160, s75, v158
	v_add_u32_e32 v164, 0x1200, v164
	v_mov_b32_e32 v248, 0xbfb8aa3b
	global_load_dwordx4 v[200:203], v164, s[22:23]
	global_load_dwordx4 v[204:207], v164, s[22:23] offset:2048
	global_load_dwordx4 v[208:211], v164, s[22:23] offset:256
	global_load_dwordx4 v[212:215], v164, s[22:23] offset:2304
	v_add_u32_e32 v165, 0x22000, v164
	global_load_dwordx4 v[216:219], v165, s[22:23]
	global_load_dwordx4 v[220:223], v165, s[22:23] offset:2048
	global_load_dwordx4 v[224:227], v165, s[22:23] offset:256
	global_load_dwordx4 v[228:231], v165, s[22:23] offset:2304
	v_add_u32_e32 v165, 0x44000, v164
	global_load_dwordx4 v[232:235], v165, s[22:23]
	global_load_dwordx4 v[236:239], v165, s[22:23] offset:2048
	global_load_dwordx4 v[240:243], v165, s[22:23] offset:256
	global_load_dwordx4 v[244:247], v165, s[22:23] offset:2304
	v_add_u32_e32 v165, 0x66000, v164
	global_load_dwordx4 v[172:175], v165, s[22:23]
	global_load_dwordx4 v[176:179], v165, s[22:23] offset:2048
	global_load_dwordx4 v[180:183], v165, s[22:23] offset:256
	global_load_dwordx4 v[184:187], v165, s[22:23] offset:2304
	s_waitcnt vmcnt(12)
;     DI void hook(Acc& acc, const Unit& u, int wr, int wc, int fr, int fq) const {
;     ...
;                     const u32x4 ga = *(const u32x4*)(Z + (size_t)r * NZ + ZC_GM + c0), gb = *(const u32x4*)(Z + (size_t)r * NZ + ZC_GM + DM + c0);
;                     float ra[8];
;                     const unsigned gaw[4] = {ga.x, ga.y, ga.z, ga.w}, gbw[4] = {gb.x, gb.y, gb.z, gb.w};
; #pragma unroll
;                     for (int q = 0; q < 4; ++q) {
;                         ra[2 * q] = (1.0f + __expf(-bflo(gbw[q]))) * __builtin_amdgcn_rcpf(1.0f + __expf(-bflo(gaw[q])));
;                         ra[2 * q + 1] = (1.0f + __expf(-bfhi(gbw[q]))) * __builtin_amdgcn_rcpf(1.0f + __expf(-bfhi(gaw[q])));
;                     }
;                     acc[ai][bj][m][0] = acc[ai][bj][m][0] * (f32x4){ra[0], ra[1], ra[2], ra[3]};
;                     acc[ai][bj][m][1] = acc[ai][bj][m][1] * (f32x4){ra[4], ra[5], ra[6], ra[7]};
	v_lshlrev_b32_e32 v188, 16, v200
	v_and_b32_e32 v189, 0xffff0000, v200
	v_lshlrev_b32_e32 v190, 16, v201
	v_and_b32_e32 v191, 0xffff0000, v201
	v_lshlrev_b32_e32 v192, 16, v202
	v_and_b32_e32 v193, 0xffff0000, v202
	v_lshlrev_b32_e32 v194, 16, v203
	v_and_b32_e32 v195, 0xffff0000, v203
	v_lshlrev_b32_e32 v130, 16, v204
	v_and_b32_e32 v131, 0xffff0000, v204
	v_lshlrev_b32_e32 v132, 16, v205
	v_and_b32_e32 v133, 0xffff0000, v205
	v_lshlrev_b32_e32 v134, 16, v206
	v_and_b32_e32 v135, 0xffff0000, v206
	v_lshlrev_b32_e32 v136, 16, v207
	v_and_b32_e32 v137, 0xffff0000, v207
	v_pk_mul_f32 v[188:189], v[188:189], v[248:249] op_sel_hi:[1,0]
	v_pk_mul_f32 v[190:191], v[190:191], v[248:249] op_sel_hi:[1,0]
	v_pk_mul_f32 v[192:193], v[192:193], v[248:249] op_sel_hi:[1,0]
	v_pk_mul_f32 v[194:195], v[194:195], v[248:249] op_sel_hi:[1,0]
	v_pk_mul_f32 v[130:131], v[130:131], v[248:249] op_sel_hi:[1,0]
	v_pk_mul_f32 v[132:133], v[132:133], v[248:249] op_sel_hi:[1,0]
	v_pk_mul_f32 v[134:135], v[134:135], v[248:249] op_sel_hi:[1,0]
	v_pk_mul_f32 v[136:137], v[136:137], v[248:249] op_sel_hi:[1,0]
	v_exp_f32_e32 v188, v188
	v_exp_f32_e32 v189, v189
	v_exp_f32_e32 v190, v190
	v_exp_f32_e32 v191, v191
	v_exp_f32_e32 v192, v192
	v_exp_f32_e32 v193, v193
	v_exp_f32_e32 v194, v194
	v_exp_f32_e32 v195, v195
	v_exp_f32_e32 v130, v130
	v_exp_f32_e32 v131, v131
	v_exp_f32_e32 v132, v132
	v_exp_f32_e32 v133, v133
	v_exp_f32_e32 v134, v134
	v_exp_f32_e32 v135, v135
	v_exp_f32_e32 v136, v136
	v_exp_f32_e32 v137, v137
	v_pk_add_f32 v[188:189], v[188:189], 1.0 op_sel_hi:[1,0]
	v_pk_add_f32 v[190:191], v[190:191], 1.0 op_sel_hi:[1,0]
	v_pk_add_f32 v[192:193], v[192:193], 1.0 op_sel_hi:[1,0]
	v_pk_add_f32 v[194:195], v[194:195], 1.0 op_sel_hi:[1,0]
	v_pk_add_f32 v[130:131], v[130:131], 1.0 op_sel_hi:[1,0]
	v_pk_add_f32 v[132:133], v[132:133], 1.0 op_sel_hi:[1,0]
	v_pk_add_f32 v[134:135], v[134:135], 1.0 op_sel_hi:[1,0]
	v_pk_add_f32 v[136:137], v[136:137], 1.0 op_sel_hi:[1,0]
	v_rcp_f32_e32 v188, v188
	v_rcp_f32_e32 v189, v189
	v_rcp_f32_e32 v190, v190
	v_rcp_f32_e32 v191, v191
	v_rcp_f32_e32 v192, v192
	v_rcp_f32_e32 v193, v193
	v_rcp_f32_e32 v194, v194
	v_rcp_f32_e32 v195, v195
	v_pk_mul_f32 v[130:131], v[130:131], v[188:189]
	v_pk_mul_f32 v[132:133], v[132:133], v[190:191]
	v_pk_mul_f32 v[134:135], v[134:135], v[192:193]
	v_pk_mul_f32 v[136:137], v[136:137], v[194:195]
	v_pk_mul_f32 v[34:35], v[34:35], v[130:131]
	v_pk_mul_f32 v[36:37], v[36:37], v[132:133]
	v_pk_mul_f32 v[30:31], v[30:31], v[134:135]
	v_pk_mul_f32 v[32:33], v[32:33], v[136:137]
	v_lshlrev_b32_e32 v188, 16, v208
	v_and_b32_e32 v189, 0xffff0000, v208
	v_lshlrev_b32_e32 v190, 16, v209
	v_and_b32_e32 v191, 0xffff0000, v209
	v_lshlrev_b32_e32 v192, 16, v210
	v_and_b32_e32 v193, 0xffff0000, v210
	v_lshlrev_b32_e32 v194, 16, v211
	v_and_b32_e32 v195, 0xffff0000, v211
	v_lshlrev_b32_e32 v130, 16, v212
	v_and_b32_e32 v131, 0xffff0000, v212
	v_lshlrev_b32_e32 v132, 16, v213
	v_and_b32_e32 v133, 0xffff0000, v213
	v_lshlrev_b32_e32 v134, 16, v214
	v_and_b32_e32 v135, 0xffff0000, v214
	v_lshlrev_b32_e32 v136, 16, v215
	v_and_b32_e32 v137, 0xffff0000, v215
	v_pk_mul_f32 v[188:189], v[188:189], v[248:249] op_sel_hi:[1,0]
	v_pk_mul_f32 v[190:191], v[190:191], v[248:249] op_sel_hi:[1,0]
	v_pk_mul_f32 v[192:193], v[192:193], v[248:249] op_sel_hi:[1,0]
	v_pk_mul_f32 v[194:195], v[194:195], v[248:249] op_sel_hi:[1,0]
	v_pk_mul_f32 v[130:131], v[130:131], v[248:249] op_sel_hi:[1,0]
	v_pk_mul_f32 v[132:133], v[132:133], v[248:249] op_sel_hi:[1,0]
	v_pk_mul_f32 v[134:135], v[134:135], v[248:249] op_sel_hi:[1,0]
	v_pk_mul_f32 v[136:137], v[136:137], v[248:249] op_sel_hi:[1,0]
	v_exp_f32_e32 v188, v188
	v_exp_f32_e32 v189, v189
	v_exp_f32_e32 v190, v190
	v_exp_f32_e32 v191, v191
	v_exp_f32_e32 v192, v192
	v_exp_f32_e32 v193, v193
	v_exp_f32_e32 v194, v194
	v_exp_f32_e32 v195, v195
	v_exp_f32_e32 v130, v130
	v_exp_f32_e32 v131, v131
	v_exp_f32_e32 v132, v132
	v_exp_f32_e32 v133, v133
	v_exp_f32_e32 v134, v134
	v_exp_f32_e32 v135, v135
	v_exp_f32_e32 v136, v136
	v_exp_f32_e32 v137, v137
	v_pk_add_f32 v[188:189], v[188:189], 1.0 op_sel_hi:[1,0]
	v_pk_add_f32 v[190:191], v[190:191], 1.0 op_sel_hi:[1,0]
	v_pk_add_f32 v[192:193], v[192:193], 1.0 op_sel_hi:[1,0]
	v_pk_add_f32 v[194:195], v[194:195], 1.0 op_sel_hi:[1,0]
	v_pk_add_f32 v[130:131], v[130:131], 1.0 op_sel_hi:[1,0]
	v_pk_add_f32 v[132:133], v[132:133], 1.0 op_sel_hi:[1,0]
	v_pk_add_f32 v[134:135], v[134:135], 1.0 op_sel_hi:[1,0]
	v_pk_add_f32 v[136:137], v[136:137], 1.0 op_sel_hi:[1,0]
	v_rcp_f32_e32 v188, v188
	v_rcp_f32_e32 v189, v189
	v_rcp_f32_e32 v190, v190
	v_rcp_f32_e32 v191, v191
	v_rcp_f32_e32 v192, v192
	v_rcp_f32_e32 v193, v193
	v_rcp_f32_e32 v194, v194
	v_rcp_f32_e32 v195, v195
	v_pk_mul_f32 v[130:131], v[130:131], v[188:189]
	v_pk_mul_f32 v[132:133], v[132:133], v[190:191]
	v_pk_mul_f32 v[134:135], v[134:135], v[192:193]
	v_pk_mul_f32 v[136:137], v[136:137], v[194:195]
	v_pk_mul_f32 v[50:51], v[50:51], v[130:131]
	v_pk_mul_f32 v[52:53], v[52:53], v[132:133]
	v_pk_mul_f32 v[62:63], v[62:63], v[134:135]
	v_pk_mul_f32 v[64:65], v[64:65], v[136:137]
	v_add_u32_e32 v165, 0x110000, v164
	global_load_dwordx4 v[200:203], v165, s[22:23]
	global_load_dwordx4 v[204:207], v165, s[22:23] offset:2048
	global_load_dwordx4 v[208:211], v165, s[22:23] offset:256
	global_load_dwordx4 v[212:215], v165, s[22:23] offset:2304
	s_waitcnt vmcnt(12)
;     DI void hook(Acc& acc, const Unit& u, int wr, int wc, int fr, int fq) const {
;     ...
;                     const u32x4 ga = *(const u32x4*)(Z + (size_t)r * NZ + ZC_GM + c0), gb = *(const u32x4*)(Z + (size_t)r * NZ + ZC_GM + DM + c0);
;                     float ra[8];
;                     const unsigned gaw[4] = {ga.x, ga.y, ga.z, ga.w}, gbw[4] = {gb.x, gb.y, gb.z, gb.w};
; #pragma unroll
;                     for (int q = 0; q < 4; ++q) {
;                         ra[2 * q] = (1.0f + __expf(-bflo(gbw[q]))) * __builtin_amdgcn_rcpf(1.0f + __expf(-bflo(gaw[q])));
;                         ra[2 * q + 1] = (1.0f + __expf(-bfhi(gbw[q]))) * __builtin_amdgcn_rcpf(1.0f + __expf(-bfhi(gaw[q])));
;                     }
;                     acc[ai][bj][m][0] = acc[ai][bj][m][0] * (f32x4){ra[0], ra[1], ra[2], ra[3]};
;                     acc[ai][bj][m][1] = acc[ai][bj][m][1] * (f32x4){ra[4], ra[5], ra[6], ra[7]};
	v_lshlrev_b32_e32 v188, 16, v216
	v_and_b32_e32 v189, 0xffff0000, v216
	v_lshlrev_b32_e32 v190, 16, v217
	v_and_b32_e32 v191, 0xffff0000, v217
	v_lshlrev_b32_e32 v192, 16, v218
	v_and_b32_e32 v193, 0xffff0000, v218
	v_lshlrev_b32_e32 v194, 16, v219
	v_and_b32_e32 v195, 0xffff0000, v219
	v_lshlrev_b32_e32 v130, 16, v220
	v_and_b32_e32 v131, 0xffff0000, v220
	v_lshlrev_b32_e32 v132, 16, v221
	v_and_b32_e32 v133, 0xffff0000, v221
	v_lshlrev_b32_e32 v134, 16, v222
	v_and_b32_e32 v135, 0xffff0000, v222
	v_lshlrev_b32_e32 v136, 16, v223
	v_and_b32_e32 v137, 0xffff0000, v223
	v_pk_mul_f32 v[188:189], v[188:189], v[248:249] op_sel_hi:[1,0]
	v_pk_mul_f32 v[190:191], v[190:191], v[248:249] op_sel_hi:[1,0]
	v_pk_mul_f32 v[192:193], v[192:193], v[248:249] op_sel_hi:[1,0]
	v_pk_mul_f32 v[194:195], v[194:195], v[248:249] op_sel_hi:[1,0]
	v_pk_mul_f32 v[130:131], v[130:131], v[248:249] op_sel_hi:[1,0]
	v_pk_mul_f32 v[132:133], v[132:133], v[248:249] op_sel_hi:[1,0]
	v_pk_mul_f32 v[134:135], v[134:135], v[248:249] op_sel_hi:[1,0]
	v_pk_mul_f32 v[136:137], v[136:137], v[248:249] op_sel_hi:[1,0]
	v_exp_f32_e32 v188, v188
	v_exp_f32_e32 v189, v189
	v_exp_f32_e32 v190, v190
	v_exp_f32_e32 v191, v191
	v_exp_f32_e32 v192, v192
	v_exp_f32_e32 v193, v193
	v_exp_f32_e32 v194, v194
	v_exp_f32_e32 v195, v195
	v_exp_f32_e32 v130, v130
	v_exp_f32_e32 v131, v131
	v_exp_f32_e32 v132, v132
	v_exp_f32_e32 v133, v133
	v_exp_f32_e32 v134, v134
	v_exp_f32_e32 v135, v135
	v_exp_f32_e32 v136, v136
	v_exp_f32_e32 v137, v137
	v_pk_add_f32 v[188:189], v[188:189], 1.0 op_sel_hi:[1,0]
	v_pk_add_f32 v[190:191], v[190:191], 1.0 op_sel_hi:[1,0]
	v_pk_add_f32 v[192:193], v[192:193], 1.0 op_sel_hi:[1,0]
	v_pk_add_f32 v[194:195], v[194:195], 1.0 op_sel_hi:[1,0]
	v_pk_add_f32 v[130:131], v[130:131], 1.0 op_sel_hi:[1,0]
	v_pk_add_f32 v[132:133], v[132:133], 1.0 op_sel_hi:[1,0]
	v_pk_add_f32 v[134:135], v[134:135], 1.0 op_sel_hi:[1,0]
	v_pk_add_f32 v[136:137], v[136:137], 1.0 op_sel_hi:[1,0]
	v_rcp_f32_e32 v188, v188
	v_rcp_f32_e32 v189, v189
	v_rcp_f32_e32 v190, v190
	v_rcp_f32_e32 v191, v191
	v_rcp_f32_e32 v192, v192
	v_rcp_f32_e32 v193, v193
	v_rcp_f32_e32 v194, v194
	v_rcp_f32_e32 v195, v195
	v_pk_mul_f32 v[130:131], v[130:131], v[188:189]
	v_pk_mul_f32 v[132:133], v[132:133], v[190:191]
	v_pk_mul_f32 v[134:135], v[134:135], v[192:193]
	v_pk_mul_f32 v[136:137], v[136:137], v[194:195]
	v_pk_mul_f32 v[58:59], v[58:59], v[130:131]
	v_pk_mul_f32 v[60:61], v[60:61], v[132:133]
	v_pk_mul_f32 v[54:55], v[54:55], v[134:135]
	v_pk_mul_f32 v[56:57], v[56:57], v[136:137]
	v_lshlrev_b32_e32 v188, 16, v224
	v_and_b32_e32 v189, 0xffff0000, v224
	v_lshlrev_b32_e32 v190, 16, v225
	v_and_b32_e32 v191, 0xffff0000, v225
	v_lshlrev_b32_e32 v192, 16, v226
	v_and_b32_e32 v193, 0xffff0000, v226
	v_lshlrev_b32_e32 v194, 16, v227
	v_and_b32_e32 v195, 0xffff0000, v227
	v_lshlrev_b32_e32 v130, 16, v228
	v_and_b32_e32 v131, 0xffff0000, v228
	v_lshlrev_b32_e32 v132, 16, v229
	v_and_b32_e32 v133, 0xffff0000, v229
	v_lshlrev_b32_e32 v134, 16, v230
	v_and_b32_e32 v135, 0xffff0000, v230
	v_lshlrev_b32_e32 v136, 16, v231
	v_and_b32_e32 v137, 0xffff0000, v231
	v_pk_mul_f32 v[188:189], v[188:189], v[248:249] op_sel_hi:[1,0]
	v_pk_mul_f32 v[190:191], v[190:191], v[248:249] op_sel_hi:[1,0]
	v_pk_mul_f32 v[192:193], v[192:193], v[248:249] op_sel_hi:[1,0]
	v_pk_mul_f32 v[194:195], v[194:195], v[248:249] op_sel_hi:[1,0]
	v_pk_mul_f32 v[130:131], v[130:131], v[248:249] op_sel_hi:[1,0]
	v_pk_mul_f32 v[132:133], v[132:133], v[248:249] op_sel_hi:[1,0]
	v_pk_mul_f32 v[134:135], v[134:135], v[248:249] op_sel_hi:[1,0]
	v_pk_mul_f32 v[136:137], v[136:137], v[248:249] op_sel_hi:[1,0]
	v_exp_f32_e32 v188, v188
	v_exp_f32_e32 v189, v189
	v_exp_f32_e32 v190, v190
	v_exp_f32_e32 v191, v191
	v_exp_f32_e32 v192, v192
	v_exp_f32_e32 v193, v193
	v_exp_f32_e32 v194, v194
	v_exp_f32_e32 v195, v195
	v_exp_f32_e32 v130, v130
	v_exp_f32_e32 v131, v131
	v_exp_f32_e32 v132, v132
	v_exp_f32_e32 v133, v133
	v_exp_f32_e32 v134, v134
	v_exp_f32_e32 v135, v135
	v_exp_f32_e32 v136, v136
	v_exp_f32_e32 v137, v137
	v_pk_add_f32 v[188:189], v[188:189], 1.0 op_sel_hi:[1,0]
	v_pk_add_f32 v[190:191], v[190:191], 1.0 op_sel_hi:[1,0]
	v_pk_add_f32 v[192:193], v[192:193], 1.0 op_sel_hi:[1,0]
	v_pk_add_f32 v[194:195], v[194:195], 1.0 op_sel_hi:[1,0]
	v_pk_add_f32 v[130:131], v[130:131], 1.0 op_sel_hi:[1,0]
	v_pk_add_f32 v[132:133], v[132:133], 1.0 op_sel_hi:[1,0]
	v_pk_add_f32 v[134:135], v[134:135], 1.0 op_sel_hi:[1,0]
	v_pk_add_f32 v[136:137], v[136:137], 1.0 op_sel_hi:[1,0]
	v_rcp_f32_e32 v188, v188
	v_rcp_f32_e32 v189, v189
	v_rcp_f32_e32 v190, v190
	v_rcp_f32_e32 v191, v191
	v_rcp_f32_e32 v192, v192
	v_rcp_f32_e32 v193, v193
	v_rcp_f32_e32 v194, v194
	v_rcp_f32_e32 v195, v195
	v_pk_mul_f32 v[130:131], v[130:131], v[188:189]
	v_pk_mul_f32 v[132:133], v[132:133], v[190:191]
	v_pk_mul_f32 v[134:135], v[134:135], v[192:193]
	v_pk_mul_f32 v[136:137], v[136:137], v[194:195]
	v_pk_mul_f32 v[66:67], v[66:67], v[130:131]
	v_pk_mul_f32 v[68:69], v[68:69], v[132:133]
	v_pk_mul_f32 v[78:79], v[78:79], v[134:135]
	v_pk_mul_f32 v[80:81], v[80:81], v[136:137]
	v_add_u32_e32 v165, 0x132000, v164
	global_load_dwordx4 v[216:219], v165, s[22:23]
	global_load_dwordx4 v[220:223], v165, s[22:23] offset:2048
	global_load_dwordx4 v[224:227], v165, s[22:23] offset:256
	global_load_dwordx4 v[228:231], v165, s[22:23] offset:2304
	s_waitcnt vmcnt(12)
;     DI void hook(Acc& acc, const Unit& u, int wr, int wc, int fr, int fq) const {
;     ...
;                     const u32x4 ga = *(const u32x4*)(Z + (size_t)r * NZ + ZC_GM + c0), gb = *(const u32x4*)(Z + (size_t)r * NZ + ZC_GM + DM + c0);
;                     float ra[8];
;                     const unsigned gaw[4] = {ga.x, ga.y, ga.z, ga.w}, gbw[4] = {gb.x, gb.y, gb.z, gb.w};
; #pragma unroll
;                     for (int q = 0; q < 4; ++q) {
;                         ra[2 * q] = (1.0f + __expf(-bflo(gbw[q]))) * __builtin_amdgcn_rcpf(1.0f + __expf(-bflo(gaw[q])));
;                         ra[2 * q + 1] = (1.0f + __expf(-bfhi(gbw[q]))) * __builtin_amdgcn_rcpf(1.0f + __expf(-bfhi(gaw[q])));
;                     }
;                     acc[ai][bj][m][0] = acc[ai][bj][m][0] * (f32x4){ra[0], ra[1], ra[2], ra[3]};
;                     acc[ai][bj][m][1] = acc[ai][bj][m][1] * (f32x4){ra[4], ra[5], ra[6], ra[7]};
	v_lshlrev_b32_e32 v188, 16, v232
	v_and_b32_e32 v189, 0xffff0000, v232
	v_lshlrev_b32_e32 v190, 16, v233
	v_and_b32_e32 v191, 0xffff0000, v233
	v_lshlrev_b32_e32 v192, 16, v234
	v_and_b32_e32 v193, 0xffff0000, v234
	v_lshlrev_b32_e32 v194, 16, v235
	v_and_b32_e32 v195, 0xffff0000, v235
	v_lshlrev_b32_e32 v130, 16, v236
	v_and_b32_e32 v131, 0xffff0000, v236
	v_lshlrev_b32_e32 v132, 16, v237
	v_and_b32_e32 v133, 0xffff0000, v237
	v_lshlrev_b32_e32 v134, 16, v238
	v_and_b32_e32 v135, 0xffff0000, v238
	v_lshlrev_b32_e32 v136, 16, v239
	v_and_b32_e32 v137, 0xffff0000, v239
	v_pk_mul_f32 v[188:189], v[188:189], v[248:249] op_sel_hi:[1,0]
	v_pk_mul_f32 v[190:191], v[190:191], v[248:249] op_sel_hi:[1,0]
	v_pk_mul_f32 v[192:193], v[192:193], v[248:249] op_sel_hi:[1,0]
	v_pk_mul_f32 v[194:195], v[194:195], v[248:249] op_sel_hi:[1,0]
	v_pk_mul_f32 v[130:131], v[130:131], v[248:249] op_sel_hi:[1,0]
	v_pk_mul_f32 v[132:133], v[132:133], v[248:249] op_sel_hi:[1,0]
	v_pk_mul_f32 v[134:135], v[134:135], v[248:249] op_sel_hi:[1,0]
	v_pk_mul_f32 v[136:137], v[136:137], v[248:249] op_sel_hi:[1,0]
	v_exp_f32_e32 v188, v188
	v_exp_f32_e32 v189, v189
	v_exp_f32_e32 v190, v190
	v_exp_f32_e32 v191, v191
	v_exp_f32_e32 v192, v192
	v_exp_f32_e32 v193, v193
	v_exp_f32_e32 v194, v194
	v_exp_f32_e32 v195, v195
	v_exp_f32_e32 v130, v130
	v_exp_f32_e32 v131, v131
	v_exp_f32_e32 v132, v132
	v_exp_f32_e32 v133, v133
	v_exp_f32_e32 v134, v134
	v_exp_f32_e32 v135, v135
	v_exp_f32_e32 v136, v136
	v_exp_f32_e32 v137, v137
	v_pk_add_f32 v[188:189], v[188:189], 1.0 op_sel_hi:[1,0]
	v_pk_add_f32 v[190:191], v[190:191], 1.0 op_sel_hi:[1,0]
	v_pk_add_f32 v[192:193], v[192:193], 1.0 op_sel_hi:[1,0]
	v_pk_add_f32 v[194:195], v[194:195], 1.0 op_sel_hi:[1,0]
	v_pk_add_f32 v[130:131], v[130:131], 1.0 op_sel_hi:[1,0]
	v_pk_add_f32 v[132:133], v[132:133], 1.0 op_sel_hi:[1,0]
	v_pk_add_f32 v[134:135], v[134:135], 1.0 op_sel_hi:[1,0]
	v_pk_add_f32 v[136:137], v[136:137], 1.0 op_sel_hi:[1,0]
	v_rcp_f32_e32 v188, v188
	v_rcp_f32_e32 v189, v189
	v_rcp_f32_e32 v190, v190
	v_rcp_f32_e32 v191, v191
	v_rcp_f32_e32 v192, v192
	v_rcp_f32_e32 v193, v193
	v_rcp_f32_e32 v194, v194
	v_rcp_f32_e32 v195, v195
	v_pk_mul_f32 v[130:131], v[130:131], v[188:189]
	v_pk_mul_f32 v[132:133], v[132:133], v[190:191]
	v_pk_mul_f32 v[134:135], v[134:135], v[192:193]
	v_pk_mul_f32 v[136:137], v[136:137], v[194:195]
	v_pk_mul_f32 v[74:75], v[74:75], v[130:131]
	v_pk_mul_f32 v[76:77], v[76:77], v[132:133]
	v_pk_mul_f32 v[70:71], v[70:71], v[134:135]
	v_pk_mul_f32 v[72:73], v[72:73], v[136:137]
	v_lshlrev_b32_e32 v188, 16, v240
	v_and_b32_e32 v189, 0xffff0000, v240
	v_lshlrev_b32_e32 v190, 16, v241
	v_and_b32_e32 v191, 0xffff0000, v241
	v_lshlrev_b32_e32 v192, 16, v242
	v_and_b32_e32 v193, 0xffff0000, v242
	v_lshlrev_b32_e32 v194, 16, v243
	v_and_b32_e32 v195, 0xffff0000, v243
	v_lshlrev_b32_e32 v130, 16, v244
	v_and_b32_e32 v131, 0xffff0000, v244
	v_lshlrev_b32_e32 v132, 16, v245
	v_and_b32_e32 v133, 0xffff0000, v245
	v_lshlrev_b32_e32 v134, 16, v246
	v_and_b32_e32 v135, 0xffff0000, v246
	v_lshlrev_b32_e32 v136, 16, v247
	v_and_b32_e32 v137, 0xffff0000, v247
	v_pk_mul_f32 v[188:189], v[188:189], v[248:249] op_sel_hi:[1,0]
	v_pk_mul_f32 v[190:191], v[190:191], v[248:249] op_sel_hi:[1,0]
	v_pk_mul_f32 v[192:193], v[192:193], v[248:249] op_sel_hi:[1,0]
	v_pk_mul_f32 v[194:195], v[194:195], v[248:249] op_sel_hi:[1,0]
	v_pk_mul_f32 v[130:131], v[130:131], v[248:249] op_sel_hi:[1,0]
	v_pk_mul_f32 v[132:133], v[132:133], v[248:249] op_sel_hi:[1,0]
	v_pk_mul_f32 v[134:135], v[134:135], v[248:249] op_sel_hi:[1,0]
	v_pk_mul_f32 v[136:137], v[136:137], v[248:249] op_sel_hi:[1,0]
	v_exp_f32_e32 v188, v188
	v_exp_f32_e32 v189, v189
	v_exp_f32_e32 v190, v190
	v_exp_f32_e32 v191, v191
	v_exp_f32_e32 v192, v192
	v_exp_f32_e32 v193, v193
	v_exp_f32_e32 v194, v194
	v_exp_f32_e32 v195, v195
	v_exp_f32_e32 v130, v130
	v_exp_f32_e32 v131, v131
	v_exp_f32_e32 v132, v132
	v_exp_f32_e32 v133, v133
	v_exp_f32_e32 v134, v134
	v_exp_f32_e32 v135, v135
	v_exp_f32_e32 v136, v136
	v_exp_f32_e32 v137, v137
	v_pk_add_f32 v[188:189], v[188:189], 1.0 op_sel_hi:[1,0]
	v_pk_add_f32 v[190:191], v[190:191], 1.0 op_sel_hi:[1,0]
	v_pk_add_f32 v[192:193], v[192:193], 1.0 op_sel_hi:[1,0]
	v_pk_add_f32 v[194:195], v[194:195], 1.0 op_sel_hi:[1,0]
	v_pk_add_f32 v[130:131], v[130:131], 1.0 op_sel_hi:[1,0]
	v_pk_add_f32 v[132:133], v[132:133], 1.0 op_sel_hi:[1,0]
	v_pk_add_f32 v[134:135], v[134:135], 1.0 op_sel_hi:[1,0]
	v_pk_add_f32 v[136:137], v[136:137], 1.0 op_sel_hi:[1,0]
	v_rcp_f32_e32 v188, v188
	v_rcp_f32_e32 v189, v189
	v_rcp_f32_e32 v190, v190
	v_rcp_f32_e32 v191, v191
	v_rcp_f32_e32 v192, v192
	v_rcp_f32_e32 v193, v193
	v_rcp_f32_e32 v194, v194
	v_rcp_f32_e32 v195, v195
	v_pk_mul_f32 v[130:131], v[130:131], v[188:189]
	v_pk_mul_f32 v[132:133], v[132:133], v[190:191]
	v_pk_mul_f32 v[134:135], v[134:135], v[192:193]
	v_pk_mul_f32 v[136:137], v[136:137], v[194:195]
	v_pk_mul_f32 v[82:83], v[82:83], v[130:131]
	v_pk_mul_f32 v[84:85], v[84:85], v[132:133]
	v_pk_mul_f32 v[102:103], v[102:103], v[134:135]
	v_pk_mul_f32 v[104:105], v[104:105], v[136:137]
	v_add_u32_e32 v165, 0x154000, v164
	global_load_dwordx4 v[232:235], v165, s[22:23]
	global_load_dwordx4 v[236:239], v165, s[22:23] offset:2048
	global_load_dwordx4 v[240:243], v165, s[22:23] offset:256
	global_load_dwordx4 v[244:247], v165, s[22:23] offset:2304
	s_waitcnt vmcnt(12)
;     DI void hook(Acc& acc, const Unit& u, int wr, int wc, int fr, int fq) const {
;     ...
;                     const u32x4 ga = *(const u32x4*)(Z + (size_t)r * NZ + ZC_GM + c0), gb = *(const u32x4*)(Z + (size_t)r * NZ + ZC_GM + DM + c0);
;                     float ra[8];
;                     const unsigned gaw[4] = {ga.x, ga.y, ga.z, ga.w}, gbw[4] = {gb.x, gb.y, gb.z, gb.w};
; #pragma unroll
;                     for (int q = 0; q < 4; ++q) {
;                         ra[2 * q] = (1.0f + __expf(-bflo(gbw[q]))) * __builtin_amdgcn_rcpf(1.0f + __expf(-bflo(gaw[q])));
;                         ra[2 * q + 1] = (1.0f + __expf(-bfhi(gbw[q]))) * __builtin_amdgcn_rcpf(1.0f + __expf(-bfhi(gaw[q])));
;                     }
;                     acc[ai][bj][m][0] = acc[ai][bj][m][0] * (f32x4){ra[0], ra[1], ra[2], ra[3]};
;                     acc[ai][bj][m][1] = acc[ai][bj][m][1] * (f32x4){ra[4], ra[5], ra[6], ra[7]};
	v_lshlrev_b32_e32 v188, 16, v172
	v_and_b32_e32 v189, 0xffff0000, v172
	v_lshlrev_b32_e32 v190, 16, v173
	v_and_b32_e32 v191, 0xffff0000, v173
	v_lshlrev_b32_e32 v192, 16, v174
	v_and_b32_e32 v193, 0xffff0000, v174
	v_lshlrev_b32_e32 v194, 16, v175
	v_and_b32_e32 v195, 0xffff0000, v175
	v_lshlrev_b32_e32 v130, 16, v176
	v_and_b32_e32 v131, 0xffff0000, v176
	v_lshlrev_b32_e32 v132, 16, v177
	v_and_b32_e32 v133, 0xffff0000, v177
	v_lshlrev_b32_e32 v134, 16, v178
	v_and_b32_e32 v135, 0xffff0000, v178
	v_lshlrev_b32_e32 v136, 16, v179
	v_and_b32_e32 v137, 0xffff0000, v179
	v_pk_mul_f32 v[188:189], v[188:189], v[248:249] op_sel_hi:[1,0]
	v_pk_mul_f32 v[190:191], v[190:191], v[248:249] op_sel_hi:[1,0]
	v_pk_mul_f32 v[192:193], v[192:193], v[248:249] op_sel_hi:[1,0]
	v_pk_mul_f32 v[194:195], v[194:195], v[248:249] op_sel_hi:[1,0]
	v_pk_mul_f32 v[130:131], v[130:131], v[248:249] op_sel_hi:[1,0]
	v_pk_mul_f32 v[132:133], v[132:133], v[248:249] op_sel_hi:[1,0]
	v_pk_mul_f32 v[134:135], v[134:135], v[248:249] op_sel_hi:[1,0]
	v_pk_mul_f32 v[136:137], v[136:137], v[248:249] op_sel_hi:[1,0]
	v_exp_f32_e32 v188, v188
	v_exp_f32_e32 v189, v189
	v_exp_f32_e32 v190, v190
	v_exp_f32_e32 v191, v191
	v_exp_f32_e32 v192, v192
	v_exp_f32_e32 v193, v193
	v_exp_f32_e32 v194, v194
	v_exp_f32_e32 v195, v195
	v_exp_f32_e32 v130, v130
	v_exp_f32_e32 v131, v131
	v_exp_f32_e32 v132, v132
	v_exp_f32_e32 v133, v133
	v_exp_f32_e32 v134, v134
	v_exp_f32_e32 v135, v135
	v_exp_f32_e32 v136, v136
	v_exp_f32_e32 v137, v137
	v_pk_add_f32 v[188:189], v[188:189], 1.0 op_sel_hi:[1,0]
	v_pk_add_f32 v[190:191], v[190:191], 1.0 op_sel_hi:[1,0]
	v_pk_add_f32 v[192:193], v[192:193], 1.0 op_sel_hi:[1,0]
	v_pk_add_f32 v[194:195], v[194:195], 1.0 op_sel_hi:[1,0]
	v_pk_add_f32 v[130:131], v[130:131], 1.0 op_sel_hi:[1,0]
	v_pk_add_f32 v[132:133], v[132:133], 1.0 op_sel_hi:[1,0]
	v_pk_add_f32 v[134:135], v[134:135], 1.0 op_sel_hi:[1,0]
	v_pk_add_f32 v[136:137], v[136:137], 1.0 op_sel_hi:[1,0]
	v_rcp_f32_e32 v188, v188
	v_rcp_f32_e32 v189, v189
	v_rcp_f32_e32 v190, v190
	v_rcp_f32_e32 v191, v191
	v_rcp_f32_e32 v192, v192
	v_rcp_f32_e32 v193, v193
	v_rcp_f32_e32 v194, v194
	v_rcp_f32_e32 v195, v195
	v_pk_mul_f32 v[130:131], v[130:131], v[188:189]
	v_pk_mul_f32 v[132:133], v[132:133], v[190:191]
	v_pk_mul_f32 v[134:135], v[134:135], v[192:193]
	v_pk_mul_f32 v[136:137], v[136:137], v[194:195]
	v_pk_mul_f32 v[110:111], v[110:111], v[130:131]
	v_pk_mul_f32 v[112:113], v[112:113], v[132:133]
	v_pk_mul_f32 v[106:107], v[106:107], v[134:135]
	v_pk_mul_f32 v[108:109], v[108:109], v[136:137]
	v_lshlrev_b32_e32 v188, 16, v180
	v_and_b32_e32 v189, 0xffff0000, v180
	v_lshlrev_b32_e32 v190, 16, v181
	v_and_b32_e32 v191, 0xffff0000, v181
	v_lshlrev_b32_e32 v192, 16, v182
	v_and_b32_e32 v193, 0xffff0000, v182
	v_lshlrev_b32_e32 v194, 16, v183
	v_and_b32_e32 v195, 0xffff0000, v183
	v_lshlrev_b32_e32 v130, 16, v184
	v_and_b32_e32 v131, 0xffff0000, v184
	v_lshlrev_b32_e32 v132, 16, v185
	v_and_b32_e32 v133, 0xffff0000, v185
	v_lshlrev_b32_e32 v134, 16, v186
	v_and_b32_e32 v135, 0xffff0000, v186
	v_lshlrev_b32_e32 v136, 16, v187
	v_and_b32_e32 v137, 0xffff0000, v187
	v_pk_mul_f32 v[188:189], v[188:189], v[248:249] op_sel_hi:[1,0]
	v_pk_mul_f32 v[190:191], v[190:191], v[248:249] op_sel_hi:[1,0]
	v_pk_mul_f32 v[192:193], v[192:193], v[248:249] op_sel_hi:[1,0]
	v_pk_mul_f32 v[194:195], v[194:195], v[248:249] op_sel_hi:[1,0]
	v_pk_mul_f32 v[130:131], v[130:131], v[248:249] op_sel_hi:[1,0]
	v_pk_mul_f32 v[132:133], v[132:133], v[248:249] op_sel_hi:[1,0]
	v_pk_mul_f32 v[134:135], v[134:135], v[248:249] op_sel_hi:[1,0]
	v_pk_mul_f32 v[136:137], v[136:137], v[248:249] op_sel_hi:[1,0]
	v_exp_f32_e32 v188, v188
	v_exp_f32_e32 v189, v189
	v_exp_f32_e32 v190, v190
	v_exp_f32_e32 v191, v191
	v_exp_f32_e32 v192, v192
	v_exp_f32_e32 v193, v193
	v_exp_f32_e32 v194, v194
	v_exp_f32_e32 v195, v195
	v_exp_f32_e32 v130, v130
	v_exp_f32_e32 v131, v131
	v_exp_f32_e32 v132, v132
	v_exp_f32_e32 v133, v133
	v_exp_f32_e32 v134, v134
	v_exp_f32_e32 v135, v135
	v_exp_f32_e32 v136, v136
	v_exp_f32_e32 v137, v137
	v_pk_add_f32 v[188:189], v[188:189], 1.0 op_sel_hi:[1,0]
	v_pk_add_f32 v[190:191], v[190:191], 1.0 op_sel_hi:[1,0]
	v_pk_add_f32 v[192:193], v[192:193], 1.0 op_sel_hi:[1,0]
	v_pk_add_f32 v[194:195], v[194:195], 1.0 op_sel_hi:[1,0]
	v_pk_add_f32 v[130:131], v[130:131], 1.0 op_sel_hi:[1,0]
	v_pk_add_f32 v[132:133], v[132:133], 1.0 op_sel_hi:[1,0]
	v_pk_add_f32 v[134:135], v[134:135], 1.0 op_sel_hi:[1,0]
	v_pk_add_f32 v[136:137], v[136:137], 1.0 op_sel_hi:[1,0]
	v_rcp_f32_e32 v188, v188
	v_rcp_f32_e32 v189, v189
	v_rcp_f32_e32 v190, v190
	v_rcp_f32_e32 v191, v191
	v_rcp_f32_e32 v192, v192
	v_rcp_f32_e32 v193, v193
	v_rcp_f32_e32 v194, v194
	v_rcp_f32_e32 v195, v195
	v_pk_mul_f32 v[130:131], v[130:131], v[188:189]
	v_pk_mul_f32 v[132:133], v[132:133], v[190:191]
	v_pk_mul_f32 v[134:135], v[134:135], v[192:193]
	v_pk_mul_f32 v[136:137], v[136:137], v[194:195]
	v_pk_mul_f32 v[114:115], v[114:115], v[130:131]
	v_pk_mul_f32 v[116:117], v[116:117], v[132:133]
	v_pk_mul_f32 v[126:127], v[126:127], v[134:135]
	v_pk_mul_f32 v[128:129], v[128:129], v[136:137]
	v_add_u32_e32 v165, 0x176000, v164
	global_load_dwordx4 v[172:175], v165, s[22:23]
	global_load_dwordx4 v[176:179], v165, s[22:23] offset:2048
	global_load_dwordx4 v[180:183], v165, s[22:23] offset:256
	global_load_dwordx4 v[184:187], v165, s[22:23] offset:2304
	s_waitcnt vmcnt(12)
;     DI void hook(Acc& acc, const Unit& u, int wr, int wc, int fr, int fq) const {
;     ...
;                     const u32x4 ga = *(const u32x4*)(Z + (size_t)r * NZ + ZC_GM + c0), gb = *(const u32x4*)(Z + (size_t)r * NZ + ZC_GM + DM + c0);
;                     float ra[8];
;                     const unsigned gaw[4] = {ga.x, ga.y, ga.z, ga.w}, gbw[4] = {gb.x, gb.y, gb.z, gb.w};
; #pragma unroll
;                     for (int q = 0; q < 4; ++q) {
;                         ra[2 * q] = (1.0f + __expf(-bflo(gbw[q]))) * __builtin_amdgcn_rcpf(1.0f + __expf(-bflo(gaw[q])));
;                         ra[2 * q + 1] = (1.0f + __expf(-bfhi(gbw[q]))) * __builtin_amdgcn_rcpf(1.0f + __expf(-bfhi(gaw[q])));
;                     }
;                     acc[ai][bj][m][0] = acc[ai][bj][m][0] * (f32x4){ra[0], ra[1], ra[2], ra[3]};
;                     acc[ai][bj][m][1] = acc[ai][bj][m][1] * (f32x4){ra[4], ra[5], ra[6], ra[7]};
	v_lshlrev_b32_e32 v188, 16, v200
	v_and_b32_e32 v189, 0xffff0000, v200
	v_lshlrev_b32_e32 v190, 16, v201
	v_and_b32_e32 v191, 0xffff0000, v201
	v_lshlrev_b32_e32 v192, 16, v202
	v_and_b32_e32 v193, 0xffff0000, v202
	v_lshlrev_b32_e32 v194, 16, v203
	v_and_b32_e32 v195, 0xffff0000, v203
	v_lshlrev_b32_e32 v130, 16, v204
	v_and_b32_e32 v131, 0xffff0000, v204
	v_lshlrev_b32_e32 v132, 16, v205
	v_and_b32_e32 v133, 0xffff0000, v205
	v_lshlrev_b32_e32 v134, 16, v206
	v_and_b32_e32 v135, 0xffff0000, v206
	v_lshlrev_b32_e32 v136, 16, v207
	v_and_b32_e32 v137, 0xffff0000, v207
	v_pk_mul_f32 v[188:189], v[188:189], v[248:249] op_sel_hi:[1,0]
	v_pk_mul_f32 v[190:191], v[190:191], v[248:249] op_sel_hi:[1,0]
	v_pk_mul_f32 v[192:193], v[192:193], v[248:249] op_sel_hi:[1,0]
	v_pk_mul_f32 v[194:195], v[194:195], v[248:249] op_sel_hi:[1,0]
	v_pk_mul_f32 v[130:131], v[130:131], v[248:249] op_sel_hi:[1,0]
	v_pk_mul_f32 v[132:133], v[132:133], v[248:249] op_sel_hi:[1,0]
	v_pk_mul_f32 v[134:135], v[134:135], v[248:249] op_sel_hi:[1,0]
	v_pk_mul_f32 v[136:137], v[136:137], v[248:249] op_sel_hi:[1,0]
	v_exp_f32_e32 v188, v188
	v_exp_f32_e32 v189, v189
	v_exp_f32_e32 v190, v190
	v_exp_f32_e32 v191, v191
	v_exp_f32_e32 v192, v192
	v_exp_f32_e32 v193, v193
	v_exp_f32_e32 v194, v194
	v_exp_f32_e32 v195, v195
	v_exp_f32_e32 v130, v130
	v_exp_f32_e32 v131, v131
	v_exp_f32_e32 v132, v132
	v_exp_f32_e32 v133, v133
	v_exp_f32_e32 v134, v134
	v_exp_f32_e32 v135, v135
	v_exp_f32_e32 v136, v136
	v_exp_f32_e32 v137, v137
	v_pk_add_f32 v[188:189], v[188:189], 1.0 op_sel_hi:[1,0]
	v_pk_add_f32 v[190:191], v[190:191], 1.0 op_sel_hi:[1,0]
	v_pk_add_f32 v[192:193], v[192:193], 1.0 op_sel_hi:[1,0]
	v_pk_add_f32 v[194:195], v[194:195], 1.0 op_sel_hi:[1,0]
	v_pk_add_f32 v[130:131], v[130:131], 1.0 op_sel_hi:[1,0]
	v_pk_add_f32 v[132:133], v[132:133], 1.0 op_sel_hi:[1,0]
	v_pk_add_f32 v[134:135], v[134:135], 1.0 op_sel_hi:[1,0]
	v_pk_add_f32 v[136:137], v[136:137], 1.0 op_sel_hi:[1,0]
	v_rcp_f32_e32 v188, v188
	v_rcp_f32_e32 v189, v189
	v_rcp_f32_e32 v190, v190
	v_rcp_f32_e32 v191, v191
	v_rcp_f32_e32 v192, v192
	v_rcp_f32_e32 v193, v193
	v_rcp_f32_e32 v194, v194
	v_rcp_f32_e32 v195, v195
	v_pk_mul_f32 v[130:131], v[130:131], v[188:189]
	v_pk_mul_f32 v[132:133], v[132:133], v[190:191]
	v_pk_mul_f32 v[134:135], v[134:135], v[192:193]
	v_pk_mul_f32 v[136:137], v[136:137], v[194:195]
	v_pk_mul_f32 v[122:123], v[122:123], v[130:131]
	v_pk_mul_f32 v[124:125], v[124:125], v[132:133]
	v_pk_mul_f32 v[118:119], v[118:119], v[134:135]
	v_pk_mul_f32 v[120:121], v[120:121], v[136:137]
	v_lshlrev_b32_e32 v188, 16, v208
	v_and_b32_e32 v189, 0xffff0000, v208
	v_lshlrev_b32_e32 v190, 16, v209
	v_and_b32_e32 v191, 0xffff0000, v209
	v_lshlrev_b32_e32 v192, 16, v210
	v_and_b32_e32 v193, 0xffff0000, v210
	v_lshlrev_b32_e32 v194, 16, v211
	v_and_b32_e32 v195, 0xffff0000, v211
	v_lshlrev_b32_e32 v130, 16, v212
	v_and_b32_e32 v131, 0xffff0000, v212
	v_lshlrev_b32_e32 v132, 16, v213
	v_and_b32_e32 v133, 0xffff0000, v213
	v_lshlrev_b32_e32 v134, 16, v214
	v_and_b32_e32 v135, 0xffff0000, v214
	v_lshlrev_b32_e32 v136, 16, v215
	v_and_b32_e32 v137, 0xffff0000, v215
	v_pk_mul_f32 v[188:189], v[188:189], v[248:249] op_sel_hi:[1,0]
	v_pk_mul_f32 v[190:191], v[190:191], v[248:249] op_sel_hi:[1,0]
	v_pk_mul_f32 v[192:193], v[192:193], v[248:249] op_sel_hi:[1,0]
	v_pk_mul_f32 v[194:195], v[194:195], v[248:249] op_sel_hi:[1,0]
	v_pk_mul_f32 v[130:131], v[130:131], v[248:249] op_sel_hi:[1,0]
	v_pk_mul_f32 v[132:133], v[132:133], v[248:249] op_sel_hi:[1,0]
	v_pk_mul_f32 v[134:135], v[134:135], v[248:249] op_sel_hi:[1,0]
	v_pk_mul_f32 v[136:137], v[136:137], v[248:249] op_sel_hi:[1,0]
	v_exp_f32_e32 v188, v188
	v_exp_f32_e32 v189, v189
	v_exp_f32_e32 v190, v190
	v_exp_f32_e32 v191, v191
	v_exp_f32_e32 v192, v192
	v_exp_f32_e32 v193, v193
	v_exp_f32_e32 v194, v194
	v_exp_f32_e32 v195, v195
	v_exp_f32_e32 v130, v130
	v_exp_f32_e32 v131, v131
	v_exp_f32_e32 v132, v132
	v_exp_f32_e32 v133, v133
	v_exp_f32_e32 v134, v134
	v_exp_f32_e32 v135, v135
	v_exp_f32_e32 v136, v136
	v_exp_f32_e32 v137, v137
	v_pk_add_f32 v[188:189], v[188:189], 1.0 op_sel_hi:[1,0]
	v_pk_add_f32 v[190:191], v[190:191], 1.0 op_sel_hi:[1,0]
	v_pk_add_f32 v[192:193], v[192:193], 1.0 op_sel_hi:[1,0]
	v_pk_add_f32 v[194:195], v[194:195], 1.0 op_sel_hi:[1,0]
	v_pk_add_f32 v[130:131], v[130:131], 1.0 op_sel_hi:[1,0]
	v_pk_add_f32 v[132:133], v[132:133], 1.0 op_sel_hi:[1,0]
	v_pk_add_f32 v[134:135], v[134:135], 1.0 op_sel_hi:[1,0]
	v_pk_add_f32 v[136:137], v[136:137], 1.0 op_sel_hi:[1,0]
	v_rcp_f32_e32 v188, v188
	v_rcp_f32_e32 v189, v189
	v_rcp_f32_e32 v190, v190
	v_rcp_f32_e32 v191, v191
	v_rcp_f32_e32 v192, v192
	v_rcp_f32_e32 v193, v193
	v_rcp_f32_e32 v194, v194
	v_rcp_f32_e32 v195, v195
	v_pk_mul_f32 v[130:131], v[130:131], v[188:189]
	v_pk_mul_f32 v[132:133], v[132:133], v[190:191]
	v_pk_mul_f32 v[134:135], v[134:135], v[192:193]
	v_pk_mul_f32 v[136:137], v[136:137], v[194:195]
	v_pk_mul_f32 v[98:99], v[98:99], v[130:131]
	v_pk_mul_f32 v[100:101], v[100:101], v[132:133]
	v_pk_mul_f32 v[94:95], v[94:95], v[134:135]
	v_pk_mul_f32 v[96:97], v[96:97], v[136:137]
	s_waitcnt vmcnt(8)
;     DI void hook(Acc& acc, const Unit& u, int wr, int wc, int fr, int fq) const {
;     ...
;                     const u32x4 ga = *(const u32x4*)(Z + (size_t)r * NZ + ZC_GM + c0), gb = *(const u32x4*)(Z + (size_t)r * NZ + ZC_GM + DM + c0);
;                     float ra[8];
;                     const unsigned gaw[4] = {ga.x, ga.y, ga.z, ga.w}, gbw[4] = {gb.x, gb.y, gb.z, gb.w};
; #pragma unroll
;                     for (int q = 0; q < 4; ++q) {
;                         ra[2 * q] = (1.0f + __expf(-bflo(gbw[q]))) * __builtin_amdgcn_rcpf(1.0f + __expf(-bflo(gaw[q])));
;                         ra[2 * q + 1] = (1.0f + __expf(-bfhi(gbw[q]))) * __builtin_amdgcn_rcpf(1.0f + __expf(-bfhi(gaw[q])));
;                     }
;                     acc[ai][bj][m][0] = acc[ai][bj][m][0] * (f32x4){ra[0], ra[1], ra[2], ra[3]};
;                     acc[ai][bj][m][1] = acc[ai][bj][m][1] * (f32x4){ra[4], ra[5], ra[6], ra[7]};
	v_lshlrev_b32_e32 v188, 16, v216
	v_and_b32_e32 v189, 0xffff0000, v216
	v_lshlrev_b32_e32 v190, 16, v217
	v_and_b32_e32 v191, 0xffff0000, v217
	v_lshlrev_b32_e32 v192, 16, v218
	v_and_b32_e32 v193, 0xffff0000, v218
	v_lshlrev_b32_e32 v194, 16, v219
	v_and_b32_e32 v195, 0xffff0000, v219
	v_lshlrev_b32_e32 v130, 16, v220
	v_and_b32_e32 v131, 0xffff0000, v220
	v_lshlrev_b32_e32 v132, 16, v221
	v_and_b32_e32 v133, 0xffff0000, v221
	v_lshlrev_b32_e32 v134, 16, v222
	v_and_b32_e32 v135, 0xffff0000, v222
	v_lshlrev_b32_e32 v136, 16, v223
	v_and_b32_e32 v137, 0xffff0000, v223
	v_pk_mul_f32 v[188:189], v[188:189], v[248:249] op_sel_hi:[1,0]
	v_pk_mul_f32 v[190:191], v[190:191], v[248:249] op_sel_hi:[1,0]
	v_pk_mul_f32 v[192:193], v[192:193], v[248:249] op_sel_hi:[1,0]
	v_pk_mul_f32 v[194:195], v[194:195], v[248:249] op_sel_hi:[1,0]
	v_pk_mul_f32 v[130:131], v[130:131], v[248:249] op_sel_hi:[1,0]
	v_pk_mul_f32 v[132:133], v[132:133], v[248:249] op_sel_hi:[1,0]
	v_pk_mul_f32 v[134:135], v[134:135], v[248:249] op_sel_hi:[1,0]
	v_pk_mul_f32 v[136:137], v[136:137], v[248:249] op_sel_hi:[1,0]
	v_exp_f32_e32 v188, v188
	v_exp_f32_e32 v189, v189
	v_exp_f32_e32 v190, v190
	v_exp_f32_e32 v191, v191
	v_exp_f32_e32 v192, v192
	v_exp_f32_e32 v193, v193
	v_exp_f32_e32 v194, v194
	v_exp_f32_e32 v195, v195
	v_exp_f32_e32 v130, v130
	v_exp_f32_e32 v131, v131
	v_exp_f32_e32 v132, v132
	v_exp_f32_e32 v133, v133
	v_exp_f32_e32 v134, v134
	v_exp_f32_e32 v135, v135
	v_exp_f32_e32 v136, v136
	v_exp_f32_e32 v137, v137
	v_pk_add_f32 v[188:189], v[188:189], 1.0 op_sel_hi:[1,0]
	v_pk_add_f32 v[190:191], v[190:191], 1.0 op_sel_hi:[1,0]
	v_pk_add_f32 v[192:193], v[192:193], 1.0 op_sel_hi:[1,0]
	v_pk_add_f32 v[194:195], v[194:195], 1.0 op_sel_hi:[1,0]
	v_pk_add_f32 v[130:131], v[130:131], 1.0 op_sel_hi:[1,0]
	v_pk_add_f32 v[132:133], v[132:133], 1.0 op_sel_hi:[1,0]
	v_pk_add_f32 v[134:135], v[134:135], 1.0 op_sel_hi:[1,0]
	v_pk_add_f32 v[136:137], v[136:137], 1.0 op_sel_hi:[1,0]
	v_rcp_f32_e32 v188, v188
	v_rcp_f32_e32 v189, v189
	v_rcp_f32_e32 v190, v190
	v_rcp_f32_e32 v191, v191
	v_rcp_f32_e32 v192, v192
	v_rcp_f32_e32 v193, v193
	v_rcp_f32_e32 v194, v194
	v_rcp_f32_e32 v195, v195
	v_pk_mul_f32 v[130:131], v[130:131], v[188:189]
	v_pk_mul_f32 v[132:133], v[132:133], v[190:191]
	v_pk_mul_f32 v[134:135], v[134:135], v[192:193]
	v_pk_mul_f32 v[136:137], v[136:137], v[194:195]
	v_pk_mul_f32 v[90:91], v[90:91], v[130:131]
	v_pk_mul_f32 v[92:93], v[92:93], v[132:133]
	v_pk_mul_f32 v[86:87], v[86:87], v[134:135]
	v_pk_mul_f32 v[88:89], v[88:89], v[136:137]
	v_lshlrev_b32_e32 v188, 16, v224
	v_and_b32_e32 v189, 0xffff0000, v224
	v_lshlrev_b32_e32 v190, 16, v225
	v_and_b32_e32 v191, 0xffff0000, v225
	v_lshlrev_b32_e32 v192, 16, v226
	v_and_b32_e32 v193, 0xffff0000, v226
	v_lshlrev_b32_e32 v194, 16, v227
	v_and_b32_e32 v195, 0xffff0000, v227
	v_lshlrev_b32_e32 v130, 16, v228
	v_and_b32_e32 v131, 0xffff0000, v228
	v_lshlrev_b32_e32 v132, 16, v229
	v_and_b32_e32 v133, 0xffff0000, v229
	v_lshlrev_b32_e32 v134, 16, v230
	v_and_b32_e32 v135, 0xffff0000, v230
	v_lshlrev_b32_e32 v136, 16, v231
	v_and_b32_e32 v137, 0xffff0000, v231
	v_pk_mul_f32 v[188:189], v[188:189], v[248:249] op_sel_hi:[1,0]
	v_pk_mul_f32 v[190:191], v[190:191], v[248:249] op_sel_hi:[1,0]
	v_pk_mul_f32 v[192:193], v[192:193], v[248:249] op_sel_hi:[1,0]
	v_pk_mul_f32 v[194:195], v[194:195], v[248:249] op_sel_hi:[1,0]
	v_pk_mul_f32 v[130:131], v[130:131], v[248:249] op_sel_hi:[1,0]
	v_pk_mul_f32 v[132:133], v[132:133], v[248:249] op_sel_hi:[1,0]
	v_pk_mul_f32 v[134:135], v[134:135], v[248:249] op_sel_hi:[1,0]
	v_pk_mul_f32 v[136:137], v[136:137], v[248:249] op_sel_hi:[1,0]
	v_exp_f32_e32 v188, v188
	v_exp_f32_e32 v189, v189
	v_exp_f32_e32 v190, v190
	v_exp_f32_e32 v191, v191
	v_exp_f32_e32 v192, v192
	v_exp_f32_e32 v193, v193
	v_exp_f32_e32 v194, v194
	v_exp_f32_e32 v195, v195
	v_exp_f32_e32 v130, v130
	v_exp_f32_e32 v131, v131
	v_exp_f32_e32 v132, v132
	v_exp_f32_e32 v133, v133
	v_exp_f32_e32 v134, v134
	v_exp_f32_e32 v135, v135
	v_exp_f32_e32 v136, v136
	v_exp_f32_e32 v137, v137
	v_pk_add_f32 v[188:189], v[188:189], 1.0 op_sel_hi:[1,0]
	v_pk_add_f32 v[190:191], v[190:191], 1.0 op_sel_hi:[1,0]
	v_pk_add_f32 v[192:193], v[192:193], 1.0 op_sel_hi:[1,0]
	v_pk_add_f32 v[194:195], v[194:195], 1.0 op_sel_hi:[1,0]
	v_pk_add_f32 v[130:131], v[130:131], 1.0 op_sel_hi:[1,0]
	v_pk_add_f32 v[132:133], v[132:133], 1.0 op_sel_hi:[1,0]
	v_pk_add_f32 v[134:135], v[134:135], 1.0 op_sel_hi:[1,0]
	v_pk_add_f32 v[136:137], v[136:137], 1.0 op_sel_hi:[1,0]
	v_rcp_f32_e32 v188, v188
	v_rcp_f32_e32 v189, v189
	v_rcp_f32_e32 v190, v190
	v_rcp_f32_e32 v191, v191
	v_rcp_f32_e32 v192, v192
	v_rcp_f32_e32 v193, v193
	v_rcp_f32_e32 v194, v194
	v_rcp_f32_e32 v195, v195
	v_pk_mul_f32 v[130:131], v[130:131], v[188:189]
	v_pk_mul_f32 v[132:133], v[132:133], v[190:191]
	v_pk_mul_f32 v[134:135], v[134:135], v[192:193]
	v_pk_mul_f32 v[136:137], v[136:137], v[194:195]
	v_pk_mul_f32 v[46:47], v[46:47], v[130:131]
	v_pk_mul_f32 v[48:49], v[48:49], v[132:133]
	v_pk_mul_f32 v[42:43], v[42:43], v[134:135]
	v_pk_mul_f32 v[44:45], v[44:45], v[136:137]
	s_waitcnt vmcnt(4)
;     DI void hook(Acc& acc, const Unit& u, int wr, int wc, int fr, int fq) const {
;     ...
;                     const u32x4 ga = *(const u32x4*)(Z + (size_t)r * NZ + ZC_GM + c0), gb = *(const u32x4*)(Z + (size_t)r * NZ + ZC_GM + DM + c0);
;                     float ra[8];
;                     const unsigned gaw[4] = {ga.x, ga.y, ga.z, ga.w}, gbw[4] = {gb.x, gb.y, gb.z, gb.w};
; #pragma unroll
;                     for (int q = 0; q < 4; ++q) {
;                         ra[2 * q] = (1.0f + __expf(-bflo(gbw[q]))) * __builtin_amdgcn_rcpf(1.0f + __expf(-bflo(gaw[q])));
;                         ra[2 * q + 1] = (1.0f + __expf(-bfhi(gbw[q]))) * __builtin_amdgcn_rcpf(1.0f + __expf(-bfhi(gaw[q])));
;                     }
;                     acc[ai][bj][m][0] = acc[ai][bj][m][0] * (f32x4){ra[0], ra[1], ra[2], ra[3]};
;                     acc[ai][bj][m][1] = acc[ai][bj][m][1] * (f32x4){ra[4], ra[5], ra[6], ra[7]};
	v_lshlrev_b32_e32 v188, 16, v232
	v_and_b32_e32 v189, 0xffff0000, v232
	v_lshlrev_b32_e32 v190, 16, v233
	v_and_b32_e32 v191, 0xffff0000, v233
	v_lshlrev_b32_e32 v192, 16, v234
	v_and_b32_e32 v193, 0xffff0000, v234
	v_lshlrev_b32_e32 v194, 16, v235
	v_and_b32_e32 v195, 0xffff0000, v235
	v_lshlrev_b32_e32 v130, 16, v236
	v_and_b32_e32 v131, 0xffff0000, v236
	v_lshlrev_b32_e32 v132, 16, v237
	v_and_b32_e32 v133, 0xffff0000, v237
	v_lshlrev_b32_e32 v134, 16, v238
	v_and_b32_e32 v135, 0xffff0000, v238
	v_lshlrev_b32_e32 v136, 16, v239
	v_and_b32_e32 v137, 0xffff0000, v239
	v_pk_mul_f32 v[188:189], v[188:189], v[248:249] op_sel_hi:[1,0]
	v_pk_mul_f32 v[190:191], v[190:191], v[248:249] op_sel_hi:[1,0]
	v_pk_mul_f32 v[192:193], v[192:193], v[248:249] op_sel_hi:[1,0]
	v_pk_mul_f32 v[194:195], v[194:195], v[248:249] op_sel_hi:[1,0]
	v_pk_mul_f32 v[130:131], v[130:131], v[248:249] op_sel_hi:[1,0]
	v_pk_mul_f32 v[132:133], v[132:133], v[248:249] op_sel_hi:[1,0]
	v_pk_mul_f32 v[134:135], v[134:135], v[248:249] op_sel_hi:[1,0]
	v_pk_mul_f32 v[136:137], v[136:137], v[248:249] op_sel_hi:[1,0]
	v_exp_f32_e32 v188, v188
	v_exp_f32_e32 v189, v189
	v_exp_f32_e32 v190, v190
	v_exp_f32_e32 v191, v191
	v_exp_f32_e32 v192, v192
	v_exp_f32_e32 v193, v193
	v_exp_f32_e32 v194, v194
	v_exp_f32_e32 v195, v195
	v_exp_f32_e32 v130, v130
	v_exp_f32_e32 v131, v131
	v_exp_f32_e32 v132, v132
	v_exp_f32_e32 v133, v133
	v_exp_f32_e32 v134, v134
	v_exp_f32_e32 v135, v135
	v_exp_f32_e32 v136, v136
	v_exp_f32_e32 v137, v137
	v_pk_add_f32 v[188:189], v[188:189], 1.0 op_sel_hi:[1,0]
	v_pk_add_f32 v[190:191], v[190:191], 1.0 op_sel_hi:[1,0]
	v_pk_add_f32 v[192:193], v[192:193], 1.0 op_sel_hi:[1,0]
	v_pk_add_f32 v[194:195], v[194:195], 1.0 op_sel_hi:[1,0]
	v_pk_add_f32 v[130:131], v[130:131], 1.0 op_sel_hi:[1,0]
	v_pk_add_f32 v[132:133], v[132:133], 1.0 op_sel_hi:[1,0]
	v_pk_add_f32 v[134:135], v[134:135], 1.0 op_sel_hi:[1,0]
	v_pk_add_f32 v[136:137], v[136:137], 1.0 op_sel_hi:[1,0]
	v_rcp_f32_e32 v188, v188
	v_rcp_f32_e32 v189, v189
	v_rcp_f32_e32 v190, v190
	v_rcp_f32_e32 v191, v191
	v_rcp_f32_e32 v192, v192
	v_rcp_f32_e32 v193, v193
	v_rcp_f32_e32 v194, v194
	v_rcp_f32_e32 v195, v195
	v_pk_mul_f32 v[130:131], v[130:131], v[188:189]
	v_pk_mul_f32 v[132:133], v[132:133], v[190:191]
	v_pk_mul_f32 v[134:135], v[134:135], v[192:193]
	v_pk_mul_f32 v[136:137], v[136:137], v[194:195]
	v_pk_mul_f32 v[38:39], v[38:39], v[130:131]
	v_pk_mul_f32 v[40:41], v[40:41], v[132:133]
	v_pk_mul_f32 v[26:27], v[26:27], v[134:135]
	v_pk_mul_f32 v[28:29], v[28:29], v[136:137]
	v_lshlrev_b32_e32 v188, 16, v240
	v_and_b32_e32 v189, 0xffff0000, v240
	v_lshlrev_b32_e32 v190, 16, v241
	v_and_b32_e32 v191, 0xffff0000, v241
	v_lshlrev_b32_e32 v192, 16, v242
	v_and_b32_e32 v193, 0xffff0000, v242
	v_lshlrev_b32_e32 v194, 16, v243
	v_and_b32_e32 v195, 0xffff0000, v243
	v_lshlrev_b32_e32 v130, 16, v244
	v_and_b32_e32 v131, 0xffff0000, v244
	v_lshlrev_b32_e32 v132, 16, v245
	v_and_b32_e32 v133, 0xffff0000, v245
	v_lshlrev_b32_e32 v134, 16, v246
	v_and_b32_e32 v135, 0xffff0000, v246
	v_lshlrev_b32_e32 v136, 16, v247
	v_and_b32_e32 v137, 0xffff0000, v247
	v_pk_mul_f32 v[188:189], v[188:189], v[248:249] op_sel_hi:[1,0]
	v_pk_mul_f32 v[190:191], v[190:191], v[248:249] op_sel_hi:[1,0]
	v_pk_mul_f32 v[192:193], v[192:193], v[248:249] op_sel_hi:[1,0]
	v_pk_mul_f32 v[194:195], v[194:195], v[248:249] op_sel_hi:[1,0]
	v_pk_mul_f32 v[130:131], v[130:131], v[248:249] op_sel_hi:[1,0]
	v_pk_mul_f32 v[132:133], v[132:133], v[248:249] op_sel_hi:[1,0]
	v_pk_mul_f32 v[134:135], v[134:135], v[248:249] op_sel_hi:[1,0]
	v_pk_mul_f32 v[136:137], v[136:137], v[248:249] op_sel_hi:[1,0]
	v_exp_f32_e32 v188, v188
	v_exp_f32_e32 v189, v189
	v_exp_f32_e32 v190, v190
	v_exp_f32_e32 v191, v191
	v_exp_f32_e32 v192, v192
	v_exp_f32_e32 v193, v193
	v_exp_f32_e32 v194, v194
	v_exp_f32_e32 v195, v195
	v_exp_f32_e32 v130, v130
	v_exp_f32_e32 v131, v131
	v_exp_f32_e32 v132, v132
	v_exp_f32_e32 v133, v133
	v_exp_f32_e32 v134, v134
	v_exp_f32_e32 v135, v135
	v_exp_f32_e32 v136, v136
	v_exp_f32_e32 v137, v137
	v_pk_add_f32 v[188:189], v[188:189], 1.0 op_sel_hi:[1,0]
	v_pk_add_f32 v[190:191], v[190:191], 1.0 op_sel_hi:[1,0]
	v_pk_add_f32 v[192:193], v[192:193], 1.0 op_sel_hi:[1,0]
	v_pk_add_f32 v[194:195], v[194:195], 1.0 op_sel_hi:[1,0]
	v_pk_add_f32 v[130:131], v[130:131], 1.0 op_sel_hi:[1,0]
	v_pk_add_f32 v[132:133], v[132:133], 1.0 op_sel_hi:[1,0]
	v_pk_add_f32 v[134:135], v[134:135], 1.0 op_sel_hi:[1,0]
	v_pk_add_f32 v[136:137], v[136:137], 1.0 op_sel_hi:[1,0]
	v_rcp_f32_e32 v188, v188
	v_rcp_f32_e32 v189, v189
	v_rcp_f32_e32 v190, v190
	v_rcp_f32_e32 v191, v191
	v_rcp_f32_e32 v192, v192
	v_rcp_f32_e32 v193, v193
	v_rcp_f32_e32 v194, v194
	v_rcp_f32_e32 v195, v195
	v_pk_mul_f32 v[130:131], v[130:131], v[188:189]
	v_pk_mul_f32 v[132:133], v[132:133], v[190:191]
	v_pk_mul_f32 v[134:135], v[134:135], v[192:193]
	v_pk_mul_f32 v[136:137], v[136:137], v[194:195]
	v_pk_mul_f32 v[22:23], v[22:23], v[130:131]
	v_pk_mul_f32 v[24:25], v[24:25], v[132:133]
	v_pk_mul_f32 v[18:19], v[18:19], v[134:135]
	v_pk_mul_f32 v[20:21], v[20:21], v[136:137]
	s_waitcnt vmcnt(0)
;     DI void hook(Acc& acc, const Unit& u, int wr, int wc, int fr, int fq) const {
;     ...
;                     const u32x4 ga = *(const u32x4*)(Z + (size_t)r * NZ + ZC_GM + c0), gb = *(const u32x4*)(Z + (size_t)r * NZ + ZC_GM + DM + c0);
;                     float ra[8];
;                     const unsigned gaw[4] = {ga.x, ga.y, ga.z, ga.w}, gbw[4] = {gb.x, gb.y, gb.z, gb.w};
; #pragma unroll
;                     for (int q = 0; q < 4; ++q) {
;                         ra[2 * q] = (1.0f + __expf(-bflo(gbw[q]))) * __builtin_amdgcn_rcpf(1.0f + __expf(-bflo(gaw[q])));
;                         ra[2 * q + 1] = (1.0f + __expf(-bfhi(gbw[q]))) * __builtin_amdgcn_rcpf(1.0f + __expf(-bfhi(gaw[q])));
;                     }
;                     acc[ai][bj][m][0] = acc[ai][bj][m][0] * (f32x4){ra[0], ra[1], ra[2], ra[3]};
;                     acc[ai][bj][m][1] = acc[ai][bj][m][1] * (f32x4){ra[4], ra[5], ra[6], ra[7]};
	v_lshlrev_b32_e32 v188, 16, v172
	v_and_b32_e32 v189, 0xffff0000, v172
	v_lshlrev_b32_e32 v190, 16, v173
	v_and_b32_e32 v191, 0xffff0000, v173
	v_lshlrev_b32_e32 v192, 16, v174
	v_and_b32_e32 v193, 0xffff0000, v174
	v_lshlrev_b32_e32 v194, 16, v175
	v_and_b32_e32 v195, 0xffff0000, v175
	v_lshlrev_b32_e32 v130, 16, v176
	v_and_b32_e32 v131, 0xffff0000, v176
	v_lshlrev_b32_e32 v132, 16, v177
	v_and_b32_e32 v133, 0xffff0000, v177
	v_lshlrev_b32_e32 v134, 16, v178
	v_and_b32_e32 v135, 0xffff0000, v178
	v_lshlrev_b32_e32 v136, 16, v179
	v_and_b32_e32 v137, 0xffff0000, v179
	v_pk_mul_f32 v[188:189], v[188:189], v[248:249] op_sel_hi:[1,0]
	v_pk_mul_f32 v[190:191], v[190:191], v[248:249] op_sel_hi:[1,0]
	v_pk_mul_f32 v[192:193], v[192:193], v[248:249] op_sel_hi:[1,0]
	v_pk_mul_f32 v[194:195], v[194:195], v[248:249] op_sel_hi:[1,0]
	v_pk_mul_f32 v[130:131], v[130:131], v[248:249] op_sel_hi:[1,0]
	v_pk_mul_f32 v[132:133], v[132:133], v[248:249] op_sel_hi:[1,0]
	v_pk_mul_f32 v[134:135], v[134:135], v[248:249] op_sel_hi:[1,0]
	v_pk_mul_f32 v[136:137], v[136:137], v[248:249] op_sel_hi:[1,0]
	v_exp_f32_e32 v188, v188
	v_exp_f32_e32 v189, v189
	v_exp_f32_e32 v190, v190
	v_exp_f32_e32 v191, v191
	v_exp_f32_e32 v192, v192
	v_exp_f32_e32 v193, v193
	v_exp_f32_e32 v194, v194
	v_exp_f32_e32 v195, v195
	v_exp_f32_e32 v130, v130
	v_exp_f32_e32 v131, v131
	v_exp_f32_e32 v132, v132
	v_exp_f32_e32 v133, v133
	v_exp_f32_e32 v134, v134
	v_exp_f32_e32 v135, v135
	v_exp_f32_e32 v136, v136
	v_exp_f32_e32 v137, v137
	v_pk_add_f32 v[188:189], v[188:189], 1.0 op_sel_hi:[1,0]
	v_pk_add_f32 v[190:191], v[190:191], 1.0 op_sel_hi:[1,0]
	v_pk_add_f32 v[192:193], v[192:193], 1.0 op_sel_hi:[1,0]
	v_pk_add_f32 v[194:195], v[194:195], 1.0 op_sel_hi:[1,0]
	v_pk_add_f32 v[130:131], v[130:131], 1.0 op_sel_hi:[1,0]
	v_pk_add_f32 v[132:133], v[132:133], 1.0 op_sel_hi:[1,0]
	v_pk_add_f32 v[134:135], v[134:135], 1.0 op_sel_hi:[1,0]
	v_pk_add_f32 v[136:137], v[136:137], 1.0 op_sel_hi:[1,0]
	v_rcp_f32_e32 v188, v188
	v_rcp_f32_e32 v189, v189
	v_rcp_f32_e32 v190, v190
	v_rcp_f32_e32 v191, v191
	v_rcp_f32_e32 v192, v192
	v_rcp_f32_e32 v193, v193
	v_rcp_f32_e32 v194, v194
	v_rcp_f32_e32 v195, v195
	v_pk_mul_f32 v[130:131], v[130:131], v[188:189]
	v_pk_mul_f32 v[132:133], v[132:133], v[190:191]
	v_pk_mul_f32 v[134:135], v[134:135], v[192:193]
	v_pk_mul_f32 v[136:137], v[136:137], v[194:195]
	v_pk_mul_f32 v[14:15], v[14:15], v[130:131]
	v_pk_mul_f32 v[16:17], v[16:17], v[132:133]
	v_pk_mul_f32 v[10:11], v[10:11], v[134:135]
	v_pk_mul_f32 v[12:13], v[12:13], v[136:137]
	v_lshlrev_b32_e32 v188, 16, v180
	v_and_b32_e32 v189, 0xffff0000, v180
	v_lshlrev_b32_e32 v190, 16, v181
	v_and_b32_e32 v191, 0xffff0000, v181
	v_lshlrev_b32_e32 v192, 16, v182
	v_and_b32_e32 v193, 0xffff0000, v182
	v_lshlrev_b32_e32 v194, 16, v183
	v_and_b32_e32 v195, 0xffff0000, v183
	v_lshlrev_b32_e32 v130, 16, v184
	v_and_b32_e32 v131, 0xffff0000, v184
	v_lshlrev_b32_e32 v132, 16, v185
	v_and_b32_e32 v133, 0xffff0000, v185
	v_lshlrev_b32_e32 v134, 16, v186
	v_and_b32_e32 v135, 0xffff0000, v186
	v_lshlrev_b32_e32 v136, 16, v187
	v_and_b32_e32 v137, 0xffff0000, v187
	v_pk_mul_f32 v[188:189], v[188:189], v[248:249] op_sel_hi:[1,0]
	v_pk_mul_f32 v[190:191], v[190:191], v[248:249] op_sel_hi:[1,0]
	v_pk_mul_f32 v[192:193], v[192:193], v[248:249] op_sel_hi:[1,0]
	v_pk_mul_f32 v[194:195], v[194:195], v[248:249] op_sel_hi:[1,0]
	v_pk_mul_f32 v[130:131], v[130:131], v[248:249] op_sel_hi:[1,0]
	v_pk_mul_f32 v[132:133], v[132:133], v[248:249] op_sel_hi:[1,0]
	v_pk_mul_f32 v[134:135], v[134:135], v[248:249] op_sel_hi:[1,0]
	v_pk_mul_f32 v[136:137], v[136:137], v[248:249] op_sel_hi:[1,0]
	v_exp_f32_e32 v188, v188
	v_exp_f32_e32 v189, v189
	v_exp_f32_e32 v190, v190
	v_exp_f32_e32 v191, v191
	v_exp_f32_e32 v192, v192
	v_exp_f32_e32 v193, v193
	v_exp_f32_e32 v194, v194
	v_exp_f32_e32 v195, v195
	v_exp_f32_e32 v130, v130
	v_exp_f32_e32 v131, v131
	v_exp_f32_e32 v132, v132
	v_exp_f32_e32 v133, v133
	v_exp_f32_e32 v134, v134
	v_exp_f32_e32 v135, v135
	v_exp_f32_e32 v136, v136
	v_exp_f32_e32 v137, v137
	v_pk_add_f32 v[188:189], v[188:189], 1.0 op_sel_hi:[1,0]
	v_pk_add_f32 v[190:191], v[190:191], 1.0 op_sel_hi:[1,0]
	v_pk_add_f32 v[192:193], v[192:193], 1.0 op_sel_hi:[1,0]
	v_pk_add_f32 v[194:195], v[194:195], 1.0 op_sel_hi:[1,0]
	v_pk_add_f32 v[130:131], v[130:131], 1.0 op_sel_hi:[1,0]
	v_pk_add_f32 v[132:133], v[132:133], 1.0 op_sel_hi:[1,0]
	v_pk_add_f32 v[134:135], v[134:135], 1.0 op_sel_hi:[1,0]
	v_pk_add_f32 v[136:137], v[136:137], 1.0 op_sel_hi:[1,0]
	v_rcp_f32_e32 v188, v188
	v_rcp_f32_e32 v189, v189
	v_rcp_f32_e32 v190, v190
	v_rcp_f32_e32 v191, v191
	v_rcp_f32_e32 v192, v192
	v_rcp_f32_e32 v193, v193
	v_rcp_f32_e32 v194, v194
	v_rcp_f32_e32 v195, v195
	v_pk_mul_f32 v[130:131], v[130:131], v[188:189]
	v_pk_mul_f32 v[132:133], v[132:133], v[190:191]
	v_pk_mul_f32 v[134:135], v[134:135], v[192:193]
	v_pk_mul_f32 v[136:137], v[136:137], v[194:195]
	v_pk_mul_f32 v[6:7], v[6:7], v[130:131]
	v_pk_mul_f32 v[8:9], v[8:9], v[132:133]
	v_pk_mul_f32 v[2:3], v[2:3], v[134:135]
	v_pk_mul_f32 v[4:5], v[4:5], v[136:137]
.LBB0_872:
	ds_read_b128 v[130:133], v168
	ds_read_b128 v[134:137], v168 offset:1024
	ds_read_b128 v[172:175], v168 offset:2048
	ds_read_b128 v[176:179], v168 offset:3072
	ds_read_b128 v[180:183], v169
	ds_read_b128 v[184:187], v169 offset:1024
	ds_read_b128 v[188:191], v169 offset:2048
	ds_read_b128 v[192:195], v169 offset:3072
	s_add_u32 s58, s60, 0xfffc0080
	s_addc_u32 s59, s61, -1
	s_cmp_eq_u32 s86, 12
	s_cselect_b32 s63, s51, s59
	s_cselect_b32 s62, s53, s58
	s_cselect_b32 s59, s82, s85
	s_cselect_b32 s58, s83, s84
	s_mov_b32 m0, s71
	v_lshl_add_u64 v[164:165], s[60:61], 0, v[148:149]
	ds_read_b128 v[200:203], v170
	ds_read_b128 v[204:207], v170 offset:1024
	ds_read_b128 v[208:211], v170 offset:2048
	ds_read_b128 v[212:215], v170 offset:3072
	ds_read_b128 v[216:219], v170 offset:4096
	ds_read_b128 v[220:223], v170 offset:5120
	ds_read_b128 v[224:227], v170 offset:6144
	ds_read_b128 v[228:231], v170 offset:7168
	global_load_lds_dwordx4 v[164:165], off
	v_lshl_add_u64 v[164:165], s[60:61], 0, v[142:143]
	s_mov_b32 m0, s72
	s_nop 0
	global_load_lds_dwordx4 v[164:165], off
	s_waitcnt vmcnt(8)
	s_waitcnt lgkmcnt(0)
	s_barrier
	s_waitcnt lgkmcnt(0)
	v_mfma_f32_16x16x32_bf16 v[34:37], v[130:133], v[200:203], v[34:37]
	v_mfma_f32_16x16x32_bf16 v[30:33], v[172:175], v[200:203], v[30:33]
	v_mfma_f32_16x16x32_bf16 v[58:61], v[130:133], v[208:211], v[58:61]
	v_mfma_f32_16x16x32_bf16 v[54:57], v[172:175], v[208:211], v[54:57]
	v_mfma_f32_16x16x32_bf16 v[74:77], v[130:133], v[216:219], v[74:77]
	v_mfma_f32_16x16x32_bf16 v[70:73], v[172:175], v[216:219], v[70:73]
	v_mfma_f32_16x16x32_bf16 v[110:113], v[130:133], v[224:227], v[110:113]
	v_mfma_f32_16x16x32_bf16 v[106:109], v[172:175], v[224:227], v[106:109]
	v_mfma_f32_16x16x32_bf16 v[34:37], v[134:137], v[204:207], v[34:37]
	v_mfma_f32_16x16x32_bf16 v[30:33], v[176:179], v[204:207], v[30:33]
	v_mfma_f32_16x16x32_bf16 v[58:61], v[134:137], v[212:215], v[58:61]
	v_mfma_f32_16x16x32_bf16 v[54:57], v[176:179], v[212:215], v[54:57]
	v_mfma_f32_16x16x32_bf16 v[74:77], v[134:137], v[220:223], v[74:77]
	v_mfma_f32_16x16x32_bf16 v[70:73], v[176:179], v[220:223], v[70:73]
	v_mfma_f32_16x16x32_bf16 v[110:113], v[134:137], v[228:231], v[110:113]
	v_mfma_f32_16x16x32_bf16 v[106:109], v[176:179], v[228:231], v[106:109]
	v_mfma_f32_16x16x32_bf16 v[50:53], v[180:183], v[200:203], v[50:53]
	v_mfma_f32_16x16x32_bf16 v[62:65], v[188:191], v[200:203], v[62:65]
	v_mfma_f32_16x16x32_bf16 v[66:69], v[180:183], v[208:211], v[66:69]
	v_mfma_f32_16x16x32_bf16 v[78:81], v[188:191], v[208:211], v[78:81]
	v_mfma_f32_16x16x32_bf16 v[82:85], v[180:183], v[216:219], v[82:85]
	v_mfma_f32_16x16x32_bf16 v[102:105], v[188:191], v[216:219], v[102:105]
	v_mfma_f32_16x16x32_bf16 v[114:117], v[180:183], v[224:227], v[114:117]
	v_mfma_f32_16x16x32_bf16 v[126:129], v[188:191], v[224:227], v[126:129]
	v_mfma_f32_16x16x32_bf16 v[50:53], v[184:187], v[204:207], v[50:53]
	v_mfma_f32_16x16x32_bf16 v[62:65], v[192:195], v[204:207], v[62:65]
	v_mfma_f32_16x16x32_bf16 v[66:69], v[184:187], v[212:215], v[66:69]
	v_mfma_f32_16x16x32_bf16 v[78:81], v[192:195], v[212:215], v[78:81]
	v_mfma_f32_16x16x32_bf16 v[82:85], v[184:187], v[220:223], v[82:85]
	v_mfma_f32_16x16x32_bf16 v[102:105], v[192:195], v[220:223], v[102:105]
	v_mfma_f32_16x16x32_bf16 v[114:117], v[184:187], v[228:231], v[114:117]
	v_mfma_f32_16x16x32_bf16 v[126:129], v[192:195], v[228:231], v[126:129]
	s_barrier
	s_mov_b32 m0, s73
	v_lshl_add_u64 v[164:165], s[58:59], 0, v[140:141]
	s_add_u32 s88, s58, 0x40000
	ds_read_b128 v[200:203], v170 offset:16384
	ds_read_b128 v[204:207], v170 offset:17408
	ds_read_b128 v[208:211], v170 offset:18432
	ds_read_b128 v[212:215], v170 offset:19456
	ds_read_b128 v[216:219], v170 offset:20480
	ds_read_b128 v[220:223], v170 offset:21504
	ds_read_b128 v[224:227], v170 offset:22528
	ds_read_b128 v[228:231], v170 offset:23552
	global_load_lds_dwordx4 v[164:165], off
	v_lshl_add_u64 v[196:197], s[58:59], 0, v[144:145]
	s_mov_b32 m0, s74
	s_addc_u32 s89, s59, 0
	global_load_lds_dwordx4 v[196:197], off
	v_lshl_add_u64 v[232:233], s[88:89], 0, v[140:141]
	s_mov_b32 m0, s76
	v_lshl_add_u64 v[234:235], s[62:63], 0, v[142:143]
	global_load_lds_dwordx4 v[232:233], off
	v_lshl_add_u64 v[232:233], s[88:89], 0, v[144:145]
	s_mov_b32 m0, s77
	s_nop 0
	global_load_lds_dwordx4 v[232:233], off
	v_lshl_add_u64 v[232:233], s[62:63], 0, v[138:139]
	s_mov_b32 m0, s21
	s_nop 0
	global_load_lds_dwordx4 v[232:233], off
	s_mov_b32 m0, s64
	s_nop 0
	global_load_lds_dwordx4 v[234:235], off
	s_waitcnt vmcnt(8)
	s_waitcnt lgkmcnt(0)
	s_barrier
	s_waitcnt lgkmcnt(0)
	v_mfma_f32_16x16x32_bf16 v[122:125], v[130:133], v[200:203], v[122:125]
	v_mfma_f32_16x16x32_bf16 v[118:121], v[172:175], v[200:203], v[118:121]
	v_mfma_f32_16x16x32_bf16 v[90:93], v[130:133], v[208:211], v[90:93]
	v_mfma_f32_16x16x32_bf16 v[86:89], v[172:175], v[208:211], v[86:89]
	v_mfma_f32_16x16x32_bf16 v[38:41], v[130:133], v[216:219], v[38:41]
	v_mfma_f32_16x16x32_bf16 v[26:29], v[172:175], v[216:219], v[26:29]
	v_mfma_f32_16x16x32_bf16 v[14:17], v[130:133], v[224:227], v[14:17]
	v_mfma_f32_16x16x32_bf16 v[10:13], v[172:175], v[224:227], v[10:13]
	v_mfma_f32_16x16x32_bf16 v[122:125], v[134:137], v[204:207], v[122:125]
	v_mfma_f32_16x16x32_bf16 v[118:121], v[176:179], v[204:207], v[118:121]
	v_mfma_f32_16x16x32_bf16 v[90:93], v[134:137], v[212:215], v[90:93]
	v_mfma_f32_16x16x32_bf16 v[86:89], v[176:179], v[212:215], v[86:89]
	v_mfma_f32_16x16x32_bf16 v[38:41], v[134:137], v[220:223], v[38:41]
	v_mfma_f32_16x16x32_bf16 v[26:29], v[176:179], v[220:223], v[26:29]
	v_mfma_f32_16x16x32_bf16 v[14:17], v[134:137], v[228:231], v[14:17]
	v_mfma_f32_16x16x32_bf16 v[10:13], v[176:179], v[228:231], v[10:13]
	v_mfma_f32_16x16x32_bf16 v[98:101], v[180:183], v[200:203], v[98:101]
	v_mfma_f32_16x16x32_bf16 v[94:97], v[188:191], v[200:203], v[94:97]
	v_mfma_f32_16x16x32_bf16 v[46:49], v[180:183], v[208:211], v[46:49]
	v_mfma_f32_16x16x32_bf16 v[42:45], v[188:191], v[208:211], v[42:45]
	v_mfma_f32_16x16x32_bf16 v[22:25], v[180:183], v[216:219], v[22:25]
	v_mfma_f32_16x16x32_bf16 v[18:21], v[188:191], v[216:219], v[18:21]
	v_mfma_f32_16x16x32_bf16 v[6:9], v[180:183], v[224:227], v[6:9]
	v_mfma_f32_16x16x32_bf16 v[2:5], v[188:191], v[224:227], v[2:5]
	v_mfma_f32_16x16x32_bf16 v[98:101], v[184:187], v[204:207], v[98:101]
	v_mfma_f32_16x16x32_bf16 v[94:97], v[192:195], v[204:207], v[94:97]
	v_mfma_f32_16x16x32_bf16 v[46:49], v[184:187], v[212:215], v[46:49]
	v_mfma_f32_16x16x32_bf16 v[42:45], v[192:195], v[212:215], v[42:45]
	v_mfma_f32_16x16x32_bf16 v[22:25], v[184:187], v[220:223], v[22:25]
	v_mfma_f32_16x16x32_bf16 v[18:21], v[192:195], v[220:223], v[18:21]
	v_mfma_f32_16x16x32_bf16 v[6:9], v[184:187], v[228:231], v[6:9]
	v_mfma_f32_16x16x32_bf16 v[2:5], v[192:195], v[228:231], v[2:5]
	s_barrier
	ds_read_b128 v[130:133], v161
	ds_read_b128 v[134:137], v161 offset:1024
	ds_read_b128 v[172:175], v161 offset:2048
	ds_read_b128 v[176:179], v161 offset:3072
	ds_read_b128 v[180:183], v171
	ds_read_b128 v[184:187], v171 offset:1024
	ds_read_b128 v[188:191], v171 offset:2048
	ds_read_b128 v[192:195], v171 offset:3072
	s_add_u32 s62, s62, 0x40000
	s_addc_u32 s63, s63, 0
	s_mov_b32 m0, s65
	v_lshl_add_u64 v[236:237], s[62:63], 0, v[138:139]
	ds_read_b128 v[200:203], v170 offset:32768
	ds_read_b128 v[204:207], v170 offset:33792
	ds_read_b128 v[208:211], v170 offset:34816
	ds_read_b128 v[212:215], v170 offset:35840
	ds_read_b128 v[216:219], v170 offset:36864
	ds_read_b128 v[220:223], v170 offset:37888
	ds_read_b128 v[224:227], v170 offset:38912
	ds_read_b128 v[228:231], v170 offset:39936
	global_load_lds_dwordx4 v[236:237], off
	v_lshl_add_u64 v[236:237], s[62:63], 0, v[142:143]
	s_mov_b32 m0, s66
	s_nop 0
	global_load_lds_dwordx4 v[236:237], off
	s_waitcnt vmcnt(8)
	s_waitcnt lgkmcnt(0)
	s_barrier
	s_waitcnt lgkmcnt(0)
	v_mfma_f32_16x16x32_bf16 v[34:37], v[130:133], v[200:203], v[34:37]
	v_mfma_f32_16x16x32_bf16 v[30:33], v[172:175], v[200:203], v[30:33]
	v_mfma_f32_16x16x32_bf16 v[58:61], v[130:133], v[208:211], v[58:61]
	v_mfma_f32_16x16x32_bf16 v[54:57], v[172:175], v[208:211], v[54:57]
	v_mfma_f32_16x16x32_bf16 v[74:77], v[130:133], v[216:219], v[74:77]
	v_mfma_f32_16x16x32_bf16 v[70:73], v[172:175], v[216:219], v[70:73]
	v_mfma_f32_16x16x32_bf16 v[110:113], v[130:133], v[224:227], v[110:113]
	v_mfma_f32_16x16x32_bf16 v[106:109], v[172:175], v[224:227], v[106:109]
	v_mfma_f32_16x16x32_bf16 v[34:37], v[134:137], v[204:207], v[34:37]
	v_mfma_f32_16x16x32_bf16 v[30:33], v[176:179], v[204:207], v[30:33]
	v_mfma_f32_16x16x32_bf16 v[58:61], v[134:137], v[212:215], v[58:61]
	v_mfma_f32_16x16x32_bf16 v[54:57], v[176:179], v[212:215], v[54:57]
	v_mfma_f32_16x16x32_bf16 v[74:77], v[134:137], v[220:223], v[74:77]
	v_mfma_f32_16x16x32_bf16 v[70:73], v[176:179], v[220:223], v[70:73]
	v_mfma_f32_16x16x32_bf16 v[110:113], v[134:137], v[228:231], v[110:113]
	v_mfma_f32_16x16x32_bf16 v[106:109], v[176:179], v[228:231], v[106:109]
	v_mfma_f32_16x16x32_bf16 v[50:53], v[180:183], v[200:203], v[50:53]
	v_mfma_f32_16x16x32_bf16 v[62:65], v[188:191], v[200:203], v[62:65]
	v_mfma_f32_16x16x32_bf16 v[66:69], v[180:183], v[208:211], v[66:69]
	v_mfma_f32_16x16x32_bf16 v[78:81], v[188:191], v[208:211], v[78:81]
	v_mfma_f32_16x16x32_bf16 v[82:85], v[180:183], v[216:219], v[82:85]
	v_mfma_f32_16x16x32_bf16 v[102:105], v[188:191], v[216:219], v[102:105]
	v_mfma_f32_16x16x32_bf16 v[114:117], v[180:183], v[224:227], v[114:117]
	v_mfma_f32_16x16x32_bf16 v[126:129], v[188:191], v[224:227], v[126:129]
	v_mfma_f32_16x16x32_bf16 v[50:53], v[184:187], v[204:207], v[50:53]
	v_mfma_f32_16x16x32_bf16 v[62:65], v[192:195], v[204:207], v[62:65]
	v_mfma_f32_16x16x32_bf16 v[66:69], v[184:187], v[212:215], v[66:69]
	v_mfma_f32_16x16x32_bf16 v[78:81], v[192:195], v[212:215], v[78:81]
	v_mfma_f32_16x16x32_bf16 v[82:85], v[184:187], v[220:223], v[82:85]
	v_mfma_f32_16x16x32_bf16 v[102:105], v[192:195], v[220:223], v[102:105]
	v_mfma_f32_16x16x32_bf16 v[114:117], v[184:187], v[228:231], v[114:117]
	v_mfma_f32_16x16x32_bf16 v[126:129], v[192:195], v[228:231], v[126:129]
	s_barrier
; #define PG8_BAR __builtin_amdgcn_s_barrier()
; template <class Epi, bool HOOK = false>
; DI void gemm_phase(LAS unsigned char* lds, const Gemm g, const StaticOrder& S, const Epi& E) {
;     ...
;         if constexpr (HOOK) {
;             for (int t = 0; t < (nt >> 1); t += 2) PG8_KBODY();
;             E.hook(acc, cur, wr, wc, fr, fq);
;             for (int t = (nt >> 1); t < nt; t += 2) PG8_KBODY();
;         } else {
;             for (int t = 0; t < nt; t += 2) PG8_KBODY();
;         }
;     ...
;         if (wr == 0) PG8_BAR;
	s_mov_b32 m0, s78
	v_lshl_add_u64 v[164:165], v[164:165], 0, s[12:13]
	s_add_u32 s58, s58, 0x40080
	ds_read_b128 v[200:203], v170 offset:49152
	ds_read_b128 v[204:207], v170 offset:50176
	ds_read_b128 v[208:211], v170 offset:51200
	ds_read_b128 v[212:215], v170 offset:52224
	ds_read_b128 v[216:219], v170 offset:53248
	ds_read_b128 v[220:223], v170 offset:54272
	ds_read_b128 v[224:227], v170 offset:55296
	ds_read_b128 v[228:231], v170 offset:56320
	global_load_lds_dwordx4 v[164:165], off
	v_lshl_add_u64 v[164:165], v[196:197], 0, s[12:13]
	s_mov_b32 m0, s79
	s_addc_u32 s59, s59, 0
	global_load_lds_dwordx4 v[164:165], off
	v_lshl_add_u64 v[164:165], s[58:59], 0, v[140:141]
	s_mov_b32 m0, s80
	s_nop 0
	global_load_lds_dwordx4 v[164:165], off
	v_lshl_add_u64 v[164:165], s[58:59], 0, v[144:145]
	s_mov_b32 m0, s81
	s_nop 0
	global_load_lds_dwordx4 v[164:165], off
	v_lshl_add_u64 v[164:165], v[232:233], 0, s[12:13]
	s_mov_b32 m0, s68
	s_nop 0
	global_load_lds_dwordx4 v[164:165], off
	v_lshl_add_u64 v[164:165], v[234:235], 0, s[12:13]
	s_mov_b32 m0, s69
	s_nop 0
	global_load_lds_dwordx4 v[164:165], off
	s_waitcnt vmcnt(8)
	s_waitcnt lgkmcnt(0)
	s_barrier
	s_waitcnt lgkmcnt(0)
	v_mfma_f32_16x16x32_bf16 v[122:125], v[130:133], v[200:203], v[122:125]
	v_mfma_f32_16x16x32_bf16 v[118:121], v[172:175], v[200:203], v[118:121]
	v_mfma_f32_16x16x32_bf16 v[90:93], v[130:133], v[208:211], v[90:93]
	v_mfma_f32_16x16x32_bf16 v[86:89], v[172:175], v[208:211], v[86:89]
	v_mfma_f32_16x16x32_bf16 v[38:41], v[130:133], v[216:219], v[38:41]
	v_mfma_f32_16x16x32_bf16 v[26:29], v[172:175], v[216:219], v[26:29]
	v_mfma_f32_16x16x32_bf16 v[14:17], v[130:133], v[224:227], v[14:17]
	v_mfma_f32_16x16x32_bf16 v[10:13], v[172:175], v[224:227], v[10:13]
	v_mfma_f32_16x16x32_bf16 v[122:125], v[134:137], v[204:207], v[122:125]
	v_mfma_f32_16x16x32_bf16 v[118:121], v[176:179], v[204:207], v[118:121]
	v_mfma_f32_16x16x32_bf16 v[90:93], v[134:137], v[212:215], v[90:93]
	v_mfma_f32_16x16x32_bf16 v[86:89], v[176:179], v[212:215], v[86:89]
	v_mfma_f32_16x16x32_bf16 v[38:41], v[134:137], v[220:223], v[38:41]
	v_mfma_f32_16x16x32_bf16 v[26:29], v[176:179], v[220:223], v[26:29]
	v_mfma_f32_16x16x32_bf16 v[14:17], v[134:137], v[228:231], v[14:17]
	v_mfma_f32_16x16x32_bf16 v[10:13], v[176:179], v[228:231], v[10:13]
	v_mfma_f32_16x16x32_bf16 v[98:101], v[180:183], v[200:203], v[98:101]
	v_mfma_f32_16x16x32_bf16 v[94:97], v[188:191], v[200:203], v[94:97]
	v_mfma_f32_16x16x32_bf16 v[46:49], v[180:183], v[208:211], v[46:49]
	v_mfma_f32_16x16x32_bf16 v[42:45], v[188:191], v[208:211], v[42:45]
	v_mfma_f32_16x16x32_bf16 v[22:25], v[180:183], v[216:219], v[22:25]
	v_mfma_f32_16x16x32_bf16 v[18:21], v[188:191], v[216:219], v[18:21]
	v_mfma_f32_16x16x32_bf16 v[6:9], v[180:183], v[224:227], v[6:9]
	v_mfma_f32_16x16x32_bf16 v[2:5], v[188:191], v[224:227], v[2:5]
	v_mfma_f32_16x16x32_bf16 v[98:101], v[184:187], v[204:207], v[98:101]
	v_mfma_f32_16x16x32_bf16 v[94:97], v[192:195], v[204:207], v[94:97]
	v_mfma_f32_16x16x32_bf16 v[46:49], v[184:187], v[212:215], v[46:49]
	v_mfma_f32_16x16x32_bf16 v[42:45], v[192:195], v[212:215], v[42:45]
	v_mfma_f32_16x16x32_bf16 v[22:25], v[184:187], v[220:223], v[22:25]
	v_mfma_f32_16x16x32_bf16 v[18:21], v[192:195], v[220:223], v[18:21]
	v_mfma_f32_16x16x32_bf16 v[6:9], v[184:187], v[228:231], v[6:9]
	v_mfma_f32_16x16x32_bf16 v[2:5], v[192:195], v[228:231], v[2:5]
	s_barrier
	s_add_i32 s86, s86, 2
	s_add_u32 s60, s60, 0x100
	s_addc_u32 s61, s61, 0
	s_add_u32 s84, s84, 0x100
	s_addc_u32 s85, s85, 0
	s_cmp_gt_u32 s86, 13
	s_cbranch_scc0 .LBB0_872
	s_and_b64 vcc, exec, s[26:27]
	s_cbranch_vccz .LBB0_875
	s_barrier

.LBB0_950:
	ds_read_b128 v[146:149], v152
	ds_read_b128 v[156:159], v152 offset:1024
	ds_read_b128 v[160:163], v152 offset:2048
	ds_read_b128 v[164:167], v152 offset:3072
	ds_read_b128 v[168:171], v153
	ds_read_b128 v[172:175], v153 offset:1024
	ds_read_b128 v[176:179], v153 offset:2048
	ds_read_b128 v[180:183], v153 offset:3072
	s_add_u32 s52, s50, 0xfffc0080
	s_addc_u32 s53, s51, -1
	s_cmp_eq_u32 s68, 12
	s_cselect_b32 s55, s43, s53
	s_cselect_b32 s54, s49, s52
	s_cselect_b32 s53, s41, s67
	s_cselect_b32 s52, s65, s66
	v_lshl_add_u64 v[196:197], s[50:51], 0, v[138:139]
	s_add_i32 m0, s21, 0xc000
	ds_read_b128 v[184:187], v154
	ds_read_b128 v[188:191], v154 offset:1024
	ds_read_b128 v[192:195], v154 offset:2048
	ds_read_b128 v[200:203], v154 offset:3072
	ds_read_b128 v[204:207], v154 offset:4096
	ds_read_b128 v[208:211], v154 offset:5120
	ds_read_b128 v[212:215], v154 offset:6144
	ds_read_b128 v[216:219], v154 offset:7168
	global_load_lds_dwordx4 v[196:197], off
	v_lshl_add_u64 v[196:197], s[50:51], 0, v[140:141]
	s_add_i32 m0, s21, 0xe000
	s_nop 0
	global_load_lds_dwordx4 v[196:197], off
	s_waitcnt vmcnt(8)
	s_waitcnt lgkmcnt(0)
	s_barrier
	s_waitcnt lgkmcnt(0)
	v_mfma_f32_16x16x32_bf16 v[126:129], v[146:149], v[184:187], v[126:129]
	v_mfma_f32_16x16x32_bf16 v[122:125], v[160:163], v[184:187], v[122:125]
	v_mfma_f32_16x16x32_bf16 v[110:113], v[146:149], v[192:195], v[110:113]
	v_mfma_f32_16x16x32_bf16 v[106:109], v[160:163], v[192:195], v[106:109]
	v_mfma_f32_16x16x32_bf16 v[94:97], v[146:149], v[204:207], v[94:97]
	v_mfma_f32_16x16x32_bf16 v[90:93], v[160:163], v[204:207], v[90:93]
	v_mfma_f32_16x16x32_bf16 v[78:81], v[146:149], v[212:215], v[78:81]
	v_mfma_f32_16x16x32_bf16 v[74:77], v[160:163], v[212:215], v[74:77]
	v_mfma_f32_16x16x32_bf16 v[126:129], v[156:159], v[188:191], v[126:129]
	v_mfma_f32_16x16x32_bf16 v[122:125], v[164:167], v[188:191], v[122:125]
	v_mfma_f32_16x16x32_bf16 v[110:113], v[156:159], v[200:203], v[110:113]
	v_mfma_f32_16x16x32_bf16 v[106:109], v[164:167], v[200:203], v[106:109]
	v_mfma_f32_16x16x32_bf16 v[94:97], v[156:159], v[208:211], v[94:97]
	v_mfma_f32_16x16x32_bf16 v[90:93], v[164:167], v[208:211], v[90:93]
	v_mfma_f32_16x16x32_bf16 v[78:81], v[156:159], v[216:219], v[78:81]
	v_mfma_f32_16x16x32_bf16 v[74:77], v[164:167], v[216:219], v[74:77]
	v_mfma_f32_16x16x32_bf16 v[118:121], v[168:171], v[184:187], v[118:121]
	v_mfma_f32_16x16x32_bf16 v[114:117], v[176:179], v[184:187], v[114:117]
	v_mfma_f32_16x16x32_bf16 v[102:105], v[168:171], v[192:195], v[102:105]
	v_mfma_f32_16x16x32_bf16 v[98:101], v[176:179], v[192:195], v[98:101]
	v_mfma_f32_16x16x32_bf16 v[86:89], v[168:171], v[204:207], v[86:89]
	v_mfma_f32_16x16x32_bf16 v[82:85], v[176:179], v[204:207], v[82:85]
	v_mfma_f32_16x16x32_bf16 v[70:73], v[168:171], v[212:215], v[70:73]
	v_mfma_f32_16x16x32_bf16 v[66:69], v[176:179], v[212:215], v[66:69]
	v_mfma_f32_16x16x32_bf16 v[118:121], v[172:175], v[188:191], v[118:121]
	v_mfma_f32_16x16x32_bf16 v[114:117], v[180:183], v[188:191], v[114:117]
	v_mfma_f32_16x16x32_bf16 v[102:105], v[172:175], v[200:203], v[102:105]
	v_mfma_f32_16x16x32_bf16 v[98:101], v[180:183], v[200:203], v[98:101]
	v_mfma_f32_16x16x32_bf16 v[86:89], v[172:175], v[208:211], v[86:89]
	v_mfma_f32_16x16x32_bf16 v[82:85], v[180:183], v[208:211], v[82:85]
	v_mfma_f32_16x16x32_bf16 v[70:73], v[172:175], v[216:219], v[70:73]
	v_mfma_f32_16x16x32_bf16 v[66:69], v[180:183], v[216:219], v[66:69]
	s_barrier
	s_add_i32 s69, s62, s20
	v_lshl_add_u64 v[196:197], s[52:53], 0, v[132:133]
	s_mov_b32 m0, s69
	ds_read_b128 v[184:187], v154 offset:16384
	ds_read_b128 v[188:191], v154 offset:17408
	ds_read_b128 v[192:195], v154 offset:18432
	ds_read_b128 v[200:203], v154 offset:19456
	ds_read_b128 v[204:207], v154 offset:20480
	ds_read_b128 v[208:211], v154 offset:21504
	ds_read_b128 v[212:215], v154 offset:22528
	ds_read_b128 v[216:219], v154 offset:23552
	global_load_lds_dwordx4 v[196:197], off
	s_add_i32 m0, s69, 0x2000
	s_add_u32 s70, s52, 0x40000
	v_lshl_add_u64 v[220:221], s[52:53], 0, v[136:137]
	s_addc_u32 s71, s53, 0
	s_add_i32 s69, s63, s20
	global_load_lds_dwordx4 v[220:221], off
	v_lshl_add_u64 v[222:223], s[70:71], 0, v[132:133]
	s_mov_b32 m0, s69
	v_lshl_add_u64 v[224:225], s[54:55], 0, v[134:135]
	global_load_lds_dwordx4 v[222:223], off
	v_lshl_add_u64 v[222:223], s[70:71], 0, v[136:137]
	s_add_i32 m0, s69, 0x2000
	s_nop 0
	global_load_lds_dwordx4 v[222:223], off
	v_lshl_add_u64 v[222:223], s[54:55], 0, v[130:131]
	s_mov_b32 m0, s21
	s_nop 0
	global_load_lds_dwordx4 v[222:223], off
	s_mov_b32 m0, s56
	s_nop 0
	global_load_lds_dwordx4 v[224:225], off
	s_waitcnt vmcnt(8)
	s_waitcnt lgkmcnt(0)
	s_barrier
	s_waitcnt lgkmcnt(0)
	v_mfma_f32_16x16x32_bf16 v[62:65], v[146:149], v[184:187], v[62:65]
	v_mfma_f32_16x16x32_bf16 v[58:61], v[160:163], v[184:187], v[58:61]
	v_mfma_f32_16x16x32_bf16 v[46:49], v[146:149], v[192:195], v[46:49]
	v_mfma_f32_16x16x32_bf16 v[42:45], v[160:163], v[192:195], v[42:45]
	v_mfma_f32_16x16x32_bf16 v[30:33], v[146:149], v[204:207], v[30:33]
	v_mfma_f32_16x16x32_bf16 v[26:29], v[160:163], v[204:207], v[26:29]
	v_mfma_f32_16x16x32_bf16 v[14:17], v[146:149], v[212:215], v[14:17]
	v_mfma_f32_16x16x32_bf16 v[10:13], v[160:163], v[212:215], v[10:13]
	v_mfma_f32_16x16x32_bf16 v[62:65], v[156:159], v[188:191], v[62:65]
	v_mfma_f32_16x16x32_bf16 v[58:61], v[164:167], v[188:191], v[58:61]
	v_mfma_f32_16x16x32_bf16 v[46:49], v[156:159], v[200:203], v[46:49]
	v_mfma_f32_16x16x32_bf16 v[42:45], v[164:167], v[200:203], v[42:45]
	v_mfma_f32_16x16x32_bf16 v[30:33], v[156:159], v[208:211], v[30:33]
	v_mfma_f32_16x16x32_bf16 v[26:29], v[164:167], v[208:211], v[26:29]
	v_mfma_f32_16x16x32_bf16 v[14:17], v[156:159], v[216:219], v[14:17]
	v_mfma_f32_16x16x32_bf16 v[10:13], v[164:167], v[216:219], v[10:13]
	v_mfma_f32_16x16x32_bf16 v[54:57], v[168:171], v[184:187], v[54:57]
	v_mfma_f32_16x16x32_bf16 v[50:53], v[176:179], v[184:187], v[50:53]
	v_mfma_f32_16x16x32_bf16 v[38:41], v[168:171], v[192:195], v[38:41]
	v_mfma_f32_16x16x32_bf16 v[34:37], v[176:179], v[192:195], v[34:37]
	v_mfma_f32_16x16x32_bf16 v[22:25], v[168:171], v[204:207], v[22:25]
	v_mfma_f32_16x16x32_bf16 v[18:21], v[176:179], v[204:207], v[18:21]
	v_mfma_f32_16x16x32_bf16 v[6:9], v[168:171], v[212:215], v[6:9]
	v_mfma_f32_16x16x32_bf16 v[2:5], v[176:179], v[212:215], v[2:5]
	v_mfma_f32_16x16x32_bf16 v[54:57], v[172:175], v[188:191], v[54:57]
	v_mfma_f32_16x16x32_bf16 v[50:53], v[180:183], v[188:191], v[50:53]
	v_mfma_f32_16x16x32_bf16 v[38:41], v[172:175], v[200:203], v[38:41]
	v_mfma_f32_16x16x32_bf16 v[34:37], v[180:183], v[200:203], v[34:37]
	v_mfma_f32_16x16x32_bf16 v[22:25], v[172:175], v[208:211], v[22:25]
	v_mfma_f32_16x16x32_bf16 v[18:21], v[180:183], v[208:211], v[18:21]
	v_mfma_f32_16x16x32_bf16 v[6:9], v[172:175], v[216:219], v[6:9]
	v_mfma_f32_16x16x32_bf16 v[2:5], v[180:183], v[216:219], v[2:5]
	s_barrier
	s_add_i32 s69, 0, 0x18000
	v_add_u32_e32 v155, s69, v150
	s_add_i32 s70, 0, 0x1c000
	ds_read_b128 v[146:149], v155
	ds_read_b128 v[156:159], v155 offset:1024
	ds_read_b128 v[160:163], v155 offset:2048
	ds_read_b128 v[164:167], v155 offset:3072
	v_add_u32_e32 v155, s70, v150
	ds_read_b128 v[168:171], v155
	ds_read_b128 v[172:175], v155 offset:1024
	ds_read_b128 v[176:179], v155 offset:2048
	ds_read_b128 v[180:183], v155 offset:3072
	s_add_u32 s54, s54, 0x40000
	s_addc_u32 s55, s55, 0
	s_mov_b32 m0, s57
	v_lshl_add_u64 v[226:227], s[54:55], 0, v[130:131]
	ds_read_b128 v[184:187], v154 offset:32768
	ds_read_b128 v[188:191], v154 offset:33792
	ds_read_b128 v[192:195], v154 offset:34816
	ds_read_b128 v[200:203], v154 offset:35840
	ds_read_b128 v[204:207], v154 offset:36864
	ds_read_b128 v[208:211], v154 offset:37888
	ds_read_b128 v[212:215], v154 offset:38912
	ds_read_b128 v[216:219], v154 offset:39936
	global_load_lds_dwordx4 v[226:227], off
	v_lshl_add_u64 v[226:227], s[54:55], 0, v[134:135]
	s_mov_b32 m0, s58
	s_nop 0
	global_load_lds_dwordx4 v[226:227], off
	s_waitcnt vmcnt(8)
	s_waitcnt lgkmcnt(0)
	s_barrier
	s_waitcnt lgkmcnt(0)
	v_mfma_f32_16x16x32_bf16 v[126:129], v[146:149], v[184:187], v[126:129]
	v_mfma_f32_16x16x32_bf16 v[122:125], v[160:163], v[184:187], v[122:125]
	v_mfma_f32_16x16x32_bf16 v[110:113], v[146:149], v[192:195], v[110:113]
	v_mfma_f32_16x16x32_bf16 v[106:109], v[160:163], v[192:195], v[106:109]
	v_mfma_f32_16x16x32_bf16 v[94:97], v[146:149], v[204:207], v[94:97]
	v_mfma_f32_16x16x32_bf16 v[90:93], v[160:163], v[204:207], v[90:93]
	v_mfma_f32_16x16x32_bf16 v[78:81], v[146:149], v[212:215], v[78:81]
	v_mfma_f32_16x16x32_bf16 v[74:77], v[160:163], v[212:215], v[74:77]
	v_mfma_f32_16x16x32_bf16 v[126:129], v[156:159], v[188:191], v[126:129]
	v_mfma_f32_16x16x32_bf16 v[122:125], v[164:167], v[188:191], v[122:125]
	v_mfma_f32_16x16x32_bf16 v[110:113], v[156:159], v[200:203], v[110:113]
	v_mfma_f32_16x16x32_bf16 v[106:109], v[164:167], v[200:203], v[106:109]
	v_mfma_f32_16x16x32_bf16 v[94:97], v[156:159], v[208:211], v[94:97]
	v_mfma_f32_16x16x32_bf16 v[90:93], v[164:167], v[208:211], v[90:93]
	v_mfma_f32_16x16x32_bf16 v[78:81], v[156:159], v[216:219], v[78:81]
	v_mfma_f32_16x16x32_bf16 v[74:77], v[164:167], v[216:219], v[74:77]
	v_mfma_f32_16x16x32_bf16 v[118:121], v[168:171], v[184:187], v[118:121]
	v_mfma_f32_16x16x32_bf16 v[114:117], v[176:179], v[184:187], v[114:117]
	v_mfma_f32_16x16x32_bf16 v[102:105], v[168:171], v[192:195], v[102:105]
	v_mfma_f32_16x16x32_bf16 v[98:101], v[176:179], v[192:195], v[98:101]
	v_mfma_f32_16x16x32_bf16 v[86:89], v[168:171], v[204:207], v[86:89]
	v_mfma_f32_16x16x32_bf16 v[82:85], v[176:179], v[204:207], v[82:85]
	v_mfma_f32_16x16x32_bf16 v[70:73], v[168:171], v[212:215], v[70:73]
	v_mfma_f32_16x16x32_bf16 v[66:69], v[176:179], v[212:215], v[66:69]
	v_mfma_f32_16x16x32_bf16 v[118:121], v[172:175], v[188:191], v[118:121]
	v_mfma_f32_16x16x32_bf16 v[114:117], v[180:183], v[188:191], v[114:117]
	v_mfma_f32_16x16x32_bf16 v[102:105], v[172:175], v[200:203], v[102:105]
	v_mfma_f32_16x16x32_bf16 v[98:101], v[180:183], v[200:203], v[98:101]
	v_mfma_f32_16x16x32_bf16 v[86:89], v[172:175], v[208:211], v[86:89]
	v_mfma_f32_16x16x32_bf16 v[82:85], v[180:183], v[208:211], v[82:85]
	v_mfma_f32_16x16x32_bf16 v[70:73], v[172:175], v[216:219], v[70:73]
	v_mfma_f32_16x16x32_bf16 v[66:69], v[180:183], v[216:219], v[66:69]
	s_barrier
; #define PG8_BAR __builtin_amdgcn_s_barrier()
; template <class Epi, bool HOOK = false>
; DI void gemm_phase(LAS unsigned char* lds, const Gemm g, const StaticOrder& S, const Epi& E) {
;     ...
;         if constexpr (HOOK) {
;             for (int t = 0; t < (nt >> 1); t += 2) PG8_KBODY();
;             E.hook(acc, cur, wr, wc, fr, fq);
;             for (int t = (nt >> 1); t < nt; t += 2) PG8_KBODY();
;         } else {
;             for (int t = 0; t < nt; t += 2) PG8_KBODY();
;         }
;     ...
;         if (wr == 0) PG8_BAR;
	s_add_i32 s54, s69, s20
	v_lshl_add_u64 v[196:197], v[196:197], 0, s[28:29]
	s_mov_b32 m0, s54
	ds_read_b128 v[184:187], v154 offset:49152
	ds_read_b128 v[188:191], v154 offset:50176
	ds_read_b128 v[192:195], v154 offset:51200
	ds_read_b128 v[200:203], v154 offset:52224
	ds_read_b128 v[204:207], v154 offset:53248
	ds_read_b128 v[208:211], v154 offset:54272
	ds_read_b128 v[212:215], v154 offset:55296
	ds_read_b128 v[216:219], v154 offset:56320
	global_load_lds_dwordx4 v[196:197], off
	s_add_i32 m0, s54, 0x2000
	s_add_u32 s52, s52, 0x40080
	v_lshl_add_u64 v[196:197], v[220:221], 0, s[28:29]
	s_addc_u32 s53, s53, 0
	s_add_i32 s54, s70, s20
	global_load_lds_dwordx4 v[196:197], off
	v_lshl_add_u64 v[196:197], s[52:53], 0, v[132:133]
	s_mov_b32 m0, s54
	s_nop 0
	global_load_lds_dwordx4 v[196:197], off
	v_lshl_add_u64 v[196:197], s[52:53], 0, v[136:137]
	s_add_i32 m0, s54, 0x2000
	s_nop 0
	global_load_lds_dwordx4 v[196:197], off
	v_lshl_add_u64 v[196:197], v[222:223], 0, s[28:29]
	s_mov_b32 m0, s60
	s_nop 0
	global_load_lds_dwordx4 v[196:197], off
	v_lshl_add_u64 v[196:197], v[224:225], 0, s[28:29]
	s_mov_b32 m0, s61
	s_nop 0
	global_load_lds_dwordx4 v[196:197], off
	s_waitcnt vmcnt(8)
	s_waitcnt lgkmcnt(0)
	s_barrier
	s_waitcnt lgkmcnt(0)
	v_mfma_f32_16x16x32_bf16 v[62:65], v[146:149], v[184:187], v[62:65]
	v_mfma_f32_16x16x32_bf16 v[58:61], v[160:163], v[184:187], v[58:61]
	v_mfma_f32_16x16x32_bf16 v[46:49], v[146:149], v[192:195], v[46:49]
	v_mfma_f32_16x16x32_bf16 v[42:45], v[160:163], v[192:195], v[42:45]
	v_mfma_f32_16x16x32_bf16 v[30:33], v[146:149], v[204:207], v[30:33]
	v_mfma_f32_16x16x32_bf16 v[26:29], v[160:163], v[204:207], v[26:29]
	v_mfma_f32_16x16x32_bf16 v[14:17], v[146:149], v[212:215], v[14:17]
	v_mfma_f32_16x16x32_bf16 v[10:13], v[160:163], v[212:215], v[10:13]
	v_mfma_f32_16x16x32_bf16 v[62:65], v[156:159], v[188:191], v[62:65]
	v_mfma_f32_16x16x32_bf16 v[58:61], v[164:167], v[188:191], v[58:61]
	v_mfma_f32_16x16x32_bf16 v[46:49], v[156:159], v[200:203], v[46:49]
	v_mfma_f32_16x16x32_bf16 v[42:45], v[164:167], v[200:203], v[42:45]
	v_mfma_f32_16x16x32_bf16 v[30:33], v[156:159], v[208:211], v[30:33]
	v_mfma_f32_16x16x32_bf16 v[26:29], v[164:167], v[208:211], v[26:29]
	v_mfma_f32_16x16x32_bf16 v[14:17], v[156:159], v[216:219], v[14:17]
	v_mfma_f32_16x16x32_bf16 v[10:13], v[164:167], v[216:219], v[10:13]
	v_mfma_f32_16x16x32_bf16 v[54:57], v[168:171], v[184:187], v[54:57]
	v_mfma_f32_16x16x32_bf16 v[50:53], v[176:179], v[184:187], v[50:53]
	v_mfma_f32_16x16x32_bf16 v[38:41], v[168:171], v[192:195], v[38:41]
	v_mfma_f32_16x16x32_bf16 v[34:37], v[176:179], v[192:195], v[34:37]
	v_mfma_f32_16x16x32_bf16 v[22:25], v[168:171], v[204:207], v[22:25]
	v_mfma_f32_16x16x32_bf16 v[18:21], v[176:179], v[204:207], v[18:21]
	v_mfma_f32_16x16x32_bf16 v[6:9], v[168:171], v[212:215], v[6:9]
	v_mfma_f32_16x16x32_bf16 v[2:5], v[176:179], v[212:215], v[2:5]
	v_mfma_f32_16x16x32_bf16 v[54:57], v[172:175], v[188:191], v[54:57]
	v_mfma_f32_16x16x32_bf16 v[50:53], v[180:183], v[188:191], v[50:53]
	v_mfma_f32_16x16x32_bf16 v[38:41], v[172:175], v[200:203], v[38:41]
	v_mfma_f32_16x16x32_bf16 v[34:37], v[180:183], v[200:203], v[34:37]
	v_mfma_f32_16x16x32_bf16 v[22:25], v[172:175], v[208:211], v[22:25]
	v_mfma_f32_16x16x32_bf16 v[18:21], v[180:183], v[208:211], v[18:21]
	v_mfma_f32_16x16x32_bf16 v[6:9], v[172:175], v[216:219], v[6:9]
	v_mfma_f32_16x16x32_bf16 v[2:5], v[180:183], v[216:219], v[2:5]
	s_barrier
	s_add_i32 s68, s68, 2
	s_add_u32 s50, s50, 0x100
	s_addc_u32 s51, s51, 0
	s_add_u32 s66, s66, 0x100
	s_addc_u32 s67, s67, 0
	s_cmp_gt_u32 s68, 13
	s_cbranch_scc0 .LBB0_950
	s_and_b64 vcc, exec, s[38:39]
	s_cbranch_vccz .LBB0_953
	s_barrier

.LBB0_1034:
	ds_read_b128 v[146:149], v156
	ds_read_b128 v[150:153], v156 offset:1024
	ds_read_b128 v[162:165], v156 offset:2048
	ds_read_b128 v[166:169], v156 offset:3072
	ds_read_b128 v[170:173], v157
	ds_read_b128 v[174:177], v157 offset:1024
	ds_read_b128 v[178:181], v157 offset:2048
	ds_read_b128 v[182:185], v157 offset:3072
	s_add_u32 s42, s40, 0xfffc0080
	s_addc_u32 s43, s41, -1
	s_cmp_eq_u32 s63, 12
	s_cselect_b32 s45, s29, s43
	s_cselect_b32 s44, s59, s42
	s_cselect_b32 s43, s27, s62
	s_cselect_b32 s42, s60, s61
	v_lshl_add_u64 v[220:221], s[40:41], 0, v[138:139]
	s_add_i32 m0, s48, 0xc000
	ds_read_b128 v[186:189], v158
	ds_read_b128 v[190:193], v158 offset:1024
	ds_read_b128 v[194:197], v158 offset:2048
	ds_read_b128 v[200:203], v158 offset:3072
	ds_read_b128 v[204:207], v158 offset:4096
	ds_read_b128 v[208:211], v158 offset:5120
	ds_read_b128 v[212:215], v158 offset:6144
	ds_read_b128 v[216:219], v158 offset:7168
	global_load_lds_dwordx4 v[220:221], off
	v_lshl_add_u64 v[220:221], s[40:41], 0, v[140:141]
	s_add_i32 m0, s48, 0xe000
	s_nop 0
	global_load_lds_dwordx4 v[220:221], off
	s_waitcnt vmcnt(8)
	s_waitcnt lgkmcnt(0)
	s_barrier
	s_waitcnt lgkmcnt(0)
	v_mfma_f32_16x16x32_bf16 v[126:129], v[146:149], v[186:189], v[126:129]
	v_mfma_f32_16x16x32_bf16 v[122:125], v[162:165], v[186:189], v[122:125]
	v_mfma_f32_16x16x32_bf16 v[110:113], v[146:149], v[194:197], v[110:113]
	v_mfma_f32_16x16x32_bf16 v[106:109], v[162:165], v[194:197], v[106:109]
	v_mfma_f32_16x16x32_bf16 v[94:97], v[146:149], v[204:207], v[94:97]
	v_mfma_f32_16x16x32_bf16 v[90:93], v[162:165], v[204:207], v[90:93]
	v_mfma_f32_16x16x32_bf16 v[78:81], v[146:149], v[212:215], v[78:81]
	v_mfma_f32_16x16x32_bf16 v[74:77], v[162:165], v[212:215], v[74:77]
	v_mfma_f32_16x16x32_bf16 v[126:129], v[150:153], v[190:193], v[126:129]
	v_mfma_f32_16x16x32_bf16 v[122:125], v[166:169], v[190:193], v[122:125]
	v_mfma_f32_16x16x32_bf16 v[110:113], v[150:153], v[200:203], v[110:113]
	v_mfma_f32_16x16x32_bf16 v[106:109], v[166:169], v[200:203], v[106:109]
	v_mfma_f32_16x16x32_bf16 v[94:97], v[150:153], v[208:211], v[94:97]
	v_mfma_f32_16x16x32_bf16 v[90:93], v[166:169], v[208:211], v[90:93]
	v_mfma_f32_16x16x32_bf16 v[78:81], v[150:153], v[216:219], v[78:81]
	v_mfma_f32_16x16x32_bf16 v[74:77], v[166:169], v[216:219], v[74:77]
	v_mfma_f32_16x16x32_bf16 v[118:121], v[170:173], v[186:189], v[118:121]
	v_mfma_f32_16x16x32_bf16 v[114:117], v[178:181], v[186:189], v[114:117]
	v_mfma_f32_16x16x32_bf16 v[102:105], v[170:173], v[194:197], v[102:105]
	v_mfma_f32_16x16x32_bf16 v[98:101], v[178:181], v[194:197], v[98:101]
	v_mfma_f32_16x16x32_bf16 v[86:89], v[170:173], v[204:207], v[86:89]
	v_mfma_f32_16x16x32_bf16 v[82:85], v[178:181], v[204:207], v[82:85]
	v_mfma_f32_16x16x32_bf16 v[70:73], v[170:173], v[212:215], v[70:73]
	v_mfma_f32_16x16x32_bf16 v[66:69], v[178:181], v[212:215], v[66:69]
	v_mfma_f32_16x16x32_bf16 v[118:121], v[174:177], v[190:193], v[118:121]
	v_mfma_f32_16x16x32_bf16 v[114:117], v[182:185], v[190:193], v[114:117]
	v_mfma_f32_16x16x32_bf16 v[102:105], v[174:177], v[200:203], v[102:105]
	v_mfma_f32_16x16x32_bf16 v[98:101], v[182:185], v[200:203], v[98:101]
	v_mfma_f32_16x16x32_bf16 v[86:89], v[174:177], v[208:211], v[86:89]
	v_mfma_f32_16x16x32_bf16 v[82:85], v[182:185], v[208:211], v[82:85]
	v_mfma_f32_16x16x32_bf16 v[70:73], v[174:177], v[216:219], v[70:73]
	v_mfma_f32_16x16x32_bf16 v[66:69], v[182:185], v[216:219], v[66:69]
	s_barrier
	s_add_i32 s64, s55, s46
	v_lshl_add_u64 v[220:221], s[42:43], 0, v[134:135]
	s_mov_b32 m0, s64
	ds_read_b128 v[186:189], v158 offset:16384
	ds_read_b128 v[190:193], v158 offset:17408
	ds_read_b128 v[194:197], v158 offset:18432
	ds_read_b128 v[200:203], v158 offset:19456
	ds_read_b128 v[204:207], v158 offset:20480
	ds_read_b128 v[208:211], v158 offset:21504
	ds_read_b128 v[212:215], v158 offset:22528
	ds_read_b128 v[216:219], v158 offset:23552
	global_load_lds_dwordx4 v[220:221], off
	s_add_i32 m0, s64, 0x2000
	s_add_u32 s64, s42, 0x40000
	v_lshl_add_u64 v[222:223], s[42:43], 0, v[130:131]
	s_addc_u32 s65, s43, 0
	s_add_i32 s66, s56, s46
	global_load_lds_dwordx4 v[222:223], off
	v_lshl_add_u64 v[224:225], s[64:65], 0, v[134:135]
	s_mov_b32 m0, s66
	v_lshl_add_u64 v[226:227], s[44:45], 0, v[132:133]
	global_load_lds_dwordx4 v[224:225], off
	v_lshl_add_u64 v[224:225], s[64:65], 0, v[130:131]
	s_add_i32 m0, s66, 0x2000
	s_nop 0
	global_load_lds_dwordx4 v[224:225], off
	v_lshl_add_u64 v[224:225], s[44:45], 0, v[136:137]
	s_mov_b32 m0, s48
	s_nop 0
	global_load_lds_dwordx4 v[224:225], off
	s_mov_b32 m0, s49
	s_nop 0
	global_load_lds_dwordx4 v[226:227], off
	s_waitcnt vmcnt(8)
	s_waitcnt lgkmcnt(0)
	s_barrier
	s_waitcnt lgkmcnt(0)
	v_mfma_f32_16x16x32_bf16 v[62:65], v[146:149], v[186:189], v[62:65]
	v_mfma_f32_16x16x32_bf16 v[58:61], v[162:165], v[186:189], v[58:61]
	v_mfma_f32_16x16x32_bf16 v[46:49], v[146:149], v[194:197], v[46:49]
	v_mfma_f32_16x16x32_bf16 v[42:45], v[162:165], v[194:197], v[42:45]
	v_mfma_f32_16x16x32_bf16 v[30:33], v[146:149], v[204:207], v[30:33]
	v_mfma_f32_16x16x32_bf16 v[26:29], v[162:165], v[204:207], v[26:29]
	v_mfma_f32_16x16x32_bf16 v[14:17], v[146:149], v[212:215], v[14:17]
	v_mfma_f32_16x16x32_bf16 v[10:13], v[162:165], v[212:215], v[10:13]
	v_mfma_f32_16x16x32_bf16 v[62:65], v[150:153], v[190:193], v[62:65]
	v_mfma_f32_16x16x32_bf16 v[58:61], v[166:169], v[190:193], v[58:61]
	v_mfma_f32_16x16x32_bf16 v[46:49], v[150:153], v[200:203], v[46:49]
	v_mfma_f32_16x16x32_bf16 v[42:45], v[166:169], v[200:203], v[42:45]
	v_mfma_f32_16x16x32_bf16 v[30:33], v[150:153], v[208:211], v[30:33]
	v_mfma_f32_16x16x32_bf16 v[26:29], v[166:169], v[208:211], v[26:29]
	v_mfma_f32_16x16x32_bf16 v[14:17], v[150:153], v[216:219], v[14:17]
	v_mfma_f32_16x16x32_bf16 v[10:13], v[166:169], v[216:219], v[10:13]
	v_mfma_f32_16x16x32_bf16 v[54:57], v[170:173], v[186:189], v[54:57]
	v_mfma_f32_16x16x32_bf16 v[50:53], v[178:181], v[186:189], v[50:53]
	v_mfma_f32_16x16x32_bf16 v[38:41], v[170:173], v[194:197], v[38:41]
	v_mfma_f32_16x16x32_bf16 v[34:37], v[178:181], v[194:197], v[34:37]
	v_mfma_f32_16x16x32_bf16 v[22:25], v[170:173], v[204:207], v[22:25]
	v_mfma_f32_16x16x32_bf16 v[18:21], v[178:181], v[204:207], v[18:21]
	v_mfma_f32_16x16x32_bf16 v[6:9], v[170:173], v[212:215], v[6:9]
	v_mfma_f32_16x16x32_bf16 v[2:5], v[178:181], v[212:215], v[2:5]
	v_mfma_f32_16x16x32_bf16 v[54:57], v[174:177], v[190:193], v[54:57]
	v_mfma_f32_16x16x32_bf16 v[50:53], v[182:185], v[190:193], v[50:53]
	v_mfma_f32_16x16x32_bf16 v[38:41], v[174:177], v[200:203], v[38:41]
	v_mfma_f32_16x16x32_bf16 v[34:37], v[182:185], v[200:203], v[34:37]
	v_mfma_f32_16x16x32_bf16 v[22:25], v[174:177], v[208:211], v[22:25]
	v_mfma_f32_16x16x32_bf16 v[18:21], v[182:185], v[208:211], v[18:21]
	v_mfma_f32_16x16x32_bf16 v[6:9], v[174:177], v[216:219], v[6:9]
	v_mfma_f32_16x16x32_bf16 v[2:5], v[182:185], v[216:219], v[2:5]
	s_barrier
	s_add_i32 s64, 0, 0x18000
	v_add_u32_e32 v161, s64, v154
	s_add_i32 s65, 0, 0x1c000
	ds_read_b128 v[146:149], v161
	ds_read_b128 v[150:153], v161 offset:1024
	ds_read_b128 v[162:165], v161 offset:2048
	ds_read_b128 v[166:169], v161 offset:3072
	v_add_u32_e32 v161, s65, v154
	ds_read_b128 v[170:173], v161
	ds_read_b128 v[174:177], v161 offset:1024
	ds_read_b128 v[178:181], v161 offset:2048
	ds_read_b128 v[182:185], v161 offset:3072
	s_add_u32 s44, s44, 0x40000
	s_addc_u32 s45, s45, 0
	s_mov_b32 m0, s50
	v_lshl_add_u64 v[228:229], s[44:45], 0, v[136:137]
	ds_read_b128 v[186:189], v158 offset:32768
	ds_read_b128 v[190:193], v158 offset:33792
	ds_read_b128 v[194:197], v158 offset:34816
	ds_read_b128 v[200:203], v158 offset:35840
	ds_read_b128 v[204:207], v158 offset:36864
	ds_read_b128 v[208:211], v158 offset:37888
	ds_read_b128 v[212:215], v158 offset:38912
	ds_read_b128 v[216:219], v158 offset:39936
	global_load_lds_dwordx4 v[228:229], off
	v_lshl_add_u64 v[228:229], s[44:45], 0, v[132:133]
	s_mov_b32 m0, s51
	s_nop 0
	global_load_lds_dwordx4 v[228:229], off
	s_waitcnt vmcnt(8)
	s_waitcnt lgkmcnt(0)
	s_barrier
	s_waitcnt lgkmcnt(0)
	v_mfma_f32_16x16x32_bf16 v[126:129], v[146:149], v[186:189], v[126:129]
	v_mfma_f32_16x16x32_bf16 v[122:125], v[162:165], v[186:189], v[122:125]
	v_mfma_f32_16x16x32_bf16 v[110:113], v[146:149], v[194:197], v[110:113]
	v_mfma_f32_16x16x32_bf16 v[106:109], v[162:165], v[194:197], v[106:109]
	v_mfma_f32_16x16x32_bf16 v[94:97], v[146:149], v[204:207], v[94:97]
	v_mfma_f32_16x16x32_bf16 v[90:93], v[162:165], v[204:207], v[90:93]
	v_mfma_f32_16x16x32_bf16 v[78:81], v[146:149], v[212:215], v[78:81]
	v_mfma_f32_16x16x32_bf16 v[74:77], v[162:165], v[212:215], v[74:77]
	v_mfma_f32_16x16x32_bf16 v[126:129], v[150:153], v[190:193], v[126:129]
	v_mfma_f32_16x16x32_bf16 v[122:125], v[166:169], v[190:193], v[122:125]
	v_mfma_f32_16x16x32_bf16 v[110:113], v[150:153], v[200:203], v[110:113]
	v_mfma_f32_16x16x32_bf16 v[106:109], v[166:169], v[200:203], v[106:109]
	v_mfma_f32_16x16x32_bf16 v[94:97], v[150:153], v[208:211], v[94:97]
	v_mfma_f32_16x16x32_bf16 v[90:93], v[166:169], v[208:211], v[90:93]
	v_mfma_f32_16x16x32_bf16 v[78:81], v[150:153], v[216:219], v[78:81]
	v_mfma_f32_16x16x32_bf16 v[74:77], v[166:169], v[216:219], v[74:77]
	v_mfma_f32_16x16x32_bf16 v[118:121], v[170:173], v[186:189], v[118:121]
	v_mfma_f32_16x16x32_bf16 v[114:117], v[178:181], v[186:189], v[114:117]
	v_mfma_f32_16x16x32_bf16 v[102:105], v[170:173], v[194:197], v[102:105]
	v_mfma_f32_16x16x32_bf16 v[98:101], v[178:181], v[194:197], v[98:101]
	v_mfma_f32_16x16x32_bf16 v[86:89], v[170:173], v[204:207], v[86:89]
	v_mfma_f32_16x16x32_bf16 v[82:85], v[178:181], v[204:207], v[82:85]
	v_mfma_f32_16x16x32_bf16 v[70:73], v[170:173], v[212:215], v[70:73]
	v_mfma_f32_16x16x32_bf16 v[66:69], v[178:181], v[212:215], v[66:69]
	v_mfma_f32_16x16x32_bf16 v[118:121], v[174:177], v[190:193], v[118:121]
	v_mfma_f32_16x16x32_bf16 v[114:117], v[182:185], v[190:193], v[114:117]
	v_mfma_f32_16x16x32_bf16 v[102:105], v[174:177], v[200:203], v[102:105]
	v_mfma_f32_16x16x32_bf16 v[98:101], v[182:185], v[200:203], v[98:101]
	v_mfma_f32_16x16x32_bf16 v[86:89], v[174:177], v[208:211], v[86:89]
	v_mfma_f32_16x16x32_bf16 v[82:85], v[182:185], v[208:211], v[82:85]
	v_mfma_f32_16x16x32_bf16 v[70:73], v[174:177], v[216:219], v[70:73]
	v_mfma_f32_16x16x32_bf16 v[66:69], v[182:185], v[216:219], v[66:69]
	s_barrier
; #define PG8_BAR __builtin_amdgcn_s_barrier()
; template <class Epi, bool HOOK = false>
; DI void gemm_phase(LAS unsigned char* lds, const Gemm g, const StaticOrder& S, const Epi& E) {
;     ...
;         if constexpr (HOOK) {
;             for (int t = 0; t < (nt >> 1); t += 2) PG8_KBODY();
;             E.hook(acc, cur, wr, wc, fr, fq);
;             for (int t = (nt >> 1); t < nt; t += 2) PG8_KBODY();
;         } else {
;             for (int t = 0; t < nt; t += 2) PG8_KBODY();
;         }
;     ...
;         if (wr == 0) PG8_BAR;
;     DI void operator()(const Acc& acc, const Unit& u, int wr, int wc, int fr, int fq) const {
;         const int row0 = u.pm * 256 + wr * 64 + fr;
; #pragma unroll
;         for (int ai = 0; ai < 2; ++ai)
; #pragma unroll
;             for (int m = 0; m < 4; ++m) {
;                 const int r = row0 + ai * 128 + m * 16;
;                 const f32x4* sp = (const f32x4*)(SS + (size_t)r * 16);
;                 const f32x4 s0 = sp[0], s1 = sp[1], s2 = sp[2], s3 = sp[3];
;                 const float tot = ((s0[0] + s0[1]) + (s0[2] + s0[3])) + ((s1[0] + s1[1]) + (s1[2] + s1[3])) + ((s2[0] + s2[1]) + (s2[2] + s2[3])) + ((s3[0] + s3[1]) + (s3[2] + s3[3]));
;                 const float rr = 1.0f / sqrtf(tot * (1.0f / DM) + EPS);
	s_add_i32 s44, s64, s46
	v_lshl_add_u64 v[220:221], v[220:221], 0, s[16:17]
	s_mov_b32 m0, s44
	ds_read_b128 v[186:189], v158 offset:49152
	ds_read_b128 v[190:193], v158 offset:50176
	ds_read_b128 v[194:197], v158 offset:51200
	ds_read_b128 v[200:203], v158 offset:52224
	ds_read_b128 v[204:207], v158 offset:53248
	ds_read_b128 v[208:211], v158 offset:54272
	ds_read_b128 v[212:215], v158 offset:55296
	ds_read_b128 v[216:219], v158 offset:56320
	global_load_lds_dwordx4 v[220:221], off
	s_add_i32 m0, s44, 0x2000
	s_add_u32 s42, s42, 0x40080
	v_lshl_add_u64 v[220:221], v[222:223], 0, s[16:17]
	s_addc_u32 s43, s43, 0
	s_add_i32 s44, s65, s46
	global_load_lds_dwordx4 v[220:221], off
	v_lshl_add_u64 v[220:221], s[42:43], 0, v[134:135]
	s_mov_b32 m0, s44
	s_nop 0
	global_load_lds_dwordx4 v[220:221], off
	v_lshl_add_u64 v[220:221], s[42:43], 0, v[130:131]
	s_add_i32 m0, s44, 0x2000
	s_nop 0
	global_load_lds_dwordx4 v[220:221], off
	v_lshl_add_u64 v[220:221], v[224:225], 0, s[16:17]
	s_mov_b32 m0, s53
	s_nop 0
	global_load_lds_dwordx4 v[220:221], off
	v_lshl_add_u64 v[220:221], v[226:227], 0, s[16:17]
	s_mov_b32 m0, s54
	s_nop 0
	global_load_lds_dwordx4 v[220:221], off
	s_waitcnt vmcnt(8)
	s_waitcnt lgkmcnt(0)
	s_barrier
	s_waitcnt lgkmcnt(0)
	v_mfma_f32_16x16x32_bf16 v[62:65], v[146:149], v[186:189], v[62:65]
	v_mfma_f32_16x16x32_bf16 v[58:61], v[162:165], v[186:189], v[58:61]
	v_mfma_f32_16x16x32_bf16 v[46:49], v[146:149], v[194:197], v[46:49]
	v_mfma_f32_16x16x32_bf16 v[42:45], v[162:165], v[194:197], v[42:45]
	v_mfma_f32_16x16x32_bf16 v[30:33], v[146:149], v[204:207], v[30:33]
	v_mfma_f32_16x16x32_bf16 v[26:29], v[162:165], v[204:207], v[26:29]
	v_mfma_f32_16x16x32_bf16 v[14:17], v[146:149], v[212:215], v[14:17]
	v_mfma_f32_16x16x32_bf16 v[10:13], v[162:165], v[212:215], v[10:13]
	v_mfma_f32_16x16x32_bf16 v[62:65], v[150:153], v[190:193], v[62:65]
	v_mfma_f32_16x16x32_bf16 v[58:61], v[166:169], v[190:193], v[58:61]
	v_mfma_f32_16x16x32_bf16 v[46:49], v[150:153], v[200:203], v[46:49]
	v_mfma_f32_16x16x32_bf16 v[42:45], v[166:169], v[200:203], v[42:45]
	v_mfma_f32_16x16x32_bf16 v[30:33], v[150:153], v[208:211], v[30:33]
	v_mfma_f32_16x16x32_bf16 v[26:29], v[166:169], v[208:211], v[26:29]
	v_mfma_f32_16x16x32_bf16 v[14:17], v[150:153], v[216:219], v[14:17]
	v_mfma_f32_16x16x32_bf16 v[10:13], v[166:169], v[216:219], v[10:13]
	v_mfma_f32_16x16x32_bf16 v[54:57], v[170:173], v[186:189], v[54:57]
	v_mfma_f32_16x16x32_bf16 v[50:53], v[178:181], v[186:189], v[50:53]
	v_mfma_f32_16x16x32_bf16 v[38:41], v[170:173], v[194:197], v[38:41]
	v_mfma_f32_16x16x32_bf16 v[34:37], v[178:181], v[194:197], v[34:37]
	v_mfma_f32_16x16x32_bf16 v[22:25], v[170:173], v[204:207], v[22:25]
	v_mfma_f32_16x16x32_bf16 v[18:21], v[178:181], v[204:207], v[18:21]
	v_mfma_f32_16x16x32_bf16 v[6:9], v[170:173], v[212:215], v[6:9]
	v_mfma_f32_16x16x32_bf16 v[2:5], v[178:181], v[212:215], v[2:5]
	v_mfma_f32_16x16x32_bf16 v[54:57], v[174:177], v[190:193], v[54:57]
	v_mfma_f32_16x16x32_bf16 v[50:53], v[182:185], v[190:193], v[50:53]
	v_mfma_f32_16x16x32_bf16 v[38:41], v[174:177], v[200:203], v[38:41]
	v_mfma_f32_16x16x32_bf16 v[34:37], v[182:185], v[200:203], v[34:37]
	v_mfma_f32_16x16x32_bf16 v[22:25], v[174:177], v[208:211], v[22:25]
	v_mfma_f32_16x16x32_bf16 v[18:21], v[182:185], v[208:211], v[18:21]
	v_mfma_f32_16x16x32_bf16 v[6:9], v[174:177], v[216:219], v[6:9]
	v_mfma_f32_16x16x32_bf16 v[2:5], v[182:185], v[216:219], v[2:5]
	s_barrier
	s_add_i32 s63, s63, 2
	s_add_u32 s40, s40, 0x100
	s_addc_u32 s41, s41, 0
	s_add_u32 s61, s61, 0x100
	s_addc_u32 s62, s62, 0
	s_cmp_gt_u32 s63, 13
	s_cbranch_scc0 .LBB0_1034
	v_lshl_add_u32 v150, s6, 8, v1
	v_and_b32_e32 v151, 12, v155
	v_lshlrev_b32_e32 v152, 6, v150
	v_lshl_add_u32 v152, v151, 8, v152
	v_add_u32_e32 v153, 0x2000, v152
	global_load_dwordx4 v[162:165], v152, s[14:15]
	global_load_dwordx4 v[166:169], v152, s[14:15] offset:16
	global_load_dwordx4 v[170:173], v152, s[14:15] offset:32
	global_load_dwordx4 v[174:177], v152, s[14:15] offset:48
	global_load_dwordx4 v[178:181], v153, s[14:15]
	global_load_dwordx4 v[182:185], v153, s[14:15] offset:16
	global_load_dwordx4 v[186:189], v153, s[14:15] offset:32
	global_load_dwordx4 v[190:193], v153, s[14:15] offset:48
	v_lshl_or_b32 v148, s7, 7, v155
	v_lshlrev_b32_e32 v148, 1, v148
	v_mad_u32_u24 v161, v150, s58, v148
	v_mov_b32_e32 v196, 0xbfb8aa3b
	s_and_b64 vcc, exec, s[20:21]
	s_cbranch_vccz .LBB0_1037
	s_barrier

.LBB0_1114:
	ds_read_b128 v[144:147], v192
	ds_read_b128 v[148:151], v192 offset:1024
	ds_read_b128 v[152:155], v192 offset:2048
	ds_read_b128 v[156:159], v192 offset:3072
	ds_read_b128 v[160:163], v193
	ds_read_b128 v[164:167], v193 offset:1024
	ds_read_b128 v[168:171], v193 offset:2048
	ds_read_b128 v[208:211], v193 offset:3072
	s_add_u32 s8, s40, 0x100
	s_addc_u32 s9, s41, 0
	s_cmp_eq_u32 s63, 40
	s_cselect_b32 s45, s35, s9
	s_cselect_b32 s44, s34, s8
	s_cselect_b32 s43, s37, s62
	s_cselect_b32 s42, s36, s39
	v_lshl_add_u64 v[244:245], s[40:41], 0, v[136:137]
	s_add_i32 m0, s47, 0xc000
	ds_read_b128 v[212:215], v194
	ds_read_b128 v[216:219], v194 offset:1024
	ds_read_b128 v[220:223], v194 offset:2048
	ds_read_b128 v[224:227], v194 offset:3072
	ds_read_b128 v[228:231], v194 offset:4096
	ds_read_b128 v[232:235], v194 offset:5120
	ds_read_b128 v[236:239], v194 offset:6144
	ds_read_b128 v[240:243], v194 offset:7168
	global_load_lds_dwordx4 v[244:245], off
	v_lshl_add_u64 v[244:245], s[40:41], 0, v[138:139]
	s_add_i32 m0, s47, 0xe000
	s_nop 0
	global_load_lds_dwordx4 v[244:245], off
	s_waitcnt vmcnt(8)
	s_waitcnt lgkmcnt(0)
	s_barrier
	s_waitcnt lgkmcnt(0)
	v_mfma_f32_16x16x32_bf16 v[124:127], v[144:147], v[212:215], v[124:127]
	v_mfma_f32_16x16x32_bf16 v[120:123], v[152:155], v[212:215], v[120:123]
	v_mfma_f32_16x16x32_bf16 v[108:111], v[144:147], v[220:223], v[108:111]
	v_mfma_f32_16x16x32_bf16 v[104:107], v[152:155], v[220:223], v[104:107]
	v_mfma_f32_16x16x32_bf16 v[92:95], v[144:147], v[228:231], v[92:95]
	v_mfma_f32_16x16x32_bf16 v[88:91], v[152:155], v[228:231], v[88:91]
	v_mfma_f32_16x16x32_bf16 v[76:79], v[144:147], v[236:239], v[76:79]
	v_mfma_f32_16x16x32_bf16 v[72:75], v[152:155], v[236:239], v[72:75]
	v_mfma_f32_16x16x32_bf16 v[124:127], v[148:151], v[216:219], v[124:127]
	v_mfma_f32_16x16x32_bf16 v[120:123], v[156:159], v[216:219], v[120:123]
	v_mfma_f32_16x16x32_bf16 v[108:111], v[148:151], v[224:227], v[108:111]
	v_mfma_f32_16x16x32_bf16 v[104:107], v[156:159], v[224:227], v[104:107]
	v_mfma_f32_16x16x32_bf16 v[92:95], v[148:151], v[232:235], v[92:95]
	v_mfma_f32_16x16x32_bf16 v[88:91], v[156:159], v[232:235], v[88:91]
	v_mfma_f32_16x16x32_bf16 v[76:79], v[148:151], v[240:243], v[76:79]
	v_mfma_f32_16x16x32_bf16 v[72:75], v[156:159], v[240:243], v[72:75]
	v_mfma_f32_16x16x32_bf16 v[116:119], v[160:163], v[212:215], v[116:119]
	v_mfma_f32_16x16x32_bf16 v[112:115], v[168:171], v[212:215], v[112:115]
	v_mfma_f32_16x16x32_bf16 v[100:103], v[160:163], v[220:223], v[100:103]
	v_mfma_f32_16x16x32_bf16 v[96:99], v[168:171], v[220:223], v[96:99]
	v_mfma_f32_16x16x32_bf16 v[84:87], v[160:163], v[228:231], v[84:87]
	v_mfma_f32_16x16x32_bf16 v[80:83], v[168:171], v[228:231], v[80:83]
	v_mfma_f32_16x16x32_bf16 v[68:71], v[160:163], v[236:239], v[68:71]
	v_mfma_f32_16x16x32_bf16 v[64:67], v[168:171], v[236:239], v[64:67]
	v_mfma_f32_16x16x32_bf16 v[116:119], v[164:167], v[216:219], v[116:119]
	v_mfma_f32_16x16x32_bf16 v[112:115], v[208:211], v[216:219], v[112:115]
	v_mfma_f32_16x16x32_bf16 v[100:103], v[164:167], v[224:227], v[100:103]
	v_mfma_f32_16x16x32_bf16 v[96:99], v[208:211], v[224:227], v[96:99]
	v_mfma_f32_16x16x32_bf16 v[84:87], v[164:167], v[232:235], v[84:87]
	v_mfma_f32_16x16x32_bf16 v[80:83], v[208:211], v[232:235], v[80:83]
	v_mfma_f32_16x16x32_bf16 v[68:71], v[164:167], v[240:243], v[68:71]
	v_mfma_f32_16x16x32_bf16 v[64:67], v[208:211], v[240:243], v[64:67]
	s_barrier
	s_add_i32 s40, s56, s46
	v_lshl_add_u64 v[244:245], s[42:43], 0, v[130:131]
	s_mov_b32 m0, s40
	ds_read_b128 v[212:215], v194 offset:16384
	ds_read_b128 v[216:219], v194 offset:17408
	ds_read_b128 v[220:223], v194 offset:18432
	ds_read_b128 v[224:227], v194 offset:19456
	ds_read_b128 v[228:231], v194 offset:20480
	ds_read_b128 v[232:235], v194 offset:21504
	ds_read_b128 v[236:239], v194 offset:22528
	ds_read_b128 v[240:243], v194 offset:23552
	global_load_lds_dwordx4 v[244:245], off
	s_add_i32 m0, s40, 0x2000
	s_add_u32 s40, s42, 0xb0000
	v_lshl_add_u64 v[246:247], s[42:43], 0, v[134:135]
	s_addc_u32 s41, s43, 0
	s_add_i32 s64, s57, s46
	global_load_lds_dwordx4 v[246:247], off
	v_lshl_add_u64 v[248:249], s[40:41], 0, v[130:131]
	s_mov_b32 m0, s64
	v_lshl_add_u64 v[250:251], s[44:45], 0, v[132:133]
	global_load_lds_dwordx4 v[248:249], off
	v_lshl_add_u64 v[248:249], s[40:41], 0, v[134:135]
	s_add_i32 m0, s64, 0x2000
	s_nop 0
	global_load_lds_dwordx4 v[248:249], off
	v_lshl_add_u64 v[248:249], s[44:45], 0, v[128:129]
	s_mov_b32 m0, s47
	s_nop 0
	global_load_lds_dwordx4 v[248:249], off
	s_mov_b32 m0, s48
	s_nop 0
	global_load_lds_dwordx4 v[250:251], off
	s_waitcnt vmcnt(8)
	s_waitcnt lgkmcnt(0)
	s_barrier
	s_waitcnt lgkmcnt(0)
	v_mfma_f32_16x16x32_bf16 v[60:63], v[144:147], v[212:215], v[60:63]
	v_mfma_f32_16x16x32_bf16 v[56:59], v[152:155], v[212:215], v[56:59]
	v_mfma_f32_16x16x32_bf16 v[44:47], v[144:147], v[220:223], v[44:47]
	v_mfma_f32_16x16x32_bf16 v[40:43], v[152:155], v[220:223], v[40:43]
	v_mfma_f32_16x16x32_bf16 v[28:31], v[144:147], v[228:231], v[28:31]
	v_mfma_f32_16x16x32_bf16 v[24:27], v[152:155], v[228:231], v[24:27]
	v_mfma_f32_16x16x32_bf16 v[12:15], v[144:147], v[236:239], v[12:15]
	v_mfma_f32_16x16x32_bf16 v[8:11], v[152:155], v[236:239], v[8:11]
	v_mfma_f32_16x16x32_bf16 v[60:63], v[148:151], v[216:219], v[60:63]
	v_mfma_f32_16x16x32_bf16 v[56:59], v[156:159], v[216:219], v[56:59]
	v_mfma_f32_16x16x32_bf16 v[44:47], v[148:151], v[224:227], v[44:47]
	v_mfma_f32_16x16x32_bf16 v[40:43], v[156:159], v[224:227], v[40:43]
	v_mfma_f32_16x16x32_bf16 v[28:31], v[148:151], v[232:235], v[28:31]
	v_mfma_f32_16x16x32_bf16 v[24:27], v[156:159], v[232:235], v[24:27]
	v_mfma_f32_16x16x32_bf16 v[12:15], v[148:151], v[240:243], v[12:15]
	v_mfma_f32_16x16x32_bf16 v[8:11], v[156:159], v[240:243], v[8:11]
	v_mfma_f32_16x16x32_bf16 v[52:55], v[160:163], v[212:215], v[52:55]
	v_mfma_f32_16x16x32_bf16 v[48:51], v[168:171], v[212:215], v[48:51]
	v_mfma_f32_16x16x32_bf16 v[36:39], v[160:163], v[220:223], v[36:39]
	v_mfma_f32_16x16x32_bf16 v[32:35], v[168:171], v[220:223], v[32:35]
	v_mfma_f32_16x16x32_bf16 v[20:23], v[160:163], v[228:231], v[20:23]
	v_mfma_f32_16x16x32_bf16 v[16:19], v[168:171], v[228:231], v[16:19]
	v_mfma_f32_16x16x32_bf16 v[4:7], v[160:163], v[236:239], v[4:7]
	v_mfma_f32_16x16x32_bf16 v[0:3], v[168:171], v[236:239], v[0:3]
	v_mfma_f32_16x16x32_bf16 v[52:55], v[164:167], v[216:219], v[52:55]
	v_mfma_f32_16x16x32_bf16 v[48:51], v[208:211], v[216:219], v[48:51]
	v_mfma_f32_16x16x32_bf16 v[36:39], v[164:167], v[224:227], v[36:39]
	v_mfma_f32_16x16x32_bf16 v[32:35], v[208:211], v[224:227], v[32:35]
	v_mfma_f32_16x16x32_bf16 v[20:23], v[164:167], v[232:235], v[20:23]
	v_mfma_f32_16x16x32_bf16 v[16:19], v[208:211], v[232:235], v[16:19]
	v_mfma_f32_16x16x32_bf16 v[4:7], v[164:167], v[240:243], v[4:7]
	v_mfma_f32_16x16x32_bf16 v[0:3], v[208:211], v[240:243], v[0:3]
	s_barrier
	s_add_i32 s64, 0, 0x18000
	s_add_i32 s65, 0, 0x1c000
	v_add_u32_e32 v156, s64, v173
	v_add_u32_e32 v206, s65, v173
	ds_read_b128 v[144:147], v156
	ds_read_b128 v[148:151], v156 offset:1024
	ds_read_b128 v[152:155], v156 offset:2048
	ds_read_b128 v[156:159], v156 offset:3072
	ds_read_b128 v[160:163], v206
	ds_read_b128 v[164:167], v206 offset:1024
	ds_read_b128 v[168:171], v206 offset:2048
	ds_read_b128 v[208:211], v206 offset:3072
	s_add_u32 s40, s44, 0xb0000
	s_addc_u32 s41, s45, 0
	s_mov_b32 m0, s49
	v_lshl_add_u64 v[206:207], s[40:41], 0, v[128:129]
	ds_read_b128 v[212:215], v194 offset:32768
	ds_read_b128 v[216:219], v194 offset:33792
	ds_read_b128 v[220:223], v194 offset:34816
	ds_read_b128 v[224:227], v194 offset:35840
	ds_read_b128 v[228:231], v194 offset:36864
	ds_read_b128 v[232:235], v194 offset:37888
	ds_read_b128 v[236:239], v194 offset:38912
	ds_read_b128 v[240:243], v194 offset:39936
	global_load_lds_dwordx4 v[206:207], off
	v_lshl_add_u64 v[206:207], s[40:41], 0, v[132:133]
	s_mov_b32 m0, s50
	s_nop 0
	global_load_lds_dwordx4 v[206:207], off
	s_waitcnt vmcnt(8)
	s_waitcnt lgkmcnt(0)
	s_barrier
	s_waitcnt lgkmcnt(0)
	v_mfma_f32_16x16x32_bf16 v[124:127], v[144:147], v[212:215], v[124:127]
	v_mfma_f32_16x16x32_bf16 v[120:123], v[152:155], v[212:215], v[120:123]
	v_mfma_f32_16x16x32_bf16 v[108:111], v[144:147], v[220:223], v[108:111]
	v_mfma_f32_16x16x32_bf16 v[104:107], v[152:155], v[220:223], v[104:107]
	v_mfma_f32_16x16x32_bf16 v[92:95], v[144:147], v[228:231], v[92:95]
	v_mfma_f32_16x16x32_bf16 v[88:91], v[152:155], v[228:231], v[88:91]
	v_mfma_f32_16x16x32_bf16 v[76:79], v[144:147], v[236:239], v[76:79]
	v_mfma_f32_16x16x32_bf16 v[72:75], v[152:155], v[236:239], v[72:75]
	v_mfma_f32_16x16x32_bf16 v[124:127], v[148:151], v[216:219], v[124:127]
	v_mfma_f32_16x16x32_bf16 v[120:123], v[156:159], v[216:219], v[120:123]
	v_mfma_f32_16x16x32_bf16 v[108:111], v[148:151], v[224:227], v[108:111]
	v_mfma_f32_16x16x32_bf16 v[104:107], v[156:159], v[224:227], v[104:107]
	v_mfma_f32_16x16x32_bf16 v[92:95], v[148:151], v[232:235], v[92:95]
	v_mfma_f32_16x16x32_bf16 v[88:91], v[156:159], v[232:235], v[88:91]
	v_mfma_f32_16x16x32_bf16 v[76:79], v[148:151], v[240:243], v[76:79]
	v_mfma_f32_16x16x32_bf16 v[72:75], v[156:159], v[240:243], v[72:75]
	v_mfma_f32_16x16x32_bf16 v[116:119], v[160:163], v[212:215], v[116:119]
	v_mfma_f32_16x16x32_bf16 v[112:115], v[168:171], v[212:215], v[112:115]
	v_mfma_f32_16x16x32_bf16 v[100:103], v[160:163], v[220:223], v[100:103]
	v_mfma_f32_16x16x32_bf16 v[96:99], v[168:171], v[220:223], v[96:99]
	v_mfma_f32_16x16x32_bf16 v[84:87], v[160:163], v[228:231], v[84:87]
	v_mfma_f32_16x16x32_bf16 v[80:83], v[168:171], v[228:231], v[80:83]
	v_mfma_f32_16x16x32_bf16 v[68:71], v[160:163], v[236:239], v[68:71]
	v_mfma_f32_16x16x32_bf16 v[64:67], v[168:171], v[236:239], v[64:67]
	v_mfma_f32_16x16x32_bf16 v[116:119], v[164:167], v[216:219], v[116:119]
	v_mfma_f32_16x16x32_bf16 v[112:115], v[208:211], v[216:219], v[112:115]
	v_mfma_f32_16x16x32_bf16 v[100:103], v[164:167], v[224:227], v[100:103]
	v_mfma_f32_16x16x32_bf16 v[96:99], v[208:211], v[224:227], v[96:99]
	v_mfma_f32_16x16x32_bf16 v[84:87], v[164:167], v[232:235], v[84:87]
	v_mfma_f32_16x16x32_bf16 v[80:83], v[208:211], v[232:235], v[80:83]
	v_mfma_f32_16x16x32_bf16 v[68:71], v[164:167], v[240:243], v[68:71]
	v_mfma_f32_16x16x32_bf16 v[64:67], v[208:211], v[240:243], v[64:67]
	s_barrier
; #define PG8_BAR __builtin_amdgcn_s_barrier()
; template <class Epi, bool HOOK = false>
; DI void gemm_phase(LAS unsigned char* lds, const Gemm g, const StaticOrder& S, const Epi& E) {
;     ...
;         if constexpr (HOOK) {
;             for (int t = 0; t < (nt >> 1); t += 2) PG8_KBODY();
;             E.hook(acc, cur, wr, wc, fr, fq);
;             for (int t = (nt >> 1); t < nt; t += 2) PG8_KBODY();
;         } else {
;             for (int t = 0; t < nt; t += 2) PG8_KBODY();
;         }
;     ...
;         if (wr == 0) PG8_BAR;
	s_add_i32 s40, s64, s46
	v_lshl_add_u64 v[206:207], v[244:245], 0, s[24:25]
	s_mov_b32 m0, s40
	ds_read_b128 v[212:215], v194 offset:49152
	ds_read_b128 v[216:219], v194 offset:50176
	ds_read_b128 v[220:223], v194 offset:51200
	ds_read_b128 v[224:227], v194 offset:52224
	ds_read_b128 v[228:231], v194 offset:53248
	ds_read_b128 v[232:235], v194 offset:54272
	ds_read_b128 v[236:239], v194 offset:55296
	ds_read_b128 v[240:243], v194 offset:56320
	global_load_lds_dwordx4 v[206:207], off
	s_add_i32 m0, s40, 0x2000
	s_add_u32 s40, s42, 0xb0080
	v_lshl_add_u64 v[206:207], v[246:247], 0, s[24:25]
	s_addc_u32 s41, s43, 0
	s_add_i32 s42, s65, s46
	global_load_lds_dwordx4 v[206:207], off
	v_lshl_add_u64 v[206:207], s[40:41], 0, v[130:131]
	s_mov_b32 m0, s42
	s_nop 0
	global_load_lds_dwordx4 v[206:207], off
	v_lshl_add_u64 v[206:207], s[40:41], 0, v[134:135]
	s_add_i32 m0, s42, 0x2000
	s_nop 0
	global_load_lds_dwordx4 v[206:207], off
	v_lshl_add_u64 v[206:207], v[248:249], 0, s[24:25]
	s_mov_b32 m0, s54
	s_nop 0
	global_load_lds_dwordx4 v[206:207], off
	v_lshl_add_u64 v[206:207], v[250:251], 0, s[24:25]
	s_mov_b32 m0, s55
	s_nop 0
	global_load_lds_dwordx4 v[206:207], off
	s_waitcnt vmcnt(8)
	s_waitcnt lgkmcnt(0)
	s_barrier
	s_waitcnt lgkmcnt(0)
	v_mfma_f32_16x16x32_bf16 v[60:63], v[144:147], v[212:215], v[60:63]
	v_mfma_f32_16x16x32_bf16 v[56:59], v[152:155], v[212:215], v[56:59]
	v_mfma_f32_16x16x32_bf16 v[44:47], v[144:147], v[220:223], v[44:47]
	v_mfma_f32_16x16x32_bf16 v[40:43], v[152:155], v[220:223], v[40:43]
	v_mfma_f32_16x16x32_bf16 v[28:31], v[144:147], v[228:231], v[28:31]
	v_mfma_f32_16x16x32_bf16 v[24:27], v[152:155], v[228:231], v[24:27]
	v_mfma_f32_16x16x32_bf16 v[12:15], v[144:147], v[236:239], v[12:15]
	v_mfma_f32_16x16x32_bf16 v[8:11], v[152:155], v[236:239], v[8:11]
	v_mfma_f32_16x16x32_bf16 v[60:63], v[148:151], v[216:219], v[60:63]
	v_mfma_f32_16x16x32_bf16 v[56:59], v[156:159], v[216:219], v[56:59]
	v_mfma_f32_16x16x32_bf16 v[44:47], v[148:151], v[224:227], v[44:47]
	v_mfma_f32_16x16x32_bf16 v[40:43], v[156:159], v[224:227], v[40:43]
	v_mfma_f32_16x16x32_bf16 v[28:31], v[148:151], v[232:235], v[28:31]
	v_mfma_f32_16x16x32_bf16 v[24:27], v[156:159], v[232:235], v[24:27]
	v_mfma_f32_16x16x32_bf16 v[12:15], v[148:151], v[240:243], v[12:15]
	v_mfma_f32_16x16x32_bf16 v[8:11], v[156:159], v[240:243], v[8:11]
	v_mfma_f32_16x16x32_bf16 v[52:55], v[160:163], v[212:215], v[52:55]
	v_mfma_f32_16x16x32_bf16 v[48:51], v[168:171], v[212:215], v[48:51]
	v_mfma_f32_16x16x32_bf16 v[36:39], v[160:163], v[220:223], v[36:39]
	v_mfma_f32_16x16x32_bf16 v[32:35], v[168:171], v[220:223], v[32:35]
	v_mfma_f32_16x16x32_bf16 v[20:23], v[160:163], v[228:231], v[20:23]
	v_mfma_f32_16x16x32_bf16 v[16:19], v[168:171], v[228:231], v[16:19]
	v_mfma_f32_16x16x32_bf16 v[4:7], v[160:163], v[236:239], v[4:7]
	v_mfma_f32_16x16x32_bf16 v[0:3], v[168:171], v[236:239], v[0:3]
	v_mfma_f32_16x16x32_bf16 v[52:55], v[164:167], v[216:219], v[52:55]
	v_mfma_f32_16x16x32_bf16 v[48:51], v[208:211], v[216:219], v[48:51]
	v_mfma_f32_16x16x32_bf16 v[36:39], v[164:167], v[224:227], v[36:39]
	v_mfma_f32_16x16x32_bf16 v[32:35], v[208:211], v[224:227], v[32:35]
	v_mfma_f32_16x16x32_bf16 v[20:23], v[164:167], v[232:235], v[20:23]
	v_mfma_f32_16x16x32_bf16 v[16:19], v[208:211], v[232:235], v[16:19]
	v_mfma_f32_16x16x32_bf16 v[4:7], v[164:167], v[240:243], v[4:7]
	v_mfma_f32_16x16x32_bf16 v[0:3], v[208:211], v[240:243], v[0:3]
	s_barrier
	s_add_i32 s63, s63, 2
	s_add_u32 s39, s39, 0x100
	s_addc_u32 s62, s62, 0
	s_cmp_gt_u32 s63, 41
	s_mov_b64 s[40:41], s[8:9]
	s_cbranch_scc0 .LBB0_1114
	s_and_b64 vcc, exec, s[26:27]
	s_cbranch_vccz .LBB0_1117
	s_barrier
